# kloop-counted-lgkmcnt-after-barrier
# speedup vs baseline: 1.0089x; 1.0059x over previous
; #define PG8_STAGE(bufoff, gbase, hoff, imm) do { _Pragma("unroll") for (int _i = 0; _i < 2; ++_i) { \
;         asm volatile("s_mov_b32 m0, %0\n\ts_nop 0\n\tglobal_load_lds_dwordx4 %1, %2" \
;             :: "s"(lds0 + (unsigned)((bufoff) + _i * 8192)), "v"(voff0), "s"((const char*)(gbase) + (size_t)(hoff) + (size_t)(_i * 8192)) : "memory"); } } while (0)
; #define PG8_LDA(dst, b, h) do { _Pragma("unroll") for (int m = 0; m < 4; ++m) _Pragma("unroll") for (int k = 0; k < 2; ++k) dst[m][k] = *(const LAS bf16x8*)(lds + PG8_SA(b, h) + aoff + m * 2048 + k * 1024); } while (0)
; #define PG8_LDB(dst, b, h) do { _Pragma("unroll") for (int n = 0; n < 2; ++n) _Pragma("unroll") for (int k = 0; k < 2; ++k) dst[n][k] = *(const LAS bf16x8*)(lds + PG8_SB(b, h) + boff + n * 2048 + k * 1024); } while (0)
; #define PG8_MMA(ai, bj, At, Bt) do { __builtin_amdgcn_s_setprio(1); _Pragma("unroll") for (int m = 0; m < 4; ++m) _Pragma("unroll") for (int n = 0; n < 2; ++n) _Pragma("unroll") for (int k = 0; k < 2; ++k) \
;         acc[ai][bj][m][n] = __builtin_amdgcn_mfma_f32_16x16x32_bf16(Bt[n][k], At[m][k], acc[ai][bj][m][n], 0, 0, 0); __builtin_amdgcn_s_setprio(0); } while (0)
; #define PG8_WAIT_L(n) asm volatile("s_waitcnt lgkmcnt(" #n ")" ::: "memory")
; #define PG8_BAR __builtin_amdgcn_s_barrier()
; #define PG8_SCHED __builtin_amdgcn_sched_barrier(0)
; template <class Epi>
; __device__ __forceinline__ void gemm_phase(LAS unsigned char* lds, const Gemm g, const StaticOrder& S, const Epi& E) {
;     ...
;             const char* aT = cA + (size_t)t * KS;
;             const char* a2 = last ? nA : aT + 2 * KS; const char* b2 = last ? nB : cB + (size_t)(t + 2) * KS;
;             PG8_LDB(B0, 0, 0); PG8_SCHED; PG8_LDA(At, 0, 0); PG8_STAGE(PG8_SA(1, 1), aT + KS, hA, 0);
;             PG8_WAIT_L(8); PG8_BAR; PG8_WAIT_L(0); PG8_MMA(0, 0, At, B0); PG8_BAR; PG8_SCHED;
;             PG8_LDB(B1, 0, 1); PG8_STAGE(PG8_SB(0, 0), b2, 0, 0);
;             PG8_BAR; PG8_WAIT_L(0); PG8_MMA(0, 1, At, B1); PG8_BAR;
;             PG8_LDA(At, 0, 1); PG8_STAGE(PG8_SA(0, 0), a2, 0, 0);
;             PG8_BAR; PG8_WAIT_L(0); PG8_MMA(1, 0, At, B0); PG8_BAR; PG8_SCHED;
.LBB0_293:
	s_add_u32 s52, s8, 0x8000
	s_addc_u32 s53, s9, 0
	ds_read_b128 v[128:131], v224
	ds_read_b128 v[132:135], v224 offset:1024
	ds_read_b128 v[136:139], v224 offset:2048
	ds_read_b128 v[140:143], v224 offset:3072
	s_add_u32 s54, s8, 0x84000
	s_addc_u32 s55, s9, 0
	s_add_u32 s96, s8, 0x86000
	s_addc_u32 s97, s9, 0
	s_cmp_eq_u32 s95, 4
	s_cselect_b32 s9, s0, s53
	s_cselect_b32 s8, s1, s52
	ds_read_b128 v[144:147], v225
	ds_read_b128 v[148:151], v225 offset:1024
	ds_read_b128 v[152:155], v225 offset:2048
	ds_read_b128 v[156:159], v225 offset:3072
	ds_read_b128 v[160:163], v225 offset:4096
	ds_read_b128 v[164:167], v225 offset:5120
	ds_read_b128 v[168:171], v225 offset:6144
	ds_read_b128 v[172:175], v225 offset:7168
	s_mov_b32 m0, s86
	s_nop 0
	global_load_lds_dwordx4 v221, s[54:55]
	s_mov_b32 m0, s87
	s_nop 0
	global_load_lds_dwordx4 v221, s[96:97]
	s_waitcnt lgkmcnt(8)
	s_waitcnt vmcnt(10)
	s_barrier
	s_waitcnt lgkmcnt(7)
	v_mfma_f32_16x16x32_bf16 v[124:127], v[128:131], v[144:147], v[124:127]
	v_mfma_f32_16x16x32_bf16 v[120:123], v[136:139], v[144:147], v[120:123]
	s_waitcnt lgkmcnt(5)
	v_mfma_f32_16x16x32_bf16 v[116:119], v[128:131], v[152:155], v[116:119]
	v_mfma_f32_16x16x32_bf16 v[112:115], v[136:139], v[152:155], v[112:115]
	s_waitcnt lgkmcnt(3)
	v_mfma_f32_16x16x32_bf16 v[96:99], v[128:131], v[160:163], v[96:99]
	v_mfma_f32_16x16x32_bf16 v[88:91], v[136:139], v[160:163], v[88:91]
	s_waitcnt lgkmcnt(1)
	v_mfma_f32_16x16x32_bf16 v[80:83], v[128:131], v[168:171], v[80:83]
	v_mfma_f32_16x16x32_bf16 v[72:75], v[136:139], v[168:171], v[72:75]
	v_mfma_f32_16x16x32_bf16 v[124:127], v[132:135], v[148:151], v[124:127]
	v_mfma_f32_16x16x32_bf16 v[120:123], v[140:143], v[148:151], v[120:123]
	v_mfma_f32_16x16x32_bf16 v[116:119], v[132:135], v[156:159], v[116:119]
	v_mfma_f32_16x16x32_bf16 v[112:115], v[140:143], v[156:159], v[112:115]
	v_mfma_f32_16x16x32_bf16 v[96:99], v[132:135], v[164:167], v[96:99]
	v_mfma_f32_16x16x32_bf16 v[88:91], v[140:143], v[164:167], v[88:91]
	s_waitcnt lgkmcnt(0)
	v_mfma_f32_16x16x32_bf16 v[80:83], v[132:135], v[172:175], v[80:83]
	v_mfma_f32_16x16x32_bf16 v[72:75], v[140:143], v[172:175], v[72:75]
	s_barrier
	ds_read_b128 v[176:179], v226
	ds_read_b128 v[180:183], v226 offset:1024
	ds_read_b128 v[184:187], v226 offset:2048
	ds_read_b128 v[188:191], v226 offset:3072
	s_cselect_b32 s54, s47, s93
	s_cselect_b32 s55, s45, s94
	s_mov_b32 m0, s60
	s_nop 0
	global_load_lds_dwordx4 v221, s[54:55]
	s_add_u32 s96, s54, 0x2000
	s_addc_u32 s97, s55, 0
	s_mov_b32 m0, s61
	s_nop 0
	global_load_lds_dwordx4 v221, s[96:97]
	s_waitcnt vmcnt(10)
	s_barrier
	s_waitcnt lgkmcnt(3)
	v_mfma_f32_16x16x32_bf16 v[108:111], v[176:179], v[144:147], v[108:111]
	s_waitcnt lgkmcnt(1)
	v_mfma_f32_16x16x32_bf16 v[104:107], v[184:187], v[144:147], v[104:107]
	v_mfma_f32_16x16x32_bf16 v[100:103], v[176:179], v[152:155], v[100:103]
	v_mfma_f32_16x16x32_bf16 v[92:95], v[184:187], v[152:155], v[92:95]
	v_mfma_f32_16x16x32_bf16 v[84:87], v[176:179], v[160:163], v[84:87]
	v_mfma_f32_16x16x32_bf16 v[76:79], v[184:187], v[160:163], v[76:79]
	v_mfma_f32_16x16x32_bf16 v[68:71], v[176:179], v[168:171], v[68:71]
	v_mfma_f32_16x16x32_bf16 v[64:67], v[184:187], v[168:171], v[64:67]
	v_mfma_f32_16x16x32_bf16 v[108:111], v[180:183], v[148:151], v[108:111]
	s_waitcnt lgkmcnt(0)
	v_mfma_f32_16x16x32_bf16 v[104:107], v[188:191], v[148:151], v[104:107]
	v_mfma_f32_16x16x32_bf16 v[100:103], v[180:183], v[156:159], v[100:103]
	v_mfma_f32_16x16x32_bf16 v[92:95], v[188:191], v[156:159], v[92:95]
	v_mfma_f32_16x16x32_bf16 v[84:87], v[180:183], v[164:167], v[84:87]
	v_mfma_f32_16x16x32_bf16 v[76:79], v[188:191], v[164:167], v[76:79]
	v_mfma_f32_16x16x32_bf16 v[68:71], v[180:183], v[172:175], v[68:71]
	v_mfma_f32_16x16x32_bf16 v[64:67], v[188:191], v[172:175], v[64:67]
	s_barrier
	ds_read_b128 v[144:147], v225 offset:16384
	ds_read_b128 v[148:151], v225 offset:17408
	ds_read_b128 v[152:155], v225 offset:18432
	ds_read_b128 v[156:159], v225 offset:19456
	ds_read_b128 v[160:163], v225 offset:20480
	ds_read_b128 v[164:167], v225 offset:21504
	ds_read_b128 v[168:171], v225 offset:22528
	ds_read_b128 v[172:175], v225 offset:23552
	s_mov_b32 m0, s59
	s_nop 0
	global_load_lds_dwordx4 v221, s[8:9]
	s_add_u32 s96, s8, 0x2000
	s_addc_u32 s97, s9, 0
	s_mov_b32 m0, s62
	s_nop 0
	global_load_lds_dwordx4 v221, s[96:97]
	s_barrier
	s_waitcnt lgkmcnt(7)
	v_mfma_f32_16x16x32_bf16 v[60:63], v[128:131], v[144:147], v[60:63]
	v_mfma_f32_16x16x32_bf16 v[56:59], v[136:139], v[144:147], v[56:59]
	s_waitcnt lgkmcnt(5)
	v_mfma_f32_16x16x32_bf16 v[48:51], v[128:131], v[152:155], v[48:51]
	v_mfma_f32_16x16x32_bf16 v[40:43], v[136:139], v[152:155], v[40:43]
	s_waitcnt lgkmcnt(3)
	v_mfma_f32_16x16x32_bf16 v[32:35], v[128:131], v[160:163], v[32:35]
	v_mfma_f32_16x16x32_bf16 v[24:27], v[136:139], v[160:163], v[24:27]
	s_waitcnt lgkmcnt(1)
	v_mfma_f32_16x16x32_bf16 v[16:19], v[128:131], v[168:171], v[16:19]
	v_mfma_f32_16x16x32_bf16 v[8:11], v[136:139], v[168:171], v[8:11]
	v_mfma_f32_16x16x32_bf16 v[60:63], v[132:135], v[148:151], v[60:63]
	v_mfma_f32_16x16x32_bf16 v[56:59], v[140:143], v[148:151], v[56:59]
	v_mfma_f32_16x16x32_bf16 v[48:51], v[132:135], v[156:159], v[48:51]
	v_mfma_f32_16x16x32_bf16 v[40:43], v[140:143], v[156:159], v[40:43]
	v_mfma_f32_16x16x32_bf16 v[32:35], v[132:135], v[164:167], v[32:35]
	v_mfma_f32_16x16x32_bf16 v[24:27], v[140:143], v[164:167], v[24:27]
	s_waitcnt lgkmcnt(0)
	v_mfma_f32_16x16x32_bf16 v[16:19], v[132:135], v[172:175], v[16:19]
	v_mfma_f32_16x16x32_bf16 v[8:11], v[140:143], v[172:175], v[8:11]
	s_barrier
; #define PG8_STAGE(bufoff, gbase, hoff, imm) do { _Pragma("unroll") for (int _i = 0; _i < 2; ++_i) { \
;         asm volatile("s_mov_b32 m0, %0\n\ts_nop 0\n\tglobal_load_lds_dwordx4 %1, %2" \
;             :: "s"(lds0 + (unsigned)((bufoff) + _i * 8192)), "v"(voff0), "s"((const char*)(gbase) + (size_t)(hoff) + (size_t)(_i * 8192)) : "memory"); } } while (0)
; #define PG8_LDA(dst, b, h) do { _Pragma("unroll") for (int m = 0; m < 4; ++m) _Pragma("unroll") for (int k = 0; k < 2; ++k) dst[m][k] = *(const LAS bf16x8*)(lds + PG8_SA(b, h) + aoff + m * 2048 + k * 1024); } while (0)
; #define PG8_LDB(dst, b, h) do { _Pragma("unroll") for (int n = 0; n < 2; ++n) _Pragma("unroll") for (int k = 0; k < 2; ++k) dst[n][k] = *(const LAS bf16x8*)(lds + PG8_SB(b, h) + boff + n * 2048 + k * 1024); } while (0)
; #define PG8_MMA(ai, bj, At, Bt) do { __builtin_amdgcn_s_setprio(1); _Pragma("unroll") for (int m = 0; m < 4; ++m) _Pragma("unroll") for (int n = 0; n < 2; ++n) _Pragma("unroll") for (int k = 0; k < 2; ++k) \
;         acc[ai][bj][m][n] = __builtin_amdgcn_mfma_f32_16x16x32_bf16(Bt[n][k], At[m][k], acc[ai][bj][m][n], 0, 0, 0); __builtin_amdgcn_s_setprio(0); } while (0)
; #define PG8_WAIT_V(n) asm volatile("s_waitcnt vmcnt(" #n ")" ::: "memory")
; #define PG8_WAIT_L(n) asm volatile("s_waitcnt lgkmcnt(" #n ")" ::: "memory")
; #define PG8_BAR __builtin_amdgcn_s_barrier()
; #define PG8_SCHED __builtin_amdgcn_sched_barrier(0)
; template <class Epi>
; __device__ __forceinline__ void gemm_phase(LAS unsigned char* lds, const Gemm g, const StaticOrder& S, const Epi& E) {
;     ...
;             PG8_STAGE(PG8_SB(0, 1), b2, hB, 0);
;             PG8_WAIT_V(6); PG8_BAR; PG8_MMA(1, 1, At, B1); PG8_BAR;
;             PG8_LDB(B0, 1, 0); PG8_SCHED; PG8_LDA(At, 1, 0); PG8_STAGE(PG8_SA(0, 1), a2, hA, 0);
;             PG8_WAIT_L(8); PG8_BAR; PG8_WAIT_L(0); PG8_MMA(0, 0, At, B0); PG8_BAR; PG8_SCHED;
;             PG8_LDB(B1, 1, 1); PG8_STAGE(PG8_SB(1, 0), b2 + KS, 0, 0);
;             PG8_BAR; PG8_WAIT_L(0); PG8_MMA(0, 1, At, B1); PG8_BAR;
	s_add_u32 s96, s54, 0x20000
	s_addc_u32 s97, s55, 0
	s_mov_b32 m0, s63
	s_nop 0
	global_load_lds_dwordx4 v221, s[96:97]
	s_add_u32 s96, s54, 0x22000
	s_addc_u32 s97, s55, 0
	s_mov_b32 m0, s64
	s_nop 0
	global_load_lds_dwordx4 v221, s[96:97]
	s_waitcnt vmcnt(10)
	s_barrier
	v_mfma_f32_16x16x32_bf16 v[52:55], v[176:179], v[144:147], v[52:55]
	v_mfma_f32_16x16x32_bf16 v[44:47], v[184:187], v[144:147], v[44:47]
	v_mfma_f32_16x16x32_bf16 v[36:39], v[176:179], v[152:155], v[36:39]
	v_mfma_f32_16x16x32_bf16 v[28:31], v[184:187], v[152:155], v[28:31]
	v_mfma_f32_16x16x32_bf16 v[20:23], v[176:179], v[160:163], v[20:23]
	v_mfma_f32_16x16x32_bf16 v[12:15], v[184:187], v[160:163], v[12:15]
	v_mfma_f32_16x16x32_bf16 v[4:7], v[176:179], v[168:171], v[4:7]
	v_mfma_f32_16x16x32_bf16 v[0:3], v[184:187], v[168:171], v[0:3]
	v_mfma_f32_16x16x32_bf16 v[52:55], v[180:183], v[148:151], v[52:55]
	v_mfma_f32_16x16x32_bf16 v[44:47], v[188:191], v[148:151], v[44:47]
	v_mfma_f32_16x16x32_bf16 v[36:39], v[180:183], v[156:159], v[36:39]
	v_mfma_f32_16x16x32_bf16 v[28:31], v[188:191], v[156:159], v[28:31]
	v_mfma_f32_16x16x32_bf16 v[20:23], v[180:183], v[164:167], v[20:23]
	v_mfma_f32_16x16x32_bf16 v[12:15], v[188:191], v[164:167], v[12:15]
	v_mfma_f32_16x16x32_bf16 v[4:7], v[180:183], v[172:175], v[4:7]
	v_mfma_f32_16x16x32_bf16 v[0:3], v[188:191], v[172:175], v[0:3]
	s_barrier
	ds_read_b128 v[128:131], v227
	ds_read_b128 v[132:135], v227 offset:1024
	ds_read_b128 v[136:139], v227 offset:2048
	ds_read_b128 v[140:143], v227 offset:3072
	ds_read_b128 v[144:147], v225 offset:32768
	ds_read_b128 v[148:151], v225 offset:33792
	ds_read_b128 v[152:155], v225 offset:34816
	ds_read_b128 v[156:159], v225 offset:35840
	ds_read_b128 v[160:163], v225 offset:36864
	ds_read_b128 v[164:167], v225 offset:37888
	ds_read_b128 v[168:171], v225 offset:38912
	ds_read_b128 v[172:175], v225 offset:39936
	s_add_u32 s96, s8, 0x80000
	s_addc_u32 s97, s9, 0
	s_mov_b32 m0, s65
	s_nop 0
	global_load_lds_dwordx4 v221, s[96:97]
	s_add_u32 s96, s8, 0x82000
	s_addc_u32 s97, s9, 0
	s_mov_b32 m0, s66
	s_nop 0
	global_load_lds_dwordx4 v221, s[96:97]
	s_waitcnt lgkmcnt(8)
	s_waitcnt vmcnt(10)
	s_barrier
	s_waitcnt lgkmcnt(7)
	v_mfma_f32_16x16x32_bf16 v[124:127], v[128:131], v[144:147], v[124:127]
	v_mfma_f32_16x16x32_bf16 v[120:123], v[136:139], v[144:147], v[120:123]
	s_waitcnt lgkmcnt(5)
	v_mfma_f32_16x16x32_bf16 v[116:119], v[128:131], v[152:155], v[116:119]
	v_mfma_f32_16x16x32_bf16 v[112:115], v[136:139], v[152:155], v[112:115]
	s_waitcnt lgkmcnt(3)
	v_mfma_f32_16x16x32_bf16 v[96:99], v[128:131], v[160:163], v[96:99]
	v_mfma_f32_16x16x32_bf16 v[88:91], v[136:139], v[160:163], v[88:91]
	s_waitcnt lgkmcnt(1)
	v_mfma_f32_16x16x32_bf16 v[80:83], v[128:131], v[168:171], v[80:83]
	v_mfma_f32_16x16x32_bf16 v[72:75], v[136:139], v[168:171], v[72:75]
	v_mfma_f32_16x16x32_bf16 v[124:127], v[132:135], v[148:151], v[124:127]
	v_mfma_f32_16x16x32_bf16 v[120:123], v[140:143], v[148:151], v[120:123]
	v_mfma_f32_16x16x32_bf16 v[116:119], v[132:135], v[156:159], v[116:119]
	v_mfma_f32_16x16x32_bf16 v[112:115], v[140:143], v[156:159], v[112:115]
	v_mfma_f32_16x16x32_bf16 v[96:99], v[132:135], v[164:167], v[96:99]
	v_mfma_f32_16x16x32_bf16 v[88:91], v[140:143], v[164:167], v[88:91]
	s_waitcnt lgkmcnt(0)
	v_mfma_f32_16x16x32_bf16 v[80:83], v[132:135], v[172:175], v[80:83]
	v_mfma_f32_16x16x32_bf16 v[72:75], v[140:143], v[172:175], v[72:75]
	s_barrier
	ds_read_b128 v[176:179], v228
	ds_read_b128 v[180:183], v228 offset:1024
	ds_read_b128 v[184:187], v228 offset:2048
	ds_read_b128 v[188:191], v228 offset:3072
	s_add_u32 s96, s54, 0x4000
	s_addc_u32 s97, s55, 0
	s_mov_b32 m0, s69
	s_nop 0
	global_load_lds_dwordx4 v221, s[96:97]
	s_add_u32 s96, s54, 0x6000
	s_addc_u32 s97, s55, 0
	s_mov_b32 m0, s70
	s_nop 0
	global_load_lds_dwordx4 v221, s[96:97]
	s_waitcnt vmcnt(10)
	s_barrier
	s_waitcnt lgkmcnt(3)
	v_mfma_f32_16x16x32_bf16 v[108:111], v[176:179], v[144:147], v[108:111]
	s_waitcnt lgkmcnt(1)
	v_mfma_f32_16x16x32_bf16 v[104:107], v[184:187], v[144:147], v[104:107]
	v_mfma_f32_16x16x32_bf16 v[100:103], v[176:179], v[152:155], v[100:103]
	v_mfma_f32_16x16x32_bf16 v[92:95], v[184:187], v[152:155], v[92:95]
	v_mfma_f32_16x16x32_bf16 v[84:87], v[176:179], v[160:163], v[84:87]
	v_mfma_f32_16x16x32_bf16 v[76:79], v[184:187], v[160:163], v[76:79]
	v_mfma_f32_16x16x32_bf16 v[68:71], v[176:179], v[168:171], v[68:71]
	v_mfma_f32_16x16x32_bf16 v[64:67], v[184:187], v[168:171], v[64:67]
	v_mfma_f32_16x16x32_bf16 v[108:111], v[180:183], v[148:151], v[108:111]
	s_waitcnt lgkmcnt(0)
	v_mfma_f32_16x16x32_bf16 v[104:107], v[188:191], v[148:151], v[104:107]
	v_mfma_f32_16x16x32_bf16 v[100:103], v[180:183], v[156:159], v[100:103]
	v_mfma_f32_16x16x32_bf16 v[92:95], v[188:191], v[156:159], v[92:95]
	v_mfma_f32_16x16x32_bf16 v[84:87], v[180:183], v[164:167], v[84:87]
	v_mfma_f32_16x16x32_bf16 v[76:79], v[188:191], v[164:167], v[76:79]
	v_mfma_f32_16x16x32_bf16 v[68:71], v[180:183], v[172:175], v[68:71]
	v_mfma_f32_16x16x32_bf16 v[64:67], v[188:191], v[172:175], v[64:67]
	s_barrier
; #define PG8_STAGE(bufoff, gbase, hoff, imm) do { _Pragma("unroll") for (int _i = 0; _i < 2; ++_i) { \
;         asm volatile("s_mov_b32 m0, %0\n\ts_nop 0\n\tglobal_load_lds_dwordx4 %1, %2" \
;             :: "s"(lds0 + (unsigned)((bufoff) + _i * 8192)), "v"(voff0), "s"((const char*)(gbase) + (size_t)(hoff) + (size_t)(_i * 8192)) : "memory"); } } while (0)
; #define PG8_LDA(dst, b, h) do { _Pragma("unroll") for (int m = 0; m < 4; ++m) _Pragma("unroll") for (int k = 0; k < 2; ++k) dst[m][k] = *(const LAS bf16x8*)(lds + PG8_SA(b, h) + aoff + m * 2048 + k * 1024); } while (0)
; #define PG8_MMA(ai, bj, At, Bt) do { __builtin_amdgcn_s_setprio(1); _Pragma("unroll") for (int m = 0; m < 4; ++m) _Pragma("unroll") for (int n = 0; n < 2; ++n) _Pragma("unroll") for (int k = 0; k < 2; ++k) \
;         acc[ai][bj][m][n] = __builtin_amdgcn_mfma_f32_16x16x32_bf16(Bt[n][k], At[m][k], acc[ai][bj][m][n], 0, 0, 0); __builtin_amdgcn_s_setprio(0); } while (0)
; #define PG8_WAIT_V(n) asm volatile("s_waitcnt vmcnt(" #n ")" ::: "memory")
; #define PG8_WAIT_L(n) asm volatile("s_waitcnt lgkmcnt(" #n ")" ::: "memory")
; #define PG8_BAR __builtin_amdgcn_s_barrier()
; #define PG8_SCHED __builtin_amdgcn_sched_barrier(0)
; template <class Epi>
; __device__ __forceinline__ void gemm_phase(LAS unsigned char* lds, const Gemm g, const StaticOrder& S, const Epi& E) {
;     ...
;             PG8_LDA(At, 1, 1); PG8_STAGE(PG8_SA(1, 0), a2 + KS, 0, 0);
;             PG8_BAR; PG8_WAIT_L(0); PG8_MMA(1, 0, At, B0); PG8_BAR; PG8_SCHED;
;             PG8_STAGE(PG8_SB(1, 1), b2 + KS, hB, 0);
;             PG8_WAIT_V(6); PG8_BAR; PG8_MMA(1, 1, At, B1); PG8_BAR;
;     __device__ __forceinline__ void operator()(f32x4 (&acc)[2][2][4][2], const Unit& u, int wr, int wc, int fr, int fq, LAS unsigned char*) const {
;         const int b = u.pm >> 6;
;         const int col0 = u.pn * BM + wc * 32 + 8 * fq;
;         const size_t off0 = (size_t)(u.pm * BM + wr * 64 + fr) * D + col0;
;         f32x4 sc[2][2];
; #pragma unroll
;         for (int bj = 0; bj < 2; ++bj)
; #pragma unroll
;             for (int n = 0; n < 2; ++n) { f32x4 gt = *(const f32x4*)(gate + (size_t)b * MODW + col0 + bj * HALF + n * 4); sc[bj][n] = gt + 1.0f;
;                 if (cs) sc[bj][n] *= *(const f32x4*)(cs + col0 + bj * HALF + n * 4); }
	ds_read_b128 v[144:147], v225 offset:49152
	ds_read_b128 v[148:151], v225 offset:50176
	ds_read_b128 v[152:155], v225 offset:51200
	ds_read_b128 v[156:159], v225 offset:52224
	ds_read_b128 v[160:163], v225 offset:53248
	ds_read_b128 v[164:167], v225 offset:54272
	ds_read_b128 v[168:171], v225 offset:55296
	ds_read_b128 v[172:175], v225 offset:56320
	s_add_u32 s96, s8, 0x4000
	s_addc_u32 s97, s9, 0
	s_mov_b32 m0, s71
	s_nop 0
	global_load_lds_dwordx4 v221, s[96:97]
	s_add_u32 s8, s8, 0x6000
	s_addc_u32 s9, s9, 0
	s_mov_b32 m0, s72
	s_nop 0
	global_load_lds_dwordx4 v221, s[8:9]
	s_barrier
	s_waitcnt lgkmcnt(7)
	v_mfma_f32_16x16x32_bf16 v[60:63], v[128:131], v[144:147], v[60:63]
	v_mfma_f32_16x16x32_bf16 v[56:59], v[136:139], v[144:147], v[56:59]
	s_waitcnt lgkmcnt(5)
	v_mfma_f32_16x16x32_bf16 v[48:51], v[128:131], v[152:155], v[48:51]
	v_mfma_f32_16x16x32_bf16 v[40:43], v[136:139], v[152:155], v[40:43]
	s_waitcnt lgkmcnt(3)
	v_mfma_f32_16x16x32_bf16 v[32:35], v[128:131], v[160:163], v[32:35]
	v_mfma_f32_16x16x32_bf16 v[24:27], v[136:139], v[160:163], v[24:27]
	s_waitcnt lgkmcnt(1)
	v_mfma_f32_16x16x32_bf16 v[16:19], v[128:131], v[168:171], v[16:19]
	v_mfma_f32_16x16x32_bf16 v[8:11], v[136:139], v[168:171], v[8:11]
	v_mfma_f32_16x16x32_bf16 v[60:63], v[132:135], v[148:151], v[60:63]
	v_mfma_f32_16x16x32_bf16 v[56:59], v[140:143], v[148:151], v[56:59]
	v_mfma_f32_16x16x32_bf16 v[48:51], v[132:135], v[156:159], v[48:51]
	v_mfma_f32_16x16x32_bf16 v[40:43], v[140:143], v[156:159], v[40:43]
	v_mfma_f32_16x16x32_bf16 v[32:35], v[132:135], v[164:167], v[32:35]
	v_mfma_f32_16x16x32_bf16 v[24:27], v[140:143], v[164:167], v[24:27]
	s_waitcnt lgkmcnt(0)
	v_mfma_f32_16x16x32_bf16 v[16:19], v[132:135], v[172:175], v[16:19]
	v_mfma_f32_16x16x32_bf16 v[8:11], v[140:143], v[172:175], v[8:11]
	s_barrier
	s_add_u32 s8, s54, 0x24000
	s_addc_u32 s9, s55, 0
	s_mov_b32 m0, s73
	s_nop 0
	global_load_lds_dwordx4 v221, s[8:9]
	s_add_u32 s8, s54, 0x26000
	s_addc_u32 s9, s55, 0
	s_mov_b32 m0, s85
	s_nop 0
	global_load_lds_dwordx4 v221, s[8:9]
	s_waitcnt vmcnt(10)
	s_barrier
	v_mfma_f32_16x16x32_bf16 v[52:55], v[176:179], v[144:147], v[52:55]
	v_mfma_f32_16x16x32_bf16 v[44:47], v[184:187], v[144:147], v[44:47]
	v_mfma_f32_16x16x32_bf16 v[36:39], v[176:179], v[152:155], v[36:39]
	v_mfma_f32_16x16x32_bf16 v[28:31], v[184:187], v[152:155], v[28:31]
	v_mfma_f32_16x16x32_bf16 v[20:23], v[176:179], v[160:163], v[20:23]
	v_mfma_f32_16x16x32_bf16 v[12:15], v[184:187], v[160:163], v[12:15]
	v_mfma_f32_16x16x32_bf16 v[4:7], v[176:179], v[168:171], v[4:7]
	v_mfma_f32_16x16x32_bf16 v[0:3], v[184:187], v[168:171], v[0:3]
	v_mfma_f32_16x16x32_bf16 v[52:55], v[180:183], v[148:151], v[52:55]
	v_mfma_f32_16x16x32_bf16 v[44:47], v[188:191], v[148:151], v[44:47]
	v_mfma_f32_16x16x32_bf16 v[36:39], v[180:183], v[156:159], v[36:39]
	v_mfma_f32_16x16x32_bf16 v[28:31], v[188:191], v[156:159], v[28:31]
	v_mfma_f32_16x16x32_bf16 v[20:23], v[180:183], v[164:167], v[20:23]
	v_mfma_f32_16x16x32_bf16 v[12:15], v[188:191], v[164:167], v[12:15]
	v_mfma_f32_16x16x32_bf16 v[4:7], v[180:183], v[172:175], v[4:7]
	v_mfma_f32_16x16x32_bf16 v[0:3], v[188:191], v[172:175], v[0:3]
	s_add_i32 s95, s95, 2
	s_add_u32 s93, s93, 0x8000
	s_addc_u32 s94, s94, 0
	s_cmp_gt_u32 s95, 5
	s_mov_b64 s[8:9], s[52:53]
	s_barrier
	s_cbranch_scc0 .LBB0_293
	s_ashr_i32 s0, s89, 6
	v_lshl_or_b32 v128, s92, 8, v223
	s_mul_hi_i32 s1, s0, 0xc000
	s_mul_i32 s0, s0, 0xc000
	v_ashrrev_i32_e32 v129, 31, v128
	s_add_u32 s0, s67, s0
	s_addc_u32 s1, s68, s1
	v_lshlrev_b64 v[130:131], 2, v[128:129]
	v_lshl_add_u64 v[132:133], s[0:1], 0, v[130:131]
	v_cndmask_b32_e64 v138, 0, 1, s[42:43]
	v_cmp_ne_u32_e64 s[8:9], 1, v138
	v_lshl_add_u64 v[130:131], s[38:39], 0, v[130:131]
	global_load_dwordx4 v[196:199], v[132:133], off
	global_load_dwordx4 v[200:203], v[132:133], off offset:16
	global_load_dwordx4 v[204:207], v[132:133], off offset:512
	global_load_dwordx4 v[208:211], v[132:133], off offset:528
	v_readlane_b32 s96, v255, 3
	v_readlane_b32 s97, v255, 4
	s_andn2_b64 vcc, exec, s[42:43]
	s_cbranch_vccnz .Lp2_nocs
	global_load_dwordx4 v[134:137], v[130:131], off
	global_load_dwordx4 v[138:141], v[130:131], off offset:16
	global_load_dwordx4 v[142:145], v[130:131], off offset:512
	global_load_dwordx4 v[146:149], v[130:131], off offset:528

; #define PG8_STAGE(bufoff, gbase, hoff, imm) do { _Pragma("unroll") for (int _i = 0; _i < 2; ++_i) { \
;         asm volatile("s_mov_b32 m0, %0\n\ts_nop 0\n\tglobal_load_lds_dwordx4 %1, %2" \
;             :: "s"(lds0 + (unsigned)((bufoff) + _i * 8192)), "v"(voff0), "s"((const char*)(gbase) + (size_t)(hoff) + (size_t)(_i * 8192)) : "memory"); } } while (0)
; #define PG8_LDA(dst, b, h) do { _Pragma("unroll") for (int m = 0; m < 4; ++m) _Pragma("unroll") for (int k = 0; k < 2; ++k) dst[m][k] = *(const LAS bf16x8*)(lds + PG8_SA(b, h) + aoff + m * 2048 + k * 1024); } while (0)
; #define PG8_LDB(dst, b, h) do { _Pragma("unroll") for (int n = 0; n < 2; ++n) _Pragma("unroll") for (int k = 0; k < 2; ++k) dst[n][k] = *(const LAS bf16x8*)(lds + PG8_SB(b, h) + boff + n * 2048 + k * 1024); } while (0)
; #define PG8_MMA(ai, bj, At, Bt) do { __builtin_amdgcn_s_setprio(1); _Pragma("unroll") for (int m = 0; m < 4; ++m) _Pragma("unroll") for (int n = 0; n < 2; ++n) _Pragma("unroll") for (int k = 0; k < 2; ++k) \
;         acc[ai][bj][m][n] = __builtin_amdgcn_mfma_f32_16x16x32_bf16(Bt[n][k], At[m][k], acc[ai][bj][m][n], 0, 0, 0); __builtin_amdgcn_s_setprio(0); } while (0)
; #define PG8_WAIT_L(n) asm volatile("s_waitcnt lgkmcnt(" #n ")" ::: "memory")
; #define PG8_BAR __builtin_amdgcn_s_barrier()
; #define PG8_SCHED __builtin_amdgcn_sched_barrier(0)
; template <class Epi>
; __device__ __forceinline__ void gemm_phase(LAS unsigned char* lds, const Gemm g, const StaticOrder& S, const Epi& E) {
;     ...
;             const char* aT = cA + (size_t)t * KS;
;             const char* a2 = last ? nA : aT + 2 * KS; const char* b2 = last ? nB : cB + (size_t)(t + 2) * KS;
;             PG8_LDB(B0, 0, 0); PG8_SCHED; PG8_LDA(At, 0, 0); PG8_STAGE(PG8_SA(1, 1), aT + KS, hA, 0);
;             PG8_WAIT_L(8); PG8_BAR; PG8_WAIT_L(0); PG8_MMA(0, 0, At, B0); PG8_BAR; PG8_SCHED;
;             PG8_LDB(B1, 0, 1); PG8_STAGE(PG8_SB(0, 0), b2, 0, 0);
;             PG8_BAR; PG8_WAIT_L(0); PG8_MMA(0, 1, At, B1); PG8_BAR;
;             PG8_LDA(At, 0, 1); PG8_STAGE(PG8_SA(0, 0), a2, 0, 0);
;             PG8_BAR; PG8_WAIT_L(0); PG8_MMA(1, 0, At, B0); PG8_BAR; PG8_SCHED;
.LBB0_434:
	s_add_u32 s56, s54, 0x8000
	v_add_u32_e32 v128, 0x10000, v133
	s_addc_u32 s57, s55, 0
	ds_read_b128 v[136:139], v128
	ds_read_b128 v[140:143], v128 offset:1024
	ds_read_b128 v[144:147], v128 offset:2048
	ds_read_b128 v[148:151], v128 offset:3072
	s_add_u32 s58, s54, 0x84000
	s_addc_u32 s59, s55, 0
	s_add_u32 s66, s54, 0x86000
	s_addc_u32 s67, s55, 0
	s_cmp_eq_u32 s65, 28
	s_cselect_b32 s55, s0, s57
	s_cselect_b32 s54, s1, s56
	ds_read_b128 v[152:155], v134
	ds_read_b128 v[156:159], v134 offset:1024
	ds_read_b128 v[160:163], v134 offset:2048
	ds_read_b128 v[164:167], v134 offset:3072
	ds_read_b128 v[168:171], v134 offset:4096
	ds_read_b128 v[172:175], v134 offset:5120
	ds_read_b128 v[176:179], v134 offset:6144
	ds_read_b128 v[180:183], v134 offset:7168
	s_mov_b32 m0, s50
	s_nop 0
	global_load_lds_dwordx4 v130, s[58:59]
	s_mov_b32 m0, s51
	s_nop 0
	global_load_lds_dwordx4 v130, s[66:67]
	s_waitcnt lgkmcnt(8)
	s_waitcnt vmcnt(10)
	s_barrier
	s_waitcnt lgkmcnt(7)
	v_mfma_f32_16x16x32_bf16 v[124:127], v[136:139], v[152:155], v[124:127]
	v_mfma_f32_16x16x32_bf16 v[120:123], v[144:147], v[152:155], v[120:123]
	s_waitcnt lgkmcnt(5)
	v_mfma_f32_16x16x32_bf16 v[116:119], v[136:139], v[160:163], v[116:119]
	v_mfma_f32_16x16x32_bf16 v[108:111], v[144:147], v[160:163], v[108:111]
	s_waitcnt lgkmcnt(3)
	v_mfma_f32_16x16x32_bf16 v[100:103], v[136:139], v[168:171], v[100:103]
	v_mfma_f32_16x16x32_bf16 v[92:95], v[144:147], v[168:171], v[92:95]
	s_waitcnt lgkmcnt(1)
	v_mfma_f32_16x16x32_bf16 v[84:87], v[136:139], v[176:179], v[84:87]
	v_mfma_f32_16x16x32_bf16 v[76:79], v[144:147], v[176:179], v[76:79]
	v_mfma_f32_16x16x32_bf16 v[124:127], v[140:143], v[156:159], v[124:127]
	v_mfma_f32_16x16x32_bf16 v[120:123], v[148:151], v[156:159], v[120:123]
	v_mfma_f32_16x16x32_bf16 v[116:119], v[140:143], v[164:167], v[116:119]
	v_mfma_f32_16x16x32_bf16 v[108:111], v[148:151], v[164:167], v[108:111]
	v_mfma_f32_16x16x32_bf16 v[100:103], v[140:143], v[172:175], v[100:103]
	v_mfma_f32_16x16x32_bf16 v[92:95], v[148:151], v[172:175], v[92:95]
	s_waitcnt lgkmcnt(0)
	v_mfma_f32_16x16x32_bf16 v[84:87], v[140:143], v[180:183], v[84:87]
	v_mfma_f32_16x16x32_bf16 v[76:79], v[148:151], v[180:183], v[76:79]
	s_barrier
	v_add_u32_e32 v128, 0x14000, v133
	ds_read_b128 v[184:187], v128
	ds_read_b128 v[200:203], v128 offset:1024
	ds_read_b128 v[204:207], v128 offset:2048
	ds_read_b128 v[208:211], v128 offset:3072
	s_cselect_b32 s58, s9, s63
	s_cselect_b32 s59, s7, s64
	s_mov_b32 m0, s26
	s_nop 0
	global_load_lds_dwordx4 v130, s[58:59]
	s_add_u32 s66, s58, 0x2000
	s_addc_u32 s67, s59, 0
	s_mov_b32 m0, s27
	s_nop 0
	global_load_lds_dwordx4 v130, s[66:67]
	s_waitcnt vmcnt(10)
	s_barrier
	s_waitcnt lgkmcnt(3)
	v_mfma_f32_16x16x32_bf16 v[112:115], v[184:187], v[152:155], v[112:115]
	s_waitcnt lgkmcnt(1)
	v_mfma_f32_16x16x32_bf16 v[104:107], v[204:207], v[152:155], v[104:107]
	v_mfma_f32_16x16x32_bf16 v[96:99], v[184:187], v[160:163], v[96:99]
	v_mfma_f32_16x16x32_bf16 v[88:91], v[204:207], v[160:163], v[88:91]
	v_mfma_f32_16x16x32_bf16 v[80:83], v[184:187], v[168:171], v[80:83]
	v_mfma_f32_16x16x32_bf16 v[72:75], v[204:207], v[168:171], v[72:75]
	v_mfma_f32_16x16x32_bf16 v[68:71], v[184:187], v[176:179], v[68:71]
	v_mfma_f32_16x16x32_bf16 v[64:67], v[204:207], v[176:179], v[64:67]
	v_mfma_f32_16x16x32_bf16 v[112:115], v[200:203], v[156:159], v[112:115]
	s_waitcnt lgkmcnt(0)
	v_mfma_f32_16x16x32_bf16 v[104:107], v[208:211], v[156:159], v[104:107]
	v_mfma_f32_16x16x32_bf16 v[96:99], v[200:203], v[164:167], v[96:99]
	v_mfma_f32_16x16x32_bf16 v[88:91], v[208:211], v[164:167], v[88:91]
	v_mfma_f32_16x16x32_bf16 v[80:83], v[200:203], v[172:175], v[80:83]
	v_mfma_f32_16x16x32_bf16 v[72:75], v[208:211], v[172:175], v[72:75]
	v_mfma_f32_16x16x32_bf16 v[68:71], v[200:203], v[180:183], v[68:71]
	v_mfma_f32_16x16x32_bf16 v[64:67], v[208:211], v[180:183], v[64:67]
	s_barrier
	ds_read_b128 v[152:155], v134 offset:16384
	ds_read_b128 v[156:159], v134 offset:17408
	ds_read_b128 v[160:163], v134 offset:18432
	ds_read_b128 v[164:167], v134 offset:19456
	ds_read_b128 v[168:171], v134 offset:20480
	ds_read_b128 v[172:175], v134 offset:21504
	ds_read_b128 v[176:179], v134 offset:22528
	ds_read_b128 v[180:183], v134 offset:23552
	s_mov_b32 m0, s25
	s_nop 0
	global_load_lds_dwordx4 v130, s[54:55]
	s_add_u32 s66, s54, 0x2000
	s_addc_u32 s67, s55, 0
	s_mov_b32 m0, s28
	s_nop 0
	global_load_lds_dwordx4 v130, s[66:67]
	s_barrier
	s_waitcnt lgkmcnt(7)
	v_mfma_f32_16x16x32_bf16 v[60:63], v[136:139], v[152:155], v[60:63]
	v_mfma_f32_16x16x32_bf16 v[56:59], v[144:147], v[152:155], v[56:59]
	s_waitcnt lgkmcnt(5)
	v_mfma_f32_16x16x32_bf16 v[52:55], v[136:139], v[160:163], v[52:55]
	v_mfma_f32_16x16x32_bf16 v[44:47], v[144:147], v[160:163], v[44:47]
	s_waitcnt lgkmcnt(3)
	v_mfma_f32_16x16x32_bf16 v[36:39], v[136:139], v[168:171], v[36:39]
	v_mfma_f32_16x16x32_bf16 v[28:31], v[144:147], v[168:171], v[28:31]
	s_waitcnt lgkmcnt(1)
	v_mfma_f32_16x16x32_bf16 v[20:23], v[136:139], v[176:179], v[20:23]
	v_mfma_f32_16x16x32_bf16 v[12:15], v[144:147], v[176:179], v[12:15]
	v_mfma_f32_16x16x32_bf16 v[60:63], v[140:143], v[156:159], v[60:63]
	v_mfma_f32_16x16x32_bf16 v[56:59], v[148:151], v[156:159], v[56:59]
	v_mfma_f32_16x16x32_bf16 v[52:55], v[140:143], v[164:167], v[52:55]
	v_mfma_f32_16x16x32_bf16 v[44:47], v[148:151], v[164:167], v[44:47]
	v_mfma_f32_16x16x32_bf16 v[36:39], v[140:143], v[172:175], v[36:39]
	v_mfma_f32_16x16x32_bf16 v[28:31], v[148:151], v[172:175], v[28:31]
	s_waitcnt lgkmcnt(0)
	v_mfma_f32_16x16x32_bf16 v[20:23], v[140:143], v[180:183], v[20:23]
	v_mfma_f32_16x16x32_bf16 v[12:15], v[148:151], v[180:183], v[12:15]
	s_barrier
; #define PG8_STAGE(bufoff, gbase, hoff, imm) do { _Pragma("unroll") for (int _i = 0; _i < 2; ++_i) { \
;         asm volatile("s_mov_b32 m0, %0\n\ts_nop 0\n\tglobal_load_lds_dwordx4 %1, %2" \
;             :: "s"(lds0 + (unsigned)((bufoff) + _i * 8192)), "v"(voff0), "s"((const char*)(gbase) + (size_t)(hoff) + (size_t)(_i * 8192)) : "memory"); } } while (0)
; #define PG8_LDA(dst, b, h) do { _Pragma("unroll") for (int m = 0; m < 4; ++m) _Pragma("unroll") for (int k = 0; k < 2; ++k) dst[m][k] = *(const LAS bf16x8*)(lds + PG8_SA(b, h) + aoff + m * 2048 + k * 1024); } while (0)
; #define PG8_LDB(dst, b, h) do { _Pragma("unroll") for (int n = 0; n < 2; ++n) _Pragma("unroll") for (int k = 0; k < 2; ++k) dst[n][k] = *(const LAS bf16x8*)(lds + PG8_SB(b, h) + boff + n * 2048 + k * 1024); } while (0)
; #define PG8_MMA(ai, bj, At, Bt) do { __builtin_amdgcn_s_setprio(1); _Pragma("unroll") for (int m = 0; m < 4; ++m) _Pragma("unroll") for (int n = 0; n < 2; ++n) _Pragma("unroll") for (int k = 0; k < 2; ++k) \
;         acc[ai][bj][m][n] = __builtin_amdgcn_mfma_f32_16x16x32_bf16(Bt[n][k], At[m][k], acc[ai][bj][m][n], 0, 0, 0); __builtin_amdgcn_s_setprio(0); } while (0)
; #define PG8_WAIT_V(n) asm volatile("s_waitcnt vmcnt(" #n ")" ::: "memory")
; #define PG8_WAIT_L(n) asm volatile("s_waitcnt lgkmcnt(" #n ")" ::: "memory")
; #define PG8_BAR __builtin_amdgcn_s_barrier()
; #define PG8_SCHED __builtin_amdgcn_sched_barrier(0)
; template <class Epi>
; __device__ __forceinline__ void gemm_phase(LAS unsigned char* lds, const Gemm g, const StaticOrder& S, const Epi& E) {
;     ...
;             PG8_STAGE(PG8_SB(0, 1), b2, hB, 0);
;             PG8_WAIT_V(6); PG8_BAR; PG8_MMA(1, 1, At, B1); PG8_BAR;
;             PG8_LDB(B0, 1, 0); PG8_SCHED; PG8_LDA(At, 1, 0); PG8_STAGE(PG8_SA(0, 1), a2, hA, 0);
;             PG8_WAIT_L(8); PG8_BAR; PG8_WAIT_L(0); PG8_MMA(0, 0, At, B0); PG8_BAR; PG8_SCHED;
;             PG8_LDB(B1, 1, 1); PG8_STAGE(PG8_SB(1, 0), b2 + KS, 0, 0);
;             PG8_BAR; PG8_WAIT_L(0); PG8_MMA(0, 1, At, B1); PG8_BAR;
;             PG8_LDA(At, 1, 1); PG8_STAGE(PG8_SA(1, 0), a2 + KS, 0, 0);
	s_add_u32 s66, s58, 0x80000
	s_addc_u32 s67, s59, 0
	s_mov_b32 m0, s29
	s_nop 0
	global_load_lds_dwordx4 v130, s[66:67]
	s_add_u32 s66, s58, 0x82000
	s_addc_u32 s67, s59, 0
	s_mov_b32 m0, s30
	s_nop 0
	global_load_lds_dwordx4 v130, s[66:67]
	s_waitcnt vmcnt(10)
	s_barrier
	v_mfma_f32_16x16x32_bf16 v[48:51], v[184:187], v[152:155], v[48:51]
	v_mfma_f32_16x16x32_bf16 v[40:43], v[204:207], v[152:155], v[40:43]
	v_mfma_f32_16x16x32_bf16 v[32:35], v[184:187], v[160:163], v[32:35]
	v_mfma_f32_16x16x32_bf16 v[24:27], v[204:207], v[160:163], v[24:27]
	v_mfma_f32_16x16x32_bf16 v[16:19], v[184:187], v[168:171], v[16:19]
	v_mfma_f32_16x16x32_bf16 v[8:11], v[204:207], v[168:171], v[8:11]
	v_mfma_f32_16x16x32_bf16 v[4:7], v[184:187], v[176:179], v[4:7]
	v_mfma_f32_16x16x32_bf16 v[0:3], v[204:207], v[176:179], v[0:3]
	v_mfma_f32_16x16x32_bf16 v[48:51], v[200:203], v[156:159], v[48:51]
	v_mfma_f32_16x16x32_bf16 v[40:43], v[208:211], v[156:159], v[40:43]
	v_mfma_f32_16x16x32_bf16 v[32:35], v[200:203], v[164:167], v[32:35]
	v_mfma_f32_16x16x32_bf16 v[24:27], v[208:211], v[164:167], v[24:27]
	v_mfma_f32_16x16x32_bf16 v[16:19], v[200:203], v[172:175], v[16:19]
	v_mfma_f32_16x16x32_bf16 v[8:11], v[208:211], v[172:175], v[8:11]
	v_mfma_f32_16x16x32_bf16 v[4:7], v[200:203], v[180:183], v[4:7]
	v_mfma_f32_16x16x32_bf16 v[0:3], v[208:211], v[180:183], v[0:3]
	v_add_u32_e32 v128, 0x18000, v133
	s_barrier
	ds_read_b128 v[136:139], v128
	ds_read_b128 v[140:143], v128 offset:1024
	ds_read_b128 v[144:147], v128 offset:2048
	ds_read_b128 v[148:151], v128 offset:3072
	ds_read_b128 v[152:155], v134 offset:32768
	ds_read_b128 v[156:159], v134 offset:33792
	ds_read_b128 v[160:163], v134 offset:34816
	ds_read_b128 v[164:167], v134 offset:35840
	ds_read_b128 v[168:171], v134 offset:36864
	ds_read_b128 v[172:175], v134 offset:37888
	ds_read_b128 v[176:179], v134 offset:38912
	ds_read_b128 v[180:183], v134 offset:39936
	s_add_u32 s66, s54, 0x80000
	s_addc_u32 s67, s55, 0
	s_mov_b32 m0, s34
	s_nop 0
	global_load_lds_dwordx4 v130, s[66:67]
	s_add_u32 s66, s54, 0x82000
	s_addc_u32 s67, s55, 0
	s_mov_b32 m0, s37
	s_nop 0
	global_load_lds_dwordx4 v130, s[66:67]
	s_waitcnt lgkmcnt(8)
	s_waitcnt vmcnt(10)
	s_barrier
	s_waitcnt lgkmcnt(7)
	v_mfma_f32_16x16x32_bf16 v[124:127], v[136:139], v[152:155], v[124:127]
	v_mfma_f32_16x16x32_bf16 v[120:123], v[144:147], v[152:155], v[120:123]
	s_waitcnt lgkmcnt(5)
	v_mfma_f32_16x16x32_bf16 v[116:119], v[136:139], v[160:163], v[116:119]
	v_mfma_f32_16x16x32_bf16 v[108:111], v[144:147], v[160:163], v[108:111]
	s_waitcnt lgkmcnt(3)
	v_mfma_f32_16x16x32_bf16 v[100:103], v[136:139], v[168:171], v[100:103]
	v_mfma_f32_16x16x32_bf16 v[92:95], v[144:147], v[168:171], v[92:95]
	s_waitcnt lgkmcnt(1)
	v_mfma_f32_16x16x32_bf16 v[84:87], v[136:139], v[176:179], v[84:87]
	v_mfma_f32_16x16x32_bf16 v[76:79], v[144:147], v[176:179], v[76:79]
	v_mfma_f32_16x16x32_bf16 v[124:127], v[140:143], v[156:159], v[124:127]
	v_mfma_f32_16x16x32_bf16 v[120:123], v[148:151], v[156:159], v[120:123]
	v_mfma_f32_16x16x32_bf16 v[116:119], v[140:143], v[164:167], v[116:119]
	v_mfma_f32_16x16x32_bf16 v[108:111], v[148:151], v[164:167], v[108:111]
	v_mfma_f32_16x16x32_bf16 v[100:103], v[140:143], v[172:175], v[100:103]
	v_mfma_f32_16x16x32_bf16 v[92:95], v[148:151], v[172:175], v[92:95]
	s_waitcnt lgkmcnt(0)
	v_mfma_f32_16x16x32_bf16 v[84:87], v[140:143], v[180:183], v[84:87]
	v_mfma_f32_16x16x32_bf16 v[76:79], v[148:151], v[180:183], v[76:79]
	s_barrier
	v_add_u32_e32 v128, 0x1c000, v133
	ds_read_b128 v[184:187], v128
	ds_read_b128 v[200:203], v128 offset:1024
	ds_read_b128 v[204:207], v128 offset:2048
	ds_read_b128 v[208:211], v128 offset:3072
	s_add_u32 s66, s58, 0x4000
	s_addc_u32 s67, s59, 0
	s_mov_b32 m0, s38
	s_nop 0
	global_load_lds_dwordx4 v130, s[66:67]
	s_add_u32 s66, s58, 0x6000
	s_addc_u32 s67, s59, 0
	s_mov_b32 m0, s39
	s_nop 0
	global_load_lds_dwordx4 v130, s[66:67]
	s_waitcnt vmcnt(10)
	s_barrier
	s_waitcnt lgkmcnt(3)
	v_mfma_f32_16x16x32_bf16 v[112:115], v[184:187], v[152:155], v[112:115]
	s_waitcnt lgkmcnt(1)
	v_mfma_f32_16x16x32_bf16 v[104:107], v[204:207], v[152:155], v[104:107]
	v_mfma_f32_16x16x32_bf16 v[96:99], v[184:187], v[160:163], v[96:99]
	v_mfma_f32_16x16x32_bf16 v[88:91], v[204:207], v[160:163], v[88:91]
	v_mfma_f32_16x16x32_bf16 v[80:83], v[184:187], v[168:171], v[80:83]
	v_mfma_f32_16x16x32_bf16 v[72:75], v[204:207], v[168:171], v[72:75]
	v_mfma_f32_16x16x32_bf16 v[68:71], v[184:187], v[176:179], v[68:71]
	v_mfma_f32_16x16x32_bf16 v[64:67], v[204:207], v[176:179], v[64:67]
	v_mfma_f32_16x16x32_bf16 v[112:115], v[200:203], v[156:159], v[112:115]
	s_waitcnt lgkmcnt(0)
	v_mfma_f32_16x16x32_bf16 v[104:107], v[208:211], v[156:159], v[104:107]
	v_mfma_f32_16x16x32_bf16 v[96:99], v[200:203], v[164:167], v[96:99]
	v_mfma_f32_16x16x32_bf16 v[88:91], v[208:211], v[164:167], v[88:91]
	v_mfma_f32_16x16x32_bf16 v[80:83], v[200:203], v[172:175], v[80:83]
	v_mfma_f32_16x16x32_bf16 v[72:75], v[208:211], v[172:175], v[72:75]
	v_mfma_f32_16x16x32_bf16 v[68:71], v[200:203], v[180:183], v[68:71]
	v_mfma_f32_16x16x32_bf16 v[64:67], v[208:211], v[180:183], v[64:67]
	s_barrier
	ds_read_b128 v[152:155], v134 offset:49152
	ds_read_b128 v[156:159], v134 offset:50176
	ds_read_b128 v[160:163], v134 offset:51200
	ds_read_b128 v[164:167], v134 offset:52224
	ds_read_b128 v[168:171], v134 offset:53248
	ds_read_b128 v[172:175], v134 offset:54272
	ds_read_b128 v[176:179], v134 offset:55296
	ds_read_b128 v[180:183], v134 offset:56320
	s_add_u32 s66, s54, 0x4000
	s_addc_u32 s67, s55, 0
	s_mov_b32 m0, s40
	s_nop 0
	global_load_lds_dwordx4 v130, s[66:67]
	s_add_u32 s54, s54, 0x6000
	s_addc_u32 s55, s55, 0
	s_mov_b32 m0, s41
	s_nop 0
	global_load_lds_dwordx4 v130, s[54:55]
	s_barrier
; #define PG8_STAGE(bufoff, gbase, hoff, imm) do { _Pragma("unroll") for (int _i = 0; _i < 2; ++_i) { \
;         asm volatile("s_mov_b32 m0, %0\n\ts_nop 0\n\tglobal_load_lds_dwordx4 %1, %2" \
;             :: "s"(lds0 + (unsigned)((bufoff) + _i * 8192)), "v"(voff0), "s"((const char*)(gbase) + (size_t)(hoff) + (size_t)(_i * 8192)) : "memory"); } } while (0)
; #define PG8_MMA(ai, bj, At, Bt) do { __builtin_amdgcn_s_setprio(1); _Pragma("unroll") for (int m = 0; m < 4; ++m) _Pragma("unroll") for (int n = 0; n < 2; ++n) _Pragma("unroll") for (int k = 0; k < 2; ++k) \
;         acc[ai][bj][m][n] = __builtin_amdgcn_mfma_f32_16x16x32_bf16(Bt[n][k], At[m][k], acc[ai][bj][m][n], 0, 0, 0); __builtin_amdgcn_s_setprio(0); } while (0)
; #define PG8_WAIT_V(n) asm volatile("s_waitcnt vmcnt(" #n ")" ::: "memory")
; #define PG8_WAIT_L(n) asm volatile("s_waitcnt lgkmcnt(" #n ")" ::: "memory")
; #define PG8_BAR __builtin_amdgcn_s_barrier()
; #define PG8_SCHED __builtin_amdgcn_sched_barrier(0)
; template <class Epi>
; __device__ __forceinline__ void gemm_phase(LAS unsigned char* lds, const Gemm g, const StaticOrder& S, const Epi& E) {
;     ...
;             PG8_BAR; PG8_WAIT_L(0); PG8_MMA(1, 0, At, B0); PG8_BAR; PG8_SCHED;
;             PG8_STAGE(PG8_SB(1, 1), b2 + KS, hB, 0);
;             PG8_WAIT_V(6); PG8_BAR; PG8_MMA(1, 1, At, B1); PG8_BAR;
	s_waitcnt lgkmcnt(7)
	v_mfma_f32_16x16x32_bf16 v[60:63], v[136:139], v[152:155], v[60:63]
	v_mfma_f32_16x16x32_bf16 v[56:59], v[144:147], v[152:155], v[56:59]
	s_waitcnt lgkmcnt(5)
	v_mfma_f32_16x16x32_bf16 v[52:55], v[136:139], v[160:163], v[52:55]
	v_mfma_f32_16x16x32_bf16 v[44:47], v[144:147], v[160:163], v[44:47]
	s_waitcnt lgkmcnt(3)
	v_mfma_f32_16x16x32_bf16 v[36:39], v[136:139], v[168:171], v[36:39]
	v_mfma_f32_16x16x32_bf16 v[28:31], v[144:147], v[168:171], v[28:31]
	s_waitcnt lgkmcnt(1)
	v_mfma_f32_16x16x32_bf16 v[20:23], v[136:139], v[176:179], v[20:23]
	v_mfma_f32_16x16x32_bf16 v[12:15], v[144:147], v[176:179], v[12:15]
	v_mfma_f32_16x16x32_bf16 v[60:63], v[140:143], v[156:159], v[60:63]
	v_mfma_f32_16x16x32_bf16 v[56:59], v[148:151], v[156:159], v[56:59]
	v_mfma_f32_16x16x32_bf16 v[52:55], v[140:143], v[164:167], v[52:55]
	v_mfma_f32_16x16x32_bf16 v[44:47], v[148:151], v[164:167], v[44:47]
	v_mfma_f32_16x16x32_bf16 v[36:39], v[140:143], v[172:175], v[36:39]
	v_mfma_f32_16x16x32_bf16 v[28:31], v[148:151], v[172:175], v[28:31]
	s_waitcnt lgkmcnt(0)
	v_mfma_f32_16x16x32_bf16 v[20:23], v[140:143], v[180:183], v[20:23]
	v_mfma_f32_16x16x32_bf16 v[12:15], v[148:151], v[180:183], v[12:15]
	s_barrier
	s_add_u32 s54, s58, 0x84000
	s_addc_u32 s55, s59, 0
	s_mov_b32 m0, s42
	s_nop 0
	global_load_lds_dwordx4 v130, s[54:55]
	s_add_u32 s54, s58, 0x86000
	s_addc_u32 s55, s59, 0
	s_mov_b32 m0, s43
	s_nop 0
	global_load_lds_dwordx4 v130, s[54:55]
	s_waitcnt vmcnt(10)
	s_barrier
	v_mfma_f32_16x16x32_bf16 v[48:51], v[184:187], v[152:155], v[48:51]
	v_mfma_f32_16x16x32_bf16 v[40:43], v[204:207], v[152:155], v[40:43]
	v_mfma_f32_16x16x32_bf16 v[32:35], v[184:187], v[160:163], v[32:35]
	v_mfma_f32_16x16x32_bf16 v[24:27], v[204:207], v[160:163], v[24:27]
	v_mfma_f32_16x16x32_bf16 v[16:19], v[184:187], v[168:171], v[16:19]
	v_mfma_f32_16x16x32_bf16 v[8:11], v[204:207], v[168:171], v[8:11]
	v_mfma_f32_16x16x32_bf16 v[4:7], v[184:187], v[176:179], v[4:7]
	v_mfma_f32_16x16x32_bf16 v[0:3], v[204:207], v[176:179], v[0:3]
	v_mfma_f32_16x16x32_bf16 v[48:51], v[200:203], v[156:159], v[48:51]
	v_mfma_f32_16x16x32_bf16 v[40:43], v[208:211], v[156:159], v[40:43]
	v_mfma_f32_16x16x32_bf16 v[32:35], v[200:203], v[164:167], v[32:35]
	v_mfma_f32_16x16x32_bf16 v[24:27], v[208:211], v[164:167], v[24:27]
	v_mfma_f32_16x16x32_bf16 v[16:19], v[200:203], v[172:175], v[16:19]
	v_mfma_f32_16x16x32_bf16 v[8:11], v[208:211], v[172:175], v[8:11]
	v_mfma_f32_16x16x32_bf16 v[4:7], v[200:203], v[180:183], v[4:7]
	v_mfma_f32_16x16x32_bf16 v[0:3], v[208:211], v[180:183], v[0:3]
	s_add_i32 s65, s65, 2
	s_add_u32 s63, s63, 0x8000
	s_addc_u32 s64, s64, 0
	s_cmp_gt_u32 s65, 29
	s_mov_b64 s[54:55], s[56:57]
	s_barrier
	s_cbranch_scc0 .LBB0_434
; #define LAS __attribute__((address_space(3)))
; __device__ __forceinline__ unsigned cvt_pk_bf16(float lo, float hi) { unsigned r; asm volatile("v_cvt_pk_bf16_f32 %0, %1, %2" : "=v"(r) : "v"(lo), "v"(hi)); return r; }
;     __device__ __forceinline__ void operator()(f32x4 (&acc)[2][2][4][2], const Unit& u, int wr, int wc, int fr, int fq, LAS unsigned char*) const {
;         const int row0 = u.pm * BM + wr * 64 + fr, col0 = u.pn * BM + wc * 32 + 8 * fq;
; #pragma unroll
;         for (int ai = 0; ai < 2; ++ai)
; #pragma unroll
;             for (int m = 0; m < 4; ++m) { bf16_t* rowp = O + (size_t)(row0 + ai * HALF + m * 16) * ldc + col0;
; #pragma unroll
;                 for (int bj = 0; bj < 2; ++bj) { const f32x4 v0 = acc[ai][bj][m][0], v1 = acc[ai][bj][m][1];
;                     u32x4 w; w.x = cvt_pk_bf16(v0[0], v0[1]); w.y = cvt_pk_bf16(v0[2], v0[3]); w.z = cvt_pk_bf16(v1[0], v1[1]); w.w = cvt_pk_bf16(v1[2], v1[3]);
;                     *(u32x4*)(rowp + bj * HALF) = w; } }
;     }
	v_lshl_add_u32 v136, s62, 8, v131
	v_lshl_or_b32 v128, s61, 8, v132
	v_ashrrev_i32_e32 v137, 31, v136
	v_ashrrev_i32_e32 v129, 31, v128
	v_lshlrev_b64 v[138:139], 12, v[136:137]
	v_lshl_add_u64 v[138:139], s[2:3], 0, v[138:139]
	v_lshlrev_b64 v[140:141], 1, v[128:129]
	v_lshl_add_u64 v[128:129], v[138:139], 0, v[140:141]
	v_cvt_pk_bf16_f32 v124, v124, v125
	v_cvt_pk_bf16_f32 v125, v126, v127
	v_cvt_pk_bf16_f32 v126, v120, v121
	v_cvt_pk_bf16_f32 v127, v122, v123
	global_store_dwordx4 v[128:129], v[124:127], off
	v_cvt_pk_bf16_f32 v112, v112, v113
	v_cvt_pk_bf16_f32 v113, v114, v115
	v_cvt_pk_bf16_f32 v114, v104, v105
	v_or_b32_e32 v104, 16, v136
	v_ashrrev_i32_e32 v105, 31, v104
	v_lshlrev_b64 v[104:105], 12, v[104:105]
	v_lshl_add_u64 v[104:105], s[2:3], 0, v[104:105]
	v_cvt_pk_bf16_f32 v115, v106, v107
	global_store_dwordx4 v[128:129], v[112:115], off offset:256
	s_mov_b64 s[0:1], 0x80000
	s_mov_b32 s61, s6
	v_lshl_add_u64 v[112:113], v[104:105], 0, v[140:141]
	v_cvt_pk_bf16_f32 v104, v116, v117
	v_cvt_pk_bf16_f32 v105, v118, v119
	v_cvt_pk_bf16_f32 v106, v108, v109
	v_cvt_pk_bf16_f32 v107, v110, v111
	global_store_dwordx4 v[112:113], v[104:107], off
	v_cvt_pk_bf16_f32 v96, v96, v97
	v_cvt_pk_bf16_f32 v97, v98, v99
	v_cvt_pk_bf16_f32 v98, v88, v89
	v_or_b32_e32 v88, 32, v136
	v_ashrrev_i32_e32 v89, 31, v88
	v_lshlrev_b64 v[88:89], 12, v[88:89]
	v_lshl_add_u64 v[88:89], s[2:3], 0, v[88:89]
	v_cvt_pk_bf16_f32 v99, v90, v91
	global_store_dwordx4 v[112:113], v[96:99], off offset:256
	s_mov_b32 s62, s8
	s_mov_b64 s[56:57], s[52:53]
	v_lshl_add_u64 v[96:97], v[88:89], 0, v[140:141]
	v_cvt_pk_bf16_f32 v88, v100, v101
	v_cvt_pk_bf16_f32 v89, v102, v103
	v_cvt_pk_bf16_f32 v90, v92, v93
	v_cvt_pk_bf16_f32 v91, v94, v95
	global_store_dwordx4 v[96:97], v[88:91], off
	v_cvt_pk_bf16_f32 v80, v80, v81
	v_cvt_pk_bf16_f32 v81, v82, v83
	v_cvt_pk_bf16_f32 v82, v72, v73
	v_or_b32_e32 v72, 48, v136
	v_ashrrev_i32_e32 v73, 31, v72
	v_lshlrev_b64 v[72:73], 12, v[72:73]
	v_lshl_add_u64 v[72:73], s[2:3], 0, v[72:73]
	v_cvt_pk_bf16_f32 v83, v74, v75
	global_store_dwordx4 v[96:97], v[80:83], off offset:256
	s_mov_b64 s[54:55], s[10:11]
	s_nop 0
	v_lshl_add_u64 v[80:81], v[72:73], 0, v[140:141]
	v_cvt_pk_bf16_f32 v72, v84, v85
	v_cvt_pk_bf16_f32 v73, v86, v87
	v_cvt_pk_bf16_f32 v74, v76, v77
	v_cvt_pk_bf16_f32 v75, v78, v79
	global_store_dwordx4 v[80:81], v[72:75], off
	v_cvt_pk_bf16_f32 v68, v68, v69
	v_cvt_pk_bf16_f32 v69, v70, v71
	v_cvt_pk_bf16_f32 v70, v64, v65
	v_cvt_pk_bf16_f32 v71, v66, v67
	global_store_dwordx4 v[80:81], v[68:71], off offset:256
	v_cvt_pk_bf16_f32 v60, v60, v61
	v_cvt_pk_bf16_f32 v61, v62, v63
	v_cvt_pk_bf16_f32 v62, v56, v57
	v_add_co_u32_e32 v56, vcc, s93, v128
	v_lshl_add_u64 v[64:65], v[128:129], 0, s[0:1]
	s_nop 0
	v_addc_co_u32_e32 v57, vcc, 0, v129, vcc
	v_cvt_pk_bf16_f32 v63, v58, v59
	global_store_dwordx4 v[56:57], v[60:63], off
	v_cvt_pk_bf16_f32 v48, v48, v49
	v_cvt_pk_bf16_f32 v49, v50, v51
	v_cvt_pk_bf16_f32 v50, v40, v41
	v_cvt_pk_bf16_f32 v51, v42, v43
	global_store_dwordx4 v[64:65], v[48:51], off offset:256
	s_mov_b64 s[0:1], 0x90000
	v_cvt_pk_bf16_f32 v40, v52, v53
	v_cvt_pk_bf16_f32 v41, v54, v55
	v_cvt_pk_bf16_f32 v42, v44, v45
	v_add_co_u32_e32 v44, vcc, s33, v128
	v_lshl_add_u64 v[48:49], v[128:129], 0, s[0:1]
	s_nop 0
	v_addc_co_u32_e32 v45, vcc, 0, v129, vcc
	v_cvt_pk_bf16_f32 v43, v46, v47
	global_store_dwordx4 v[44:45], v[40:43], off
	v_cvt_pk_bf16_f32 v32, v32, v33
	v_cvt_pk_bf16_f32 v33, v34, v35
	v_cvt_pk_bf16_f32 v34, v24, v25
	v_cvt_pk_bf16_f32 v35, v26, v27
	global_store_dwordx4 v[48:49], v[32:35], off offset:256
	s_mov_b64 s[0:1], 0xa0000
	v_cvt_pk_bf16_f32 v24, v36, v37
	v_cvt_pk_bf16_f32 v25, v38, v39
	v_cvt_pk_bf16_f32 v26, v28, v29
	v_add_co_u32_e32 v28, vcc, s18, v128
	v_lshl_add_u64 v[32:33], v[128:129], 0, s[0:1]
	s_nop 0
	v_addc_co_u32_e32 v29, vcc, 0, v129, vcc
	v_cvt_pk_bf16_f32 v27, v30, v31
	global_store_dwordx4 v[28:29], v[24:27], off
	v_cvt_pk_bf16_f32 v16, v16, v17
	v_cvt_pk_bf16_f32 v17, v18, v19
	v_cvt_pk_bf16_f32 v18, v8, v9
	v_cvt_pk_bf16_f32 v19, v10, v11
	global_store_dwordx4 v[32:33], v[16:19], off offset:256
	v_cvt_pk_bf16_f32 v8, v20, v21
	v_cvt_pk_bf16_f32 v9, v22, v23
	v_cvt_pk_bf16_f32 v10, v12, v13
	v_add_co_u32_e32 v12, vcc, s19, v128
	s_mov_b64 s[0:1], 0xb0000
	s_nop 0
	v_addc_co_u32_e32 v13, vcc, 0, v129, vcc
	v_lshl_add_u64 v[16:17], v[128:129], 0, s[0:1]
	s_and_b64 vcc, exec, s[4:5]
	v_cvt_pk_bf16_f32 v11, v14, v15
	global_store_dwordx4 v[12:13], v[8:11], off
	v_cvt_pk_bf16_f32 v4, v4, v5
	v_cvt_pk_bf16_f32 v5, v6, v7
	v_cvt_pk_bf16_f32 v6, v0, v1
	v_cvt_pk_bf16_f32 v7, v2, v3
	global_store_dwordx4 v[16:17], v[4:7], off offset:256
	s_cbranch_vccz .LBB0_427
	s_waitcnt vmcnt(0)
	s_cmpk_gt_u32 s16, 0xff
	v_readlane_b32 s38, v255, 44
	s_cbranch_scc1 .LBB0_438
	s_barrier

; #define PG8_STAGE(bufoff, gbase, hoff, imm) do { _Pragma("unroll") for (int _i = 0; _i < 2; ++_i) { \
;         asm volatile("s_mov_b32 m0, %0\n\ts_nop 0\n\tglobal_load_lds_dwordx4 %1, %2" \
;             :: "s"(lds0 + (unsigned)((bufoff) + _i * 8192)), "v"(voff0), "s"((const char*)(gbase) + (size_t)(hoff) + (size_t)(_i * 8192)) : "memory"); } } while (0)
; #define PG8_LDA(dst, b, h) do { _Pragma("unroll") for (int m = 0; m < 4; ++m) _Pragma("unroll") for (int k = 0; k < 2; ++k) dst[m][k] = *(const LAS bf16x8*)(lds + PG8_SA(b, h) + aoff + m * 2048 + k * 1024); } while (0)
; #define PG8_LDB(dst, b, h) do { _Pragma("unroll") for (int n = 0; n < 2; ++n) _Pragma("unroll") for (int k = 0; k < 2; ++k) dst[n][k] = *(const LAS bf16x8*)(lds + PG8_SB(b, h) + boff + n * 2048 + k * 1024); } while (0)
; #define PG8_MMA(ai, bj, At, Bt) do { __builtin_amdgcn_s_setprio(1); _Pragma("unroll") for (int m = 0; m < 4; ++m) _Pragma("unroll") for (int n = 0; n < 2; ++n) _Pragma("unroll") for (int k = 0; k < 2; ++k) \
;         acc[ai][bj][m][n] = __builtin_amdgcn_mfma_f32_16x16x32_bf16(Bt[n][k], At[m][k], acc[ai][bj][m][n], 0, 0, 0); __builtin_amdgcn_s_setprio(0); } while (0)
; #define PG8_WAIT_L(n) asm volatile("s_waitcnt lgkmcnt(" #n ")" ::: "memory")
; #define PG8_BAR __builtin_amdgcn_s_barrier()
; #define PG8_SCHED __builtin_amdgcn_sched_barrier(0)
; template <class Epi>
; __device__ __forceinline__ void gemm_phase(LAS unsigned char* lds, const Gemm g, const StaticOrder& S, const Epi& E) {
;     ...
;             const char* aT = cA + (size_t)t * KS;
;             const char* a2 = last ? nA : aT + 2 * KS; const char* b2 = last ? nB : cB + (size_t)(t + 2) * KS;
;             PG8_LDB(B0, 0, 0); PG8_SCHED; PG8_LDA(At, 0, 0); PG8_STAGE(PG8_SA(1, 1), aT + KS, hA, 0);
;             PG8_WAIT_L(8); PG8_BAR; PG8_WAIT_L(0); PG8_MMA(0, 0, At, B0); PG8_BAR; PG8_SCHED;
;             PG8_LDB(B1, 0, 1); PG8_STAGE(PG8_SB(0, 0), b2, 0, 0);
;             PG8_BAR; PG8_WAIT_L(0); PG8_MMA(0, 1, At, B1); PG8_BAR;
;             PG8_LDA(At, 0, 1); PG8_STAGE(PG8_SA(0, 0), a2, 0, 0);
;             PG8_BAR; PG8_WAIT_L(0); PG8_MMA(1, 0, At, B0); PG8_BAR; PG8_SCHED;
.LBB0_506:
	v_add_u32_e32 v140, 0x10000, v202
	ds_read_b128 v[128:131], v140
	ds_read_b128 v[132:135], v140 offset:1024
	ds_read_b128 v[136:139], v140 offset:2048
	ds_read_b128 v[140:143], v140 offset:3072
	s_add_u32 s80, s78, 0x8000
	s_addc_u32 s81, s79, 0
	s_and_b64 s[82:83], s[84:85], exec
	s_cselect_b32 s83, s51, s81
	s_cselect_b32 s82, s71, s80
	ds_read_b128 v[144:147], v203
	ds_read_b128 v[148:151], v203 offset:1024
	ds_read_b128 v[152:155], v203 offset:2048
	ds_read_b128 v[156:159], v203 offset:3072
	ds_read_b128 v[160:163], v203 offset:4096
	ds_read_b128 v[164:167], v203 offset:5120
	ds_read_b128 v[204:207], v203 offset:6144
	ds_read_b128 v[208:211], v203 offset:7168
	s_add_u32 s48, s78, 0x84000
	s_addc_u32 s49, s79, 0
	s_mov_b32 m0, s87
	s_nop 0
	global_load_lds_dwordx4 v168, s[48:49]
	s_add_u32 s48, s78, 0x86000
	s_addc_u32 s49, s79, 0
	s_mov_b32 m0, s96
	s_nop 0
	global_load_lds_dwordx4 v168, s[48:49]
	s_waitcnt lgkmcnt(8)
	s_waitcnt vmcnt(10)
	s_barrier
	s_waitcnt lgkmcnt(7)
	v_mfma_f32_16x16x32_bf16 v[96:99], v[128:131], v[144:147], v[96:99]
	v_mfma_f32_16x16x32_bf16 v[44:47], v[136:139], v[144:147], v[44:47]
	s_waitcnt lgkmcnt(5)
	v_mfma_f32_16x16x32_bf16 v[92:95], v[128:131], v[152:155], v[92:95]
	v_mfma_f32_16x16x32_bf16 v[40:43], v[136:139], v[152:155], v[40:43]
	s_waitcnt lgkmcnt(3)
	v_mfma_f32_16x16x32_bf16 v[84:87], v[128:131], v[160:163], v[84:87]
	v_mfma_f32_16x16x32_bf16 v[36:39], v[136:139], v[160:163], v[36:39]
	s_waitcnt lgkmcnt(1)
	v_mfma_f32_16x16x32_bf16 v[124:127], v[128:131], v[204:207], v[124:127]
	v_mfma_f32_16x16x32_bf16 v[120:123], v[136:139], v[204:207], v[120:123]
	v_mfma_f32_16x16x32_bf16 v[96:99], v[132:135], v[148:151], v[96:99]
	v_mfma_f32_16x16x32_bf16 v[44:47], v[140:143], v[148:151], v[44:47]
	v_mfma_f32_16x16x32_bf16 v[92:95], v[132:135], v[156:159], v[92:95]
	v_mfma_f32_16x16x32_bf16 v[40:43], v[140:143], v[156:159], v[40:43]
	v_mfma_f32_16x16x32_bf16 v[84:87], v[132:135], v[164:167], v[84:87]
	v_mfma_f32_16x16x32_bf16 v[36:39], v[140:143], v[164:167], v[36:39]
	s_waitcnt lgkmcnt(0)
	v_mfma_f32_16x16x32_bf16 v[124:127], v[132:135], v[208:211], v[124:127]
	v_mfma_f32_16x16x32_bf16 v[120:123], v[140:143], v[208:211], v[120:123]
	s_barrier
	v_add_u32_e32 v188, 0x14000, v202
	ds_read_b128 v[212:215], v188
	ds_read_b128 v[236:239], v188 offset:1024
	ds_read_b128 v[240:243], v188 offset:2048
	ds_read_b128 v[244:247], v188 offset:3072
	s_and_b64 s[48:49], s[84:85], exec
	s_cselect_b32 s78, s62, s9
	s_cselect_b32 s79, s69, s63
	s_mov_b32 m0, s25
	s_nop 0
	global_load_lds_dwordx4 v168, s[78:79]
	s_add_u32 s48, s78, 0x2000
	s_addc_u32 s49, s79, 0
	s_mov_b32 m0, s26
	s_nop 0
	global_load_lds_dwordx4 v168, s[48:49]
	s_waitcnt vmcnt(10)
	s_barrier
	s_waitcnt lgkmcnt(3)
	v_mfma_f32_16x16x32_bf16 v[80:83], v[212:215], v[144:147], v[80:83]
	s_waitcnt lgkmcnt(1)
	v_mfma_f32_16x16x32_bf16 v[32:35], v[240:243], v[144:147], v[32:35]
	v_mfma_f32_16x16x32_bf16 v[76:79], v[212:215], v[152:155], v[76:79]
	v_mfma_f32_16x16x32_bf16 v[28:31], v[240:243], v[152:155], v[28:31]
	v_mfma_f32_16x16x32_bf16 v[72:75], v[212:215], v[160:163], v[72:75]
	v_mfma_f32_16x16x32_bf16 v[24:27], v[240:243], v[160:163], v[24:27]
	v_mfma_f32_16x16x32_bf16 v[116:119], v[212:215], v[204:207], v[116:119]
	v_mfma_f32_16x16x32_bf16 v[112:115], v[240:243], v[204:207], v[112:115]
	v_mfma_f32_16x16x32_bf16 v[80:83], v[236:239], v[148:151], v[80:83]
	s_waitcnt lgkmcnt(0)
	v_mfma_f32_16x16x32_bf16 v[32:35], v[244:247], v[148:151], v[32:35]
	v_mfma_f32_16x16x32_bf16 v[76:79], v[236:239], v[156:159], v[76:79]
	v_mfma_f32_16x16x32_bf16 v[28:31], v[244:247], v[156:159], v[28:31]
	v_mfma_f32_16x16x32_bf16 v[72:75], v[236:239], v[164:167], v[72:75]
	v_mfma_f32_16x16x32_bf16 v[24:27], v[244:247], v[164:167], v[24:27]
	v_mfma_f32_16x16x32_bf16 v[116:119], v[236:239], v[208:211], v[116:119]
	v_mfma_f32_16x16x32_bf16 v[112:115], v[244:247], v[208:211], v[112:115]
	s_barrier
	ds_read_b128 v[144:147], v203 offset:16384
	ds_read_b128 v[148:151], v203 offset:17408
	ds_read_b128 v[152:155], v203 offset:18432
	ds_read_b128 v[156:159], v203 offset:19456
	ds_read_b128 v[160:163], v203 offset:20480
	ds_read_b128 v[164:167], v203 offset:21504
	ds_read_b128 v[204:207], v203 offset:22528
	ds_read_b128 v[208:211], v203 offset:23552
	s_mov_b32 m0, s24
	s_nop 0
	global_load_lds_dwordx4 v168, s[82:83]
	s_add_u32 s48, s82, 0x2000
	s_addc_u32 s49, s83, 0
	s_mov_b32 m0, s27
	s_nop 0
	global_load_lds_dwordx4 v168, s[48:49]
	s_barrier
	s_waitcnt lgkmcnt(7)
	v_mfma_f32_16x16x32_bf16 v[68:71], v[128:131], v[144:147], v[68:71]
	v_mfma_f32_16x16x32_bf16 v[20:23], v[136:139], v[144:147], v[20:23]
	s_waitcnt lgkmcnt(5)
	v_mfma_f32_16x16x32_bf16 v[64:67], v[128:131], v[152:155], v[64:67]
	v_mfma_f32_16x16x32_bf16 v[16:19], v[136:139], v[152:155], v[16:19]
	s_waitcnt lgkmcnt(3)
	v_mfma_f32_16x16x32_bf16 v[60:63], v[128:131], v[160:163], v[60:63]
	v_mfma_f32_16x16x32_bf16 v[12:15], v[136:139], v[160:163], v[12:15]
	s_waitcnt lgkmcnt(1)
	v_mfma_f32_16x16x32_bf16 v[108:111], v[128:131], v[204:207], v[108:111]
	v_mfma_f32_16x16x32_bf16 v[104:107], v[136:139], v[204:207], v[104:107]
	v_mfma_f32_16x16x32_bf16 v[68:71], v[132:135], v[148:151], v[68:71]
	v_mfma_f32_16x16x32_bf16 v[20:23], v[140:143], v[148:151], v[20:23]
	v_mfma_f32_16x16x32_bf16 v[64:67], v[132:135], v[156:159], v[64:67]
	v_mfma_f32_16x16x32_bf16 v[16:19], v[140:143], v[156:159], v[16:19]
	v_mfma_f32_16x16x32_bf16 v[60:63], v[132:135], v[164:167], v[60:63]
	v_mfma_f32_16x16x32_bf16 v[12:15], v[140:143], v[164:167], v[12:15]
	s_waitcnt lgkmcnt(0)
	v_mfma_f32_16x16x32_bf16 v[108:111], v[132:135], v[208:211], v[108:111]
	v_mfma_f32_16x16x32_bf16 v[104:107], v[140:143], v[208:211], v[104:107]
	s_barrier
; #define PG8_STAGE(bufoff, gbase, hoff, imm) do { _Pragma("unroll") for (int _i = 0; _i < 2; ++_i) { \
;         asm volatile("s_mov_b32 m0, %0\n\ts_nop 0\n\tglobal_load_lds_dwordx4 %1, %2" \
;             :: "s"(lds0 + (unsigned)((bufoff) + _i * 8192)), "v"(voff0), "s"((const char*)(gbase) + (size_t)(hoff) + (size_t)(_i * 8192)) : "memory"); } } while (0)
; #define PG8_LDA(dst, b, h) do { _Pragma("unroll") for (int m = 0; m < 4; ++m) _Pragma("unroll") for (int k = 0; k < 2; ++k) dst[m][k] = *(const LAS bf16x8*)(lds + PG8_SA(b, h) + aoff + m * 2048 + k * 1024); } while (0)
; #define PG8_LDB(dst, b, h) do { _Pragma("unroll") for (int n = 0; n < 2; ++n) _Pragma("unroll") for (int k = 0; k < 2; ++k) dst[n][k] = *(const LAS bf16x8*)(lds + PG8_SB(b, h) + boff + n * 2048 + k * 1024); } while (0)
; #define PG8_MMA(ai, bj, At, Bt) do { __builtin_amdgcn_s_setprio(1); _Pragma("unroll") for (int m = 0; m < 4; ++m) _Pragma("unroll") for (int n = 0; n < 2; ++n) _Pragma("unroll") for (int k = 0; k < 2; ++k) \
;         acc[ai][bj][m][n] = __builtin_amdgcn_mfma_f32_16x16x32_bf16(Bt[n][k], At[m][k], acc[ai][bj][m][n], 0, 0, 0); __builtin_amdgcn_s_setprio(0); } while (0)
; #define PG8_WAIT_V(n) asm volatile("s_waitcnt vmcnt(" #n ")" ::: "memory")
; #define PG8_WAIT_L(n) asm volatile("s_waitcnt lgkmcnt(" #n ")" ::: "memory")
; #define PG8_BAR __builtin_amdgcn_s_barrier()
; #define PG8_SCHED __builtin_amdgcn_sched_barrier(0)
; template <class Epi>
; __device__ __forceinline__ void gemm_phase(LAS unsigned char* lds, const Gemm g, const StaticOrder& S, const Epi& E) {
;     ...
;             PG8_STAGE(PG8_SB(0, 1), b2, hB, 0);
;             PG8_WAIT_V(6); PG8_BAR; PG8_MMA(1, 1, At, B1); PG8_BAR;
;             PG8_LDB(B0, 1, 0); PG8_SCHED; PG8_LDA(At, 1, 0); PG8_STAGE(PG8_SA(0, 1), a2, hA, 0);
;             PG8_WAIT_L(8); PG8_BAR; PG8_WAIT_L(0); PG8_MMA(0, 0, At, B0); PG8_BAR; PG8_SCHED;
;             PG8_LDB(B1, 1, 1); PG8_STAGE(PG8_SB(1, 0), b2 + KS, 0, 0);
	s_add_u32 s48, s78, 0x80000
	s_addc_u32 s49, s79, 0
	s_mov_b32 m0, s28
	s_nop 0
	global_load_lds_dwordx4 v168, s[48:49]
	s_add_u32 s48, s78, 0x82000
	s_addc_u32 s49, s79, 0
	s_mov_b32 m0, s29
	s_nop 0
	global_load_lds_dwordx4 v168, s[48:49]
	s_waitcnt vmcnt(10)
	s_barrier
	v_mfma_f32_16x16x32_bf16 v[56:59], v[212:215], v[144:147], v[56:59]
	v_mfma_f32_16x16x32_bf16 v[8:11], v[240:243], v[144:147], v[8:11]
	v_mfma_f32_16x16x32_bf16 v[52:55], v[212:215], v[152:155], v[52:55]
	v_mfma_f32_16x16x32_bf16 v[4:7], v[240:243], v[152:155], v[4:7]
	v_mfma_f32_16x16x32_bf16 v[48:51], v[212:215], v[160:163], v[48:51]
	v_mfma_f32_16x16x32_bf16 v[0:3], v[240:243], v[160:163], v[0:3]
	v_mfma_f32_16x16x32_bf16 v[100:103], v[212:215], v[204:207], v[100:103]
	v_mfma_f32_16x16x32_bf16 v[88:91], v[240:243], v[204:207], v[88:91]
	v_mfma_f32_16x16x32_bf16 v[56:59], v[236:239], v[148:151], v[56:59]
	v_mfma_f32_16x16x32_bf16 v[8:11], v[244:247], v[148:151], v[8:11]
	v_mfma_f32_16x16x32_bf16 v[52:55], v[236:239], v[156:159], v[52:55]
	v_mfma_f32_16x16x32_bf16 v[4:7], v[244:247], v[156:159], v[4:7]
	v_mfma_f32_16x16x32_bf16 v[48:51], v[236:239], v[164:167], v[48:51]
	v_mfma_f32_16x16x32_bf16 v[0:3], v[244:247], v[164:167], v[0:3]
	v_mfma_f32_16x16x32_bf16 v[100:103], v[236:239], v[208:211], v[100:103]
	v_mfma_f32_16x16x32_bf16 v[88:91], v[244:247], v[208:211], v[88:91]
	v_add_u32_e32 v140, 0x18000, v202
	s_barrier
	ds_read_b128 v[128:131], v140
	ds_read_b128 v[132:135], v140 offset:1024
	ds_read_b128 v[136:139], v140 offset:2048
	ds_read_b128 v[140:143], v140 offset:3072
	ds_read_b128 v[144:147], v203 offset:32768
	ds_read_b128 v[148:151], v203 offset:33792
	ds_read_b128 v[152:155], v203 offset:34816
	ds_read_b128 v[156:159], v203 offset:35840
	ds_read_b128 v[160:163], v203 offset:36864
	ds_read_b128 v[164:167], v203 offset:37888
	ds_read_b128 v[204:207], v203 offset:38912
	ds_read_b128 v[208:211], v203 offset:39936
	s_add_u32 s48, s82, 0x80000
	s_addc_u32 s49, s83, 0
	s_mov_b32 m0, s30
	s_nop 0
	global_load_lds_dwordx4 v168, s[48:49]
	s_add_u32 s48, s82, 0x82000
	s_addc_u32 s49, s83, 0
	s_mov_b32 m0, s34
	s_nop 0
	global_load_lds_dwordx4 v168, s[48:49]
	s_waitcnt lgkmcnt(8)
	s_waitcnt vmcnt(10)
	s_barrier
	s_waitcnt lgkmcnt(7)
	v_mfma_f32_16x16x32_bf16 v[96:99], v[128:131], v[144:147], v[96:99]
	v_mfma_f32_16x16x32_bf16 v[44:47], v[136:139], v[144:147], v[44:47]
	s_waitcnt lgkmcnt(5)
	v_mfma_f32_16x16x32_bf16 v[92:95], v[128:131], v[152:155], v[92:95]
	v_mfma_f32_16x16x32_bf16 v[40:43], v[136:139], v[152:155], v[40:43]
	s_waitcnt lgkmcnt(3)
	v_mfma_f32_16x16x32_bf16 v[84:87], v[128:131], v[160:163], v[84:87]
	v_mfma_f32_16x16x32_bf16 v[36:39], v[136:139], v[160:163], v[36:39]
	s_waitcnt lgkmcnt(1)
	v_mfma_f32_16x16x32_bf16 v[124:127], v[128:131], v[204:207], v[124:127]
	v_mfma_f32_16x16x32_bf16 v[120:123], v[136:139], v[204:207], v[120:123]
	v_mfma_f32_16x16x32_bf16 v[96:99], v[132:135], v[148:151], v[96:99]
	v_mfma_f32_16x16x32_bf16 v[44:47], v[140:143], v[148:151], v[44:47]
	v_mfma_f32_16x16x32_bf16 v[92:95], v[132:135], v[156:159], v[92:95]
	v_mfma_f32_16x16x32_bf16 v[40:43], v[140:143], v[156:159], v[40:43]
	v_mfma_f32_16x16x32_bf16 v[84:87], v[132:135], v[164:167], v[84:87]
	v_mfma_f32_16x16x32_bf16 v[36:39], v[140:143], v[164:167], v[36:39]
	s_waitcnt lgkmcnt(0)
	v_mfma_f32_16x16x32_bf16 v[124:127], v[132:135], v[208:211], v[124:127]
	v_mfma_f32_16x16x32_bf16 v[120:123], v[140:143], v[208:211], v[120:123]
	s_barrier
	v_add_u32_e32 v188, 0x1c000, v202
	ds_read_b128 v[212:215], v188
	ds_read_b128 v[236:239], v188 offset:1024
	ds_read_b128 v[240:243], v188 offset:2048
	ds_read_b128 v[244:247], v188 offset:3072
	s_add_u32 s48, s78, 0x4000
	s_addc_u32 s49, s79, 0
	s_mov_b32 m0, s38
	s_nop 0
	global_load_lds_dwordx4 v168, s[48:49]
	s_add_u32 s48, s78, 0x6000
	s_addc_u32 s49, s79, 0
	s_mov_b32 m0, s39
	s_nop 0
	global_load_lds_dwordx4 v168, s[48:49]
	s_waitcnt vmcnt(10)
	s_barrier
; #define PG8_STAGE(bufoff, gbase, hoff, imm) do { _Pragma("unroll") for (int _i = 0; _i < 2; ++_i) { \
;         asm volatile("s_mov_b32 m0, %0\n\ts_nop 0\n\tglobal_load_lds_dwordx4 %1, %2" \
;             :: "s"(lds0 + (unsigned)((bufoff) + _i * 8192)), "v"(voff0), "s"((const char*)(gbase) + (size_t)(hoff) + (size_t)(_i * 8192)) : "memory"); } } while (0)
; #define PG8_LDA(dst, b, h) do { _Pragma("unroll") for (int m = 0; m < 4; ++m) _Pragma("unroll") for (int k = 0; k < 2; ++k) dst[m][k] = *(const LAS bf16x8*)(lds + PG8_SA(b, h) + aoff + m * 2048 + k * 1024); } while (0)
; #define PG8_MMA(ai, bj, At, Bt) do { __builtin_amdgcn_s_setprio(1); _Pragma("unroll") for (int m = 0; m < 4; ++m) _Pragma("unroll") for (int n = 0; n < 2; ++n) _Pragma("unroll") for (int k = 0; k < 2; ++k) \
;         acc[ai][bj][m][n] = __builtin_amdgcn_mfma_f32_16x16x32_bf16(Bt[n][k], At[m][k], acc[ai][bj][m][n], 0, 0, 0); __builtin_amdgcn_s_setprio(0); } while (0)
; #define PG8_WAIT_V(n) asm volatile("s_waitcnt vmcnt(" #n ")" ::: "memory")
; #define PG8_WAIT_L(n) asm volatile("s_waitcnt lgkmcnt(" #n ")" ::: "memory")
; #define PG8_BAR __builtin_amdgcn_s_barrier()
; #define PG8_SCHED __builtin_amdgcn_sched_barrier(0)
; template <class Epi>
; __device__ __forceinline__ void gemm_phase(LAS unsigned char* lds, const Gemm g, const StaticOrder& S, const Epi& E) {
;     ...
;             PG8_BAR; PG8_WAIT_L(0); PG8_MMA(0, 1, At, B1); PG8_BAR;
;             PG8_LDA(At, 1, 1); PG8_STAGE(PG8_SA(1, 0), a2 + KS, 0, 0);
;             PG8_BAR; PG8_WAIT_L(0); PG8_MMA(1, 0, At, B0); PG8_BAR; PG8_SCHED;
;             PG8_STAGE(PG8_SB(1, 1), b2 + KS, hB, 0);
;             PG8_WAIT_V(6); PG8_BAR; PG8_MMA(1, 1, At, B1); PG8_BAR;
	s_waitcnt lgkmcnt(3)
	v_mfma_f32_16x16x32_bf16 v[80:83], v[212:215], v[144:147], v[80:83]
	s_waitcnt lgkmcnt(1)
	v_mfma_f32_16x16x32_bf16 v[32:35], v[240:243], v[144:147], v[32:35]
	v_mfma_f32_16x16x32_bf16 v[76:79], v[212:215], v[152:155], v[76:79]
	v_mfma_f32_16x16x32_bf16 v[28:31], v[240:243], v[152:155], v[28:31]
	v_mfma_f32_16x16x32_bf16 v[72:75], v[212:215], v[160:163], v[72:75]
	v_mfma_f32_16x16x32_bf16 v[24:27], v[240:243], v[160:163], v[24:27]
	v_mfma_f32_16x16x32_bf16 v[116:119], v[212:215], v[204:207], v[116:119]
	v_mfma_f32_16x16x32_bf16 v[112:115], v[240:243], v[204:207], v[112:115]
	v_mfma_f32_16x16x32_bf16 v[80:83], v[236:239], v[148:151], v[80:83]
	s_waitcnt lgkmcnt(0)
	v_mfma_f32_16x16x32_bf16 v[32:35], v[244:247], v[148:151], v[32:35]
	v_mfma_f32_16x16x32_bf16 v[76:79], v[236:239], v[156:159], v[76:79]
	v_mfma_f32_16x16x32_bf16 v[28:31], v[244:247], v[156:159], v[28:31]
	v_mfma_f32_16x16x32_bf16 v[72:75], v[236:239], v[164:167], v[72:75]
	v_mfma_f32_16x16x32_bf16 v[24:27], v[244:247], v[164:167], v[24:27]
	v_mfma_f32_16x16x32_bf16 v[116:119], v[236:239], v[208:211], v[116:119]
	v_mfma_f32_16x16x32_bf16 v[112:115], v[244:247], v[208:211], v[112:115]
	s_barrier
	ds_read_b128 v[144:147], v203 offset:49152
	ds_read_b128 v[148:151], v203 offset:50176
	ds_read_b128 v[152:155], v203 offset:51200
	ds_read_b128 v[156:159], v203 offset:52224
	ds_read_b128 v[160:163], v203 offset:53248
	ds_read_b128 v[164:167], v203 offset:54272
	ds_read_b128 v[204:207], v203 offset:55296
	ds_read_b128 v[208:211], v203 offset:56320
	s_add_u32 s48, s82, 0x4000
	s_addc_u32 s49, s83, 0
	s_mov_b32 m0, s40
	s_nop 0
	global_load_lds_dwordx4 v168, s[48:49]
	s_add_u32 s48, s82, 0x6000
	s_addc_u32 s49, s83, 0
	s_mov_b32 m0, s41
	s_nop 0
	global_load_lds_dwordx4 v168, s[48:49]
	s_barrier
	s_waitcnt lgkmcnt(7)
	v_mfma_f32_16x16x32_bf16 v[68:71], v[128:131], v[144:147], v[68:71]
	v_mfma_f32_16x16x32_bf16 v[20:23], v[136:139], v[144:147], v[20:23]
	s_waitcnt lgkmcnt(5)
	v_mfma_f32_16x16x32_bf16 v[64:67], v[128:131], v[152:155], v[64:67]
	v_mfma_f32_16x16x32_bf16 v[16:19], v[136:139], v[152:155], v[16:19]
	s_waitcnt lgkmcnt(3)
	v_mfma_f32_16x16x32_bf16 v[60:63], v[128:131], v[160:163], v[60:63]
	v_mfma_f32_16x16x32_bf16 v[12:15], v[136:139], v[160:163], v[12:15]
	s_waitcnt lgkmcnt(1)
	v_mfma_f32_16x16x32_bf16 v[108:111], v[128:131], v[204:207], v[108:111]
	v_mfma_f32_16x16x32_bf16 v[104:107], v[136:139], v[204:207], v[104:107]
	v_mfma_f32_16x16x32_bf16 v[68:71], v[132:135], v[148:151], v[68:71]
	v_mfma_f32_16x16x32_bf16 v[20:23], v[140:143], v[148:151], v[20:23]
	v_mfma_f32_16x16x32_bf16 v[64:67], v[132:135], v[156:159], v[64:67]
	v_mfma_f32_16x16x32_bf16 v[16:19], v[140:143], v[156:159], v[16:19]
	v_mfma_f32_16x16x32_bf16 v[60:63], v[132:135], v[164:167], v[60:63]
	v_mfma_f32_16x16x32_bf16 v[12:15], v[140:143], v[164:167], v[12:15]
	s_waitcnt lgkmcnt(0)
	v_mfma_f32_16x16x32_bf16 v[108:111], v[132:135], v[208:211], v[108:111]
	v_mfma_f32_16x16x32_bf16 v[104:107], v[140:143], v[208:211], v[104:107]
	s_barrier
	s_add_u32 s48, s78, 0x84000
	s_addc_u32 s49, s79, 0
	s_mov_b32 m0, s42
	s_nop 0
	global_load_lds_dwordx4 v168, s[48:49]
	s_add_u32 s48, s78, 0x86000
	s_addc_u32 s49, s79, 0
	s_mov_b32 m0, s43
	s_nop 0
	global_load_lds_dwordx4 v168, s[48:49]
	s_waitcnt vmcnt(10)
	s_barrier
	v_mfma_f32_16x16x32_bf16 v[56:59], v[212:215], v[144:147], v[56:59]
	v_mfma_f32_16x16x32_bf16 v[8:11], v[240:243], v[144:147], v[8:11]
	v_mfma_f32_16x16x32_bf16 v[52:55], v[212:215], v[152:155], v[52:55]
	v_mfma_f32_16x16x32_bf16 v[4:7], v[240:243], v[152:155], v[4:7]
	v_mfma_f32_16x16x32_bf16 v[48:51], v[212:215], v[160:163], v[48:51]
	v_mfma_f32_16x16x32_bf16 v[0:3], v[240:243], v[160:163], v[0:3]
	v_mfma_f32_16x16x32_bf16 v[100:103], v[212:215], v[204:207], v[100:103]
	v_mfma_f32_16x16x32_bf16 v[88:91], v[240:243], v[204:207], v[88:91]
	v_mfma_f32_16x16x32_bf16 v[56:59], v[236:239], v[148:151], v[56:59]
	v_mfma_f32_16x16x32_bf16 v[8:11], v[244:247], v[148:151], v[8:11]
	v_mfma_f32_16x16x32_bf16 v[52:55], v[236:239], v[156:159], v[52:55]
	v_mfma_f32_16x16x32_bf16 v[4:7], v[244:247], v[156:159], v[4:7]
	v_mfma_f32_16x16x32_bf16 v[48:51], v[236:239], v[164:167], v[48:51]
	v_mfma_f32_16x16x32_bf16 v[0:3], v[244:247], v[164:167], v[0:3]
	v_mfma_f32_16x16x32_bf16 v[100:103], v[236:239], v[208:211], v[100:103]
	v_mfma_f32_16x16x32_bf16 v[88:91], v[244:247], v[208:211], v[88:91]
	s_add_i32 s0, s0, 2
	s_add_u32 s9, s9, 0x8000
	s_addc_u32 s63, s63, 0
	s_cmp_gt_u32 s0, 29
	s_mov_b64 s[78:79], s[80:81]
	s_barrier
	s_cbranch_scc1 .LBB0_509

; #define PG8_STAGE(bufoff, gbase, hoff, imm) do { _Pragma("unroll") for (int _i = 0; _i < 2; ++_i) { \
;         asm volatile("s_mov_b32 m0, %0\n\ts_nop 0\n\tglobal_load_lds_dwordx4 %1, %2" \
;             :: "s"(lds0 + (unsigned)((bufoff) + _i * 8192)), "v"(voff0), "s"((const char*)(gbase) + (size_t)(hoff) + (size_t)(_i * 8192)) : "memory"); } } while (0)
; #define PG8_LDA(dst, b, h) do { _Pragma("unroll") for (int m = 0; m < 4; ++m) _Pragma("unroll") for (int k = 0; k < 2; ++k) dst[m][k] = *(const LAS bf16x8*)(lds + PG8_SA(b, h) + aoff + m * 2048 + k * 1024); } while (0)
; #define PG8_LDB(dst, b, h) do { _Pragma("unroll") for (int n = 0; n < 2; ++n) _Pragma("unroll") for (int k = 0; k < 2; ++k) dst[n][k] = *(const LAS bf16x8*)(lds + PG8_SB(b, h) + boff + n * 2048 + k * 1024); } while (0)
; #define PG8_MMA(ai, bj, At, Bt) do { __builtin_amdgcn_s_setprio(1); _Pragma("unroll") for (int m = 0; m < 4; ++m) _Pragma("unroll") for (int n = 0; n < 2; ++n) _Pragma("unroll") for (int k = 0; k < 2; ++k) \
;         acc[ai][bj][m][n] = __builtin_amdgcn_mfma_f32_16x16x32_bf16(Bt[n][k], At[m][k], acc[ai][bj][m][n], 0, 0, 0); __builtin_amdgcn_s_setprio(0); } while (0)
; #define PG8_WAIT_L(n) asm volatile("s_waitcnt lgkmcnt(" #n ")" ::: "memory")
; #define PG8_BAR __builtin_amdgcn_s_barrier()
; #define PG8_SCHED __builtin_amdgcn_sched_barrier(0)
; template <class Epi>
; __device__ __forceinline__ void gemm_phase(LAS unsigned char* lds, const Gemm g, const StaticOrder& S, const Epi& E) {
;     ...
;             const char* aT = cA + (size_t)t * KS;
;             const char* a2 = last ? nA : aT + 2 * KS; const char* b2 = last ? nB : cB + (size_t)(t + 2) * KS;
;             PG8_LDB(B0, 0, 0); PG8_SCHED; PG8_LDA(At, 0, 0); PG8_STAGE(PG8_SA(1, 1), aT + KS, hA, 0);
;             PG8_WAIT_L(8); PG8_BAR; PG8_WAIT_L(0); PG8_MMA(0, 0, At, B0); PG8_BAR; PG8_SCHED;
;             PG8_LDB(B1, 0, 1); PG8_STAGE(PG8_SB(0, 0), b2, 0, 0);
;             PG8_BAR; PG8_WAIT_L(0); PG8_MMA(0, 1, At, B1); PG8_BAR;
;             PG8_LDA(At, 0, 1); PG8_STAGE(PG8_SA(0, 0), a2, 0, 0);
;             PG8_BAR; PG8_WAIT_L(0); PG8_MMA(1, 0, At, B0); PG8_BAR; PG8_SCHED;
.LBB0_610:
	s_add_u32 s62, s60, 0x8000
	v_add_u32_e32 v132, 0x10000, v236
	s_addc_u32 s63, s61, 0
	ds_read_b128 v[120:123], v132
	ds_read_b128 v[124:127], v132 offset:1024
	ds_read_b128 v[128:131], v132 offset:2048
	ds_read_b128 v[132:135], v132 offset:3072
	s_add_u32 s48, s60, 0x84000
	s_addc_u32 s49, s61, 0
	s_add_u32 s64, s60, 0x86000
	s_addc_u32 s65, s61, 0
	s_cmp_eq_u32 s71, 28
	s_cselect_b32 s61, s0, s63
	s_cselect_b32 s60, s1, s62
	ds_read_b128 v[136:139], v237
	ds_read_b128 v[140:143], v237 offset:1024
	ds_read_b128 v[152:155], v237 offset:2048
	ds_read_b128 v[156:159], v237 offset:3072
	ds_read_b128 v[160:163], v237 offset:4096
	ds_read_b128 v[164:167], v237 offset:5120
	ds_read_b128 v[168:171], v237 offset:6144
	ds_read_b128 v[172:175], v237 offset:7168
	s_mov_b32 m0, s67
	s_nop 0
	global_load_lds_dwordx4 v188, s[48:49]
	s_mov_b32 m0, s68
	s_nop 0
	global_load_lds_dwordx4 v188, s[64:65]
	s_waitcnt lgkmcnt(8)
	s_waitcnt vmcnt(10)
	s_barrier
	s_waitcnt lgkmcnt(7)
	v_mfma_f32_16x16x32_bf16 v[148:151], v[120:123], v[136:139], v[148:151]
	v_mfma_f32_16x16x32_bf16 v[144:147], v[128:131], v[136:139], v[144:147]
	s_waitcnt lgkmcnt(5)
	v_mfma_f32_16x16x32_bf16 v[108:111], v[120:123], v[152:155], v[108:111]
	v_mfma_f32_16x16x32_bf16 v[104:107], v[128:131], v[152:155], v[104:107]
	s_waitcnt lgkmcnt(3)
	v_mfma_f32_16x16x32_bf16 v[92:95], v[120:123], v[160:163], v[92:95]
	v_mfma_f32_16x16x32_bf16 v[88:91], v[128:131], v[160:163], v[88:91]
	s_waitcnt lgkmcnt(1)
	v_mfma_f32_16x16x32_bf16 v[76:79], v[120:123], v[168:171], v[76:79]
	v_mfma_f32_16x16x32_bf16 v[72:75], v[128:131], v[168:171], v[72:75]
	v_mfma_f32_16x16x32_bf16 v[148:151], v[124:127], v[140:143], v[148:151]
	v_mfma_f32_16x16x32_bf16 v[144:147], v[132:135], v[140:143], v[144:147]
	v_mfma_f32_16x16x32_bf16 v[108:111], v[124:127], v[156:159], v[108:111]
	v_mfma_f32_16x16x32_bf16 v[104:107], v[132:135], v[156:159], v[104:107]
	v_mfma_f32_16x16x32_bf16 v[92:95], v[124:127], v[164:167], v[92:95]
	v_mfma_f32_16x16x32_bf16 v[88:91], v[132:135], v[164:167], v[88:91]
	s_waitcnt lgkmcnt(0)
	v_mfma_f32_16x16x32_bf16 v[76:79], v[124:127], v[172:175], v[76:79]
	v_mfma_f32_16x16x32_bf16 v[72:75], v[132:135], v[172:175], v[72:75]
	s_barrier
	v_add_u32_e32 v200, 0x14000, v236
	ds_read_b128 v[176:179], v200
	ds_read_b128 v[180:183], v200 offset:1024
	ds_read_b128 v[184:187], v200 offset:2048
	ds_read_b128 v[200:203], v200 offset:3072
	s_cselect_b32 s64, s55, s69
	s_cselect_b32 s65, s53, s70
	s_mov_b32 m0, s24
	s_nop 0
	global_load_lds_dwordx4 v188, s[64:65]
	s_add_u32 s48, s64, 0x2000
	s_addc_u32 s49, s65, 0
	s_mov_b32 m0, s25
	s_nop 0
	global_load_lds_dwordx4 v188, s[48:49]
	s_waitcnt vmcnt(10)
	s_barrier
	s_waitcnt lgkmcnt(3)
	v_mfma_f32_16x16x32_bf16 v[116:119], v[176:179], v[136:139], v[116:119]
	s_waitcnt lgkmcnt(1)
	v_mfma_f32_16x16x32_bf16 v[112:115], v[184:187], v[136:139], v[112:115]
	v_mfma_f32_16x16x32_bf16 v[100:103], v[176:179], v[152:155], v[100:103]
	v_mfma_f32_16x16x32_bf16 v[96:99], v[184:187], v[152:155], v[96:99]
	v_mfma_f32_16x16x32_bf16 v[84:87], v[176:179], v[160:163], v[84:87]
	v_mfma_f32_16x16x32_bf16 v[80:83], v[184:187], v[160:163], v[80:83]
	v_mfma_f32_16x16x32_bf16 v[68:71], v[176:179], v[168:171], v[68:71]
	v_mfma_f32_16x16x32_bf16 v[64:67], v[184:187], v[168:171], v[64:67]
	v_mfma_f32_16x16x32_bf16 v[116:119], v[180:183], v[140:143], v[116:119]
	s_waitcnt lgkmcnt(0)
	v_mfma_f32_16x16x32_bf16 v[112:115], v[200:203], v[140:143], v[112:115]
	v_mfma_f32_16x16x32_bf16 v[100:103], v[180:183], v[156:159], v[100:103]
	v_mfma_f32_16x16x32_bf16 v[96:99], v[200:203], v[156:159], v[96:99]
	v_mfma_f32_16x16x32_bf16 v[84:87], v[180:183], v[164:167], v[84:87]
	v_mfma_f32_16x16x32_bf16 v[80:83], v[200:203], v[164:167], v[80:83]
	v_mfma_f32_16x16x32_bf16 v[68:71], v[180:183], v[172:175], v[68:71]
	v_mfma_f32_16x16x32_bf16 v[64:67], v[200:203], v[172:175], v[64:67]
	s_barrier
	ds_read_b128 v[136:139], v237 offset:16384
	ds_read_b128 v[140:143], v237 offset:17408
	ds_read_b128 v[152:155], v237 offset:18432
	ds_read_b128 v[156:159], v237 offset:19456
	ds_read_b128 v[160:163], v237 offset:20480
	ds_read_b128 v[164:167], v237 offset:21504
	ds_read_b128 v[168:171], v237 offset:22528
	ds_read_b128 v[172:175], v237 offset:23552
	s_mov_b32 m0, s22
	s_nop 0
	global_load_lds_dwordx4 v188, s[60:61]
	s_add_u32 s48, s60, 0x2000
	s_addc_u32 s49, s61, 0
	s_mov_b32 m0, s26
	s_nop 0
	global_load_lds_dwordx4 v188, s[48:49]
	s_barrier
	s_waitcnt lgkmcnt(7)
	v_mfma_f32_16x16x32_bf16 v[60:63], v[120:123], v[136:139], v[60:63]
	v_mfma_f32_16x16x32_bf16 v[56:59], v[128:131], v[136:139], v[56:59]
	s_waitcnt lgkmcnt(5)
	v_mfma_f32_16x16x32_bf16 v[44:47], v[120:123], v[152:155], v[44:47]
	v_mfma_f32_16x16x32_bf16 v[40:43], v[128:131], v[152:155], v[40:43]
	s_waitcnt lgkmcnt(3)
	v_mfma_f32_16x16x32_bf16 v[28:31], v[120:123], v[160:163], v[28:31]
	v_mfma_f32_16x16x32_bf16 v[24:27], v[128:131], v[160:163], v[24:27]
	s_waitcnt lgkmcnt(1)
	v_mfma_f32_16x16x32_bf16 v[12:15], v[120:123], v[168:171], v[12:15]
	v_mfma_f32_16x16x32_bf16 v[8:11], v[128:131], v[168:171], v[8:11]
	v_mfma_f32_16x16x32_bf16 v[60:63], v[124:127], v[140:143], v[60:63]
	v_mfma_f32_16x16x32_bf16 v[56:59], v[132:135], v[140:143], v[56:59]
	v_mfma_f32_16x16x32_bf16 v[44:47], v[124:127], v[156:159], v[44:47]
	v_mfma_f32_16x16x32_bf16 v[40:43], v[132:135], v[156:159], v[40:43]
	v_mfma_f32_16x16x32_bf16 v[28:31], v[124:127], v[164:167], v[28:31]
	v_mfma_f32_16x16x32_bf16 v[24:27], v[132:135], v[164:167], v[24:27]
	s_waitcnt lgkmcnt(0)
	v_mfma_f32_16x16x32_bf16 v[12:15], v[124:127], v[172:175], v[12:15]
	v_mfma_f32_16x16x32_bf16 v[8:11], v[132:135], v[172:175], v[8:11]
	s_barrier
; #define PG8_STAGE(bufoff, gbase, hoff, imm) do { _Pragma("unroll") for (int _i = 0; _i < 2; ++_i) { \
;         asm volatile("s_mov_b32 m0, %0\n\ts_nop 0\n\tglobal_load_lds_dwordx4 %1, %2" \
;             :: "s"(lds0 + (unsigned)((bufoff) + _i * 8192)), "v"(voff0), "s"((const char*)(gbase) + (size_t)(hoff) + (size_t)(_i * 8192)) : "memory"); } } while (0)
; #define PG8_LDA(dst, b, h) do { _Pragma("unroll") for (int m = 0; m < 4; ++m) _Pragma("unroll") for (int k = 0; k < 2; ++k) dst[m][k] = *(const LAS bf16x8*)(lds + PG8_SA(b, h) + aoff + m * 2048 + k * 1024); } while (0)
; #define PG8_LDB(dst, b, h) do { _Pragma("unroll") for (int n = 0; n < 2; ++n) _Pragma("unroll") for (int k = 0; k < 2; ++k) dst[n][k] = *(const LAS bf16x8*)(lds + PG8_SB(b, h) + boff + n * 2048 + k * 1024); } while (0)
; #define PG8_MMA(ai, bj, At, Bt) do { __builtin_amdgcn_s_setprio(1); _Pragma("unroll") for (int m = 0; m < 4; ++m) _Pragma("unroll") for (int n = 0; n < 2; ++n) _Pragma("unroll") for (int k = 0; k < 2; ++k) \
;         acc[ai][bj][m][n] = __builtin_amdgcn_mfma_f32_16x16x32_bf16(Bt[n][k], At[m][k], acc[ai][bj][m][n], 0, 0, 0); __builtin_amdgcn_s_setprio(0); } while (0)
; #define PG8_WAIT_V(n) asm volatile("s_waitcnt vmcnt(" #n ")" ::: "memory")
; #define PG8_WAIT_L(n) asm volatile("s_waitcnt lgkmcnt(" #n ")" ::: "memory")
; #define PG8_BAR __builtin_amdgcn_s_barrier()
; #define PG8_SCHED __builtin_amdgcn_sched_barrier(0)
; template <class Epi>
; __device__ __forceinline__ void gemm_phase(LAS unsigned char* lds, const Gemm g, const StaticOrder& S, const Epi& E) {
;     ...
;             PG8_STAGE(PG8_SB(0, 1), b2, hB, 0);
;             PG8_WAIT_V(6); PG8_BAR; PG8_MMA(1, 1, At, B1); PG8_BAR;
;             PG8_LDB(B0, 1, 0); PG8_SCHED; PG8_LDA(At, 1, 0); PG8_STAGE(PG8_SA(0, 1), a2, hA, 0);
;             PG8_WAIT_L(8); PG8_BAR; PG8_WAIT_L(0); PG8_MMA(0, 0, At, B0); PG8_BAR; PG8_SCHED;
;             PG8_LDB(B1, 1, 1); PG8_STAGE(PG8_SB(1, 0), b2 + KS, 0, 0);
;             PG8_BAR; PG8_WAIT_L(0); PG8_MMA(0, 1, At, B1); PG8_BAR;
;             PG8_LDA(At, 1, 1); PG8_STAGE(PG8_SA(1, 0), a2 + KS, 0, 0);
	s_add_u32 s48, s64, 0x80000
	s_addc_u32 s49, s65, 0
	s_mov_b32 m0, s27
	s_nop 0
	global_load_lds_dwordx4 v188, s[48:49]
	s_add_u32 s48, s64, 0x82000
	s_addc_u32 s49, s65, 0
	s_mov_b32 m0, s28
	s_nop 0
	global_load_lds_dwordx4 v188, s[48:49]
	s_waitcnt vmcnt(10)
	s_barrier
	v_mfma_f32_16x16x32_bf16 v[52:55], v[176:179], v[136:139], v[52:55]
	v_mfma_f32_16x16x32_bf16 v[48:51], v[184:187], v[136:139], v[48:51]
	v_mfma_f32_16x16x32_bf16 v[36:39], v[176:179], v[152:155], v[36:39]
	v_mfma_f32_16x16x32_bf16 v[32:35], v[184:187], v[152:155], v[32:35]
	v_mfma_f32_16x16x32_bf16 v[20:23], v[176:179], v[160:163], v[20:23]
	v_mfma_f32_16x16x32_bf16 v[16:19], v[184:187], v[160:163], v[16:19]
	v_mfma_f32_16x16x32_bf16 v[4:7], v[176:179], v[168:171], v[4:7]
	v_mfma_f32_16x16x32_bf16 v[0:3], v[184:187], v[168:171], v[0:3]
	v_mfma_f32_16x16x32_bf16 v[52:55], v[180:183], v[140:143], v[52:55]
	v_mfma_f32_16x16x32_bf16 v[48:51], v[200:203], v[140:143], v[48:51]
	v_mfma_f32_16x16x32_bf16 v[36:39], v[180:183], v[156:159], v[36:39]
	v_mfma_f32_16x16x32_bf16 v[32:35], v[200:203], v[156:159], v[32:35]
	v_mfma_f32_16x16x32_bf16 v[20:23], v[180:183], v[164:167], v[20:23]
	v_mfma_f32_16x16x32_bf16 v[16:19], v[200:203], v[164:167], v[16:19]
	v_mfma_f32_16x16x32_bf16 v[4:7], v[180:183], v[172:175], v[4:7]
	v_mfma_f32_16x16x32_bf16 v[0:3], v[200:203], v[172:175], v[0:3]
	v_add_u32_e32 v132, 0x18000, v236
	s_barrier
	ds_read_b128 v[120:123], v132
	ds_read_b128 v[124:127], v132 offset:1024
	ds_read_b128 v[128:131], v132 offset:2048
	ds_read_b128 v[132:135], v132 offset:3072
	ds_read_b128 v[136:139], v237 offset:32768
	ds_read_b128 v[140:143], v237 offset:33792
	ds_read_b128 v[152:155], v237 offset:34816
	ds_read_b128 v[156:159], v237 offset:35840
	ds_read_b128 v[160:163], v237 offset:36864
	ds_read_b128 v[164:167], v237 offset:37888
	ds_read_b128 v[168:171], v237 offset:38912
	ds_read_b128 v[172:175], v237 offset:39936
	s_add_u32 s48, s60, 0x80000
	s_addc_u32 s49, s61, 0
	s_mov_b32 m0, s29
	s_nop 0
	global_load_lds_dwordx4 v188, s[48:49]
	s_add_u32 s48, s60, 0x82000
	s_addc_u32 s49, s61, 0
	s_mov_b32 m0, s30
	s_nop 0
	global_load_lds_dwordx4 v188, s[48:49]
	s_waitcnt lgkmcnt(8)
	s_waitcnt vmcnt(10)
	s_barrier
	s_waitcnt lgkmcnt(7)
	v_mfma_f32_16x16x32_bf16 v[148:151], v[120:123], v[136:139], v[148:151]
	v_mfma_f32_16x16x32_bf16 v[144:147], v[128:131], v[136:139], v[144:147]
	s_waitcnt lgkmcnt(5)
	v_mfma_f32_16x16x32_bf16 v[108:111], v[120:123], v[152:155], v[108:111]
	v_mfma_f32_16x16x32_bf16 v[104:107], v[128:131], v[152:155], v[104:107]
	s_waitcnt lgkmcnt(3)
	v_mfma_f32_16x16x32_bf16 v[92:95], v[120:123], v[160:163], v[92:95]
	v_mfma_f32_16x16x32_bf16 v[88:91], v[128:131], v[160:163], v[88:91]
	s_waitcnt lgkmcnt(1)
	v_mfma_f32_16x16x32_bf16 v[76:79], v[120:123], v[168:171], v[76:79]
	v_mfma_f32_16x16x32_bf16 v[72:75], v[128:131], v[168:171], v[72:75]
	v_mfma_f32_16x16x32_bf16 v[148:151], v[124:127], v[140:143], v[148:151]
	v_mfma_f32_16x16x32_bf16 v[144:147], v[132:135], v[140:143], v[144:147]
	v_mfma_f32_16x16x32_bf16 v[108:111], v[124:127], v[156:159], v[108:111]
	v_mfma_f32_16x16x32_bf16 v[104:107], v[132:135], v[156:159], v[104:107]
	v_mfma_f32_16x16x32_bf16 v[92:95], v[124:127], v[164:167], v[92:95]
	v_mfma_f32_16x16x32_bf16 v[88:91], v[132:135], v[164:167], v[88:91]
	s_waitcnt lgkmcnt(0)
	v_mfma_f32_16x16x32_bf16 v[76:79], v[124:127], v[172:175], v[76:79]
	v_mfma_f32_16x16x32_bf16 v[72:75], v[132:135], v[172:175], v[72:75]
	s_barrier
	v_add_u32_e32 v200, 0x1c000, v236
	ds_read_b128 v[176:179], v200
	ds_read_b128 v[180:183], v200 offset:1024
	ds_read_b128 v[184:187], v200 offset:2048
	ds_read_b128 v[200:203], v200 offset:3072
	s_add_u32 s48, s64, 0x4000
	s_addc_u32 s49, s65, 0
	s_mov_b32 m0, s39
	s_nop 0
	global_load_lds_dwordx4 v188, s[48:49]
	s_add_u32 s48, s64, 0x6000
	s_addc_u32 s49, s65, 0
	s_mov_b32 m0, s40
	s_nop 0
	global_load_lds_dwordx4 v188, s[48:49]
	s_waitcnt vmcnt(10)
	s_barrier
	s_waitcnt lgkmcnt(3)
	v_mfma_f32_16x16x32_bf16 v[116:119], v[176:179], v[136:139], v[116:119]
	s_waitcnt lgkmcnt(1)
	v_mfma_f32_16x16x32_bf16 v[112:115], v[184:187], v[136:139], v[112:115]
	v_mfma_f32_16x16x32_bf16 v[100:103], v[176:179], v[152:155], v[100:103]
	v_mfma_f32_16x16x32_bf16 v[96:99], v[184:187], v[152:155], v[96:99]
	v_mfma_f32_16x16x32_bf16 v[84:87], v[176:179], v[160:163], v[84:87]
	v_mfma_f32_16x16x32_bf16 v[80:83], v[184:187], v[160:163], v[80:83]
	v_mfma_f32_16x16x32_bf16 v[68:71], v[176:179], v[168:171], v[68:71]
	v_mfma_f32_16x16x32_bf16 v[64:67], v[184:187], v[168:171], v[64:67]
	v_mfma_f32_16x16x32_bf16 v[116:119], v[180:183], v[140:143], v[116:119]
	s_waitcnt lgkmcnt(0)
	v_mfma_f32_16x16x32_bf16 v[112:115], v[200:203], v[140:143], v[112:115]
	v_mfma_f32_16x16x32_bf16 v[100:103], v[180:183], v[156:159], v[100:103]
	v_mfma_f32_16x16x32_bf16 v[96:99], v[200:203], v[156:159], v[96:99]
	v_mfma_f32_16x16x32_bf16 v[84:87], v[180:183], v[164:167], v[84:87]
	v_mfma_f32_16x16x32_bf16 v[80:83], v[200:203], v[164:167], v[80:83]
	v_mfma_f32_16x16x32_bf16 v[68:71], v[180:183], v[172:175], v[68:71]
	v_mfma_f32_16x16x32_bf16 v[64:67], v[200:203], v[172:175], v[64:67]
	s_barrier
	ds_read_b128 v[136:139], v237 offset:49152
	ds_read_b128 v[140:143], v237 offset:50176
	ds_read_b128 v[152:155], v237 offset:51200
	ds_read_b128 v[156:159], v237 offset:52224
	ds_read_b128 v[160:163], v237 offset:53248
	ds_read_b128 v[164:167], v237 offset:54272
	ds_read_b128 v[168:171], v237 offset:55296
	ds_read_b128 v[172:175], v237 offset:56320
	s_add_u32 s48, s60, 0x4000
	s_addc_u32 s49, s61, 0
	s_mov_b32 m0, s41
	s_nop 0
	global_load_lds_dwordx4 v188, s[48:49]
	s_add_u32 s48, s60, 0x6000
	s_addc_u32 s49, s61, 0
	s_mov_b32 m0, s42
	s_nop 0
	global_load_lds_dwordx4 v188, s[48:49]
	s_barrier
; template <class Epi>
; __device__ __forceinline__ void gemm_phase(LAS unsigned char* lds, const Gemm g, const StaticOrder& S, const Epi& E) {
;     ...
;             PG8_BAR; PG8_WAIT_L(0); PG8_MMA(1, 0, At, B0); PG8_BAR; PG8_SCHED;
;             PG8_STAGE(PG8_SB(1, 1), b2 + KS, hB, 0);
;             PG8_WAIT_V(6); PG8_BAR; PG8_MMA(1, 1, At, B1); PG8_BAR;
;     __device__ __forceinline__ void operator()(f32x4 (&acc)[2][2][4][2], const Unit& u, int wr, int wc, int fr, int fq, LAS unsigned char*) const {
;         const int b = u.pm >> 6;
;         const int col0 = u.pn * BM + wc * 32 + 8 * fq;
;         const size_t off0 = (size_t)(u.pm * BM + wr * 64 + fr) * D + col0;
;         f32x4 sc[2][2];
; #pragma unroll
;         for (int bj = 0; bj < 2; ++bj)
; #pragma unroll
;             for (int n = 0; n < 2; ++n) { f32x4 gt = *(const f32x4*)(gate + (size_t)b * MODW + col0 + bj * HALF + n * 4); sc[bj][n] = gt + 1.0f;
;                 if (cs) sc[bj][n] *= *(const f32x4*)(cs + col0 + bj * HALF + n * 4); }
;         if (IN_F32) {
; #pragma unroll
;             for (int ai = 0; ai < 2; ++ai) {
;                 f32x4 r[4][2][2];
; #pragma unroll
;                 for (int m = 0; m < 4; ++m)
; #pragma unroll
;                     for (int bj = 0; bj < 2; ++bj)
; #pragma unroll
;                         for (int n = 0; n < 2; ++n) r[m][bj][n] = *(const f32x4*)((const float*)in + off0 + (size_t)(ai * HALF + m * 16) * D + bj * HALF + n * 4);
; #pragma unroll
;                 for (int m = 0; m < 4; ++m)
; #pragma unroll
;                     for (int bj = 0; bj < 2; ++bj) { const f32x4 r0 = r[m][bj][0] + sc[bj][0] * acc[ai][bj][m][0], r1 = r[m][bj][1] + sc[bj][1] * acc[ai][bj][m][1];
;                         u32x4 w; w.x = cvt_pk_bf16(r0[0], r0[1]); w.y = cvt_pk_bf16(r0[2], r0[3]); w.z = cvt_pk_bf16(r1[0], r1[1]); w.w = cvt_pk_bf16(r1[2], r1[3]);
;                         *(u32x4*)(out + off0 + (size_t)(ai * HALF + m * 16) * D + bj * HALF) = w; }
;                 asm volatile("" ::: "memory");
;             }
;         } else {
;             u32x4 xb[2][4][2];
; #pragma unroll
;             for (int ai = 0; ai < 2; ++ai)
; #pragma unroll
;                 for (int m = 0; m < 4; ++m)
; #pragma unroll
;                     for (int bj = 0; bj < 2; ++bj) xb[ai][m][bj] = *(const u32x4*)((const bf16_t*)in + off0 + (size_t)(ai * HALF + m * 16) * D + bj * HALF);
	s_waitcnt lgkmcnt(7)
	v_mfma_f32_16x16x32_bf16 v[60:63], v[120:123], v[136:139], v[60:63]
	v_mfma_f32_16x16x32_bf16 v[56:59], v[128:131], v[136:139], v[56:59]
	s_waitcnt lgkmcnt(5)
	v_mfma_f32_16x16x32_bf16 v[44:47], v[120:123], v[152:155], v[44:47]
	v_mfma_f32_16x16x32_bf16 v[40:43], v[128:131], v[152:155], v[40:43]
	s_waitcnt lgkmcnt(3)
	v_mfma_f32_16x16x32_bf16 v[28:31], v[120:123], v[160:163], v[28:31]
	v_mfma_f32_16x16x32_bf16 v[24:27], v[128:131], v[160:163], v[24:27]
	s_waitcnt lgkmcnt(1)
	v_mfma_f32_16x16x32_bf16 v[12:15], v[120:123], v[168:171], v[12:15]
	v_mfma_f32_16x16x32_bf16 v[8:11], v[128:131], v[168:171], v[8:11]
	v_mfma_f32_16x16x32_bf16 v[60:63], v[124:127], v[140:143], v[60:63]
	v_mfma_f32_16x16x32_bf16 v[56:59], v[132:135], v[140:143], v[56:59]
	v_mfma_f32_16x16x32_bf16 v[44:47], v[124:127], v[156:159], v[44:47]
	v_mfma_f32_16x16x32_bf16 v[40:43], v[132:135], v[156:159], v[40:43]
	v_mfma_f32_16x16x32_bf16 v[28:31], v[124:127], v[164:167], v[28:31]
	v_mfma_f32_16x16x32_bf16 v[24:27], v[132:135], v[164:167], v[24:27]
	s_waitcnt lgkmcnt(0)
	v_mfma_f32_16x16x32_bf16 v[12:15], v[124:127], v[172:175], v[12:15]
	v_mfma_f32_16x16x32_bf16 v[8:11], v[132:135], v[172:175], v[8:11]
	s_barrier
	s_add_u32 s48, s64, 0x84000
	s_addc_u32 s49, s65, 0
	s_mov_b32 m0, s43
	s_nop 0
	global_load_lds_dwordx4 v188, s[48:49]
	s_add_u32 s48, s64, 0x86000
	s_addc_u32 s49, s65, 0
	s_mov_b32 m0, s66
	s_nop 0
	global_load_lds_dwordx4 v188, s[48:49]
	s_waitcnt vmcnt(10)
	s_barrier
	v_mfma_f32_16x16x32_bf16 v[52:55], v[176:179], v[136:139], v[52:55]
	v_mfma_f32_16x16x32_bf16 v[48:51], v[184:187], v[136:139], v[48:51]
	v_mfma_f32_16x16x32_bf16 v[36:39], v[176:179], v[152:155], v[36:39]
	v_mfma_f32_16x16x32_bf16 v[32:35], v[184:187], v[152:155], v[32:35]
	v_mfma_f32_16x16x32_bf16 v[20:23], v[176:179], v[160:163], v[20:23]
	v_mfma_f32_16x16x32_bf16 v[16:19], v[184:187], v[160:163], v[16:19]
	v_mfma_f32_16x16x32_bf16 v[4:7], v[176:179], v[168:171], v[4:7]
	v_mfma_f32_16x16x32_bf16 v[0:3], v[184:187], v[168:171], v[0:3]
	v_mfma_f32_16x16x32_bf16 v[52:55], v[180:183], v[140:143], v[52:55]
	v_mfma_f32_16x16x32_bf16 v[48:51], v[200:203], v[140:143], v[48:51]
	v_mfma_f32_16x16x32_bf16 v[36:39], v[180:183], v[156:159], v[36:39]
	v_mfma_f32_16x16x32_bf16 v[32:35], v[200:203], v[156:159], v[32:35]
	v_mfma_f32_16x16x32_bf16 v[20:23], v[180:183], v[164:167], v[20:23]
	v_mfma_f32_16x16x32_bf16 v[16:19], v[200:203], v[164:167], v[16:19]
	v_mfma_f32_16x16x32_bf16 v[4:7], v[180:183], v[172:175], v[4:7]
	v_mfma_f32_16x16x32_bf16 v[0:3], v[200:203], v[172:175], v[0:3]
	s_add_i32 s71, s71, 2
	s_add_u32 s69, s69, 0x8000
	s_addc_u32 s70, s70, 0
	s_cmp_gt_u32 s71, 29
	s_mov_b64 s[60:61], s[62:63]
	s_barrier
	s_cbranch_scc0 .LBB0_610
	s_ashr_i32 s0, s50, 6
	s_mul_hi_i32 s1, s0, 0xc000
	s_mul_i32 s0, s0, 0xc000
	v_lshl_or_b32 v128, s51, 8, v234
	s_add_u32 s0, s37, s0
	v_ashrrev_i32_e32 v129, 31, v128
	s_addc_u32 s1, s38, s1
	v_lshl_add_u64 v[130:131], v[128:129], 2, s[0:1]
	global_load_dwordx4 v[120:123], v[130:131], off offset:16
	global_load_dwordx4 v[124:127], v[130:131], off
	s_mov_b32 s51, s52
	s_mov_b64 s[62:63], s[58:59]
	s_mov_b64 s[60:61], s[56:57]
	s_waitcnt vmcnt(1)
	v_pk_add_f32 v[210:211], v[122:123], 1.0 op_sel_hi:[1,0]
	s_waitcnt vmcnt(0)
	v_pk_add_f32 v[214:215], v[126:127], 1.0 op_sel_hi:[1,0]
	v_pk_add_f32 v[212:213], v[124:125], 1.0 op_sel_hi:[1,0]
	v_pk_add_f32 v[208:209], v[120:121], 1.0 op_sel_hi:[1,0]
	global_load_dwordx4 v[120:123], v[130:131], off offset:528
	global_load_dwordx4 v[124:127], v[130:131], off offset:512
	s_waitcnt vmcnt(1)
	v_pk_add_f32 v[200:201], v[120:121], 1.0 op_sel_hi:[1,0]
	v_lshl_add_u32 v120, s50, 8, v233
	v_ashrrev_i32_e32 v121, 31, v120
	v_lshlrev_b64 v[120:121], 11, v[120:121]
	v_lshl_add_u64 v[120:121], v[120:121], 0, v[128:129]
	v_lshlrev_b64 v[216:217], 1, v[120:121]
	v_lshl_add_u64 v[120:121], s[8:9], 0, v[216:217]
	global_load_dwordx4 v[238:241], v[120:121], off
	global_load_dwordx4 v[184:187], v[120:121], off offset:256
	v_pk_add_f32 v[202:203], v[122:123], 1.0 op_sel_hi:[1,0]
	v_add_co_u32_e32 v122, vcc, s45, v120
	s_waitcnt vmcnt(2)
	v_pk_add_f32 v[206:207], v[126:127], 1.0 op_sel_hi:[1,0]
	v_addc_co_u32_e32 v123, vcc, 0, v121, vcc
	global_load_dwordx4 v[180:183], v[122:123], off
	global_load_dwordx4 v[176:179], v[122:123], off offset:256
	v_add_co_u32_e32 v122, vcc, s36, v120
	v_pk_add_f32 v[204:205], v[124:125], 1.0 op_sel_hi:[1,0]
	s_nop 0
	v_addc_co_u32_e32 v123, vcc, 0, v121, vcc
	global_load_dwordx4 v[172:175], v[122:123], off
	global_load_dwordx4 v[168:171], v[122:123], off offset:256
	v_add_co_u32_e32 v122, vcc, s23, v120
	s_mov_b32 s50, s54
	s_nop 0
	v_addc_co_u32_e32 v123, vcc, 0, v121, vcc
	global_load_dwordx4 v[164:167], v[122:123], off
	global_load_dwordx4 v[160:163], v[122:123], off offset:256
	v_add_co_u32_e32 v122, vcc, s93, v120
	s_waitcnt vmcnt(7)
; __device__ __forceinline__ unsigned cvt_pk_bf16(float lo, float hi) { unsigned r; asm volatile("v_cvt_pk_bf16_f32 %0, %1, %2" : "=v"(r) : "v"(lo), "v"(hi)); return r; }
;     __device__ __forceinline__ void operator()(f32x4 (&acc)[2][2][4][2], const Unit& u, int wr, int wc, int fr, int fq, LAS unsigned char*) const {
;     ...
; #pragma unroll
;             for (int ai = 0; ai < 2; ++ai)
; #pragma unroll
;                 for (int m = 0; m < 4; ++m)
; #pragma unroll
;                     for (int bj = 0; bj < 2; ++bj) { const u32x4 x = xb[ai][m][bj];
;                         f32x4 r0 = (f32x4){__uint_as_float(x.x << 16), __uint_as_float(x.x & 0xffff0000u), __uint_as_float(x.y << 16), __uint_as_float(x.y & 0xffff0000u)};
;                         f32x4 r1 = (f32x4){__uint_as_float(x.z << 16), __uint_as_float(x.z & 0xffff0000u), __uint_as_float(x.w << 16), __uint_as_float(x.w & 0xffff0000u)};
;                         r0 += sc[bj][0] * acc[ai][bj][m][0]; r1 += sc[bj][1] * acc[ai][bj][m][1];
;                         u32x4 w; w.x = cvt_pk_bf16(r0[0], r0[1]); w.y = cvt_pk_bf16(r0[2], r0[3]); w.z = cvt_pk_bf16(r1[0], r1[1]); w.w = cvt_pk_bf16(r1[2], r1[3]);
;                         *(u32x4*)(out + off0 + (size_t)(ai * HALF + m * 16) * D + bj * HALF) = w; }
	v_lshlrev_b32_e32 v230, 16, v238
	v_addc_co_u32_e32 v123, vcc, 0, v121, vcc
	global_load_dwordx4 v[156:159], v[122:123], off
	global_load_dwordx4 v[152:155], v[122:123], off offset:256
	v_add_co_u32_e32 v122, vcc, s33, v120
	v_and_b32_e32 v231, 0xffff0000, v238
	s_nop 0
	v_addc_co_u32_e32 v123, vcc, 0, v121, vcc
	global_load_dwordx4 v[140:143], v[122:123], off
	global_load_dwordx4 v[136:139], v[122:123], off offset:256
	v_add_co_u32_e32 v122, vcc, s18, v120
	v_lshlrev_b32_e32 v242, 16, v240
	s_nop 0
	v_addc_co_u32_e32 v123, vcc, 0, v121, vcc
	global_load_dwordx4 v[132:135], v[122:123], off
	global_load_dwordx4 v[128:131], v[122:123], off offset:256
	v_add_co_u32_e32 v120, vcc, s19, v120
	v_and_b32_e32 v243, 0xffff0000, v240
	s_nop 0
	v_addc_co_u32_e32 v121, vcc, 0, v121, vcc
	global_load_dwordx4 v[124:127], v[120:121], off
	s_nop 0
	global_load_dwordx4 v[120:123], v[120:121], off offset:256
	v_lshlrev_b32_e32 v238, 16, v239
	v_and_b32_e32 v239, 0xffff0000, v239
	v_lshlrev_b32_e32 v240, 16, v241
	v_and_b32_e32 v241, 0xffff0000, v241
	v_pk_fma_f32 v[148:149], v[148:149], v[212:213], v[230:231]
	v_pk_fma_f32 v[144:145], v[144:145], v[208:209], v[242:243]
	v_pk_fma_f32 v[150:151], v[150:151], v[214:215], v[238:239]
	v_pk_fma_f32 v[230:231], v[146:147], v[210:211], v[240:241]
	v_cvt_pk_bf16_f32 v146, v148, v149
	v_cvt_pk_bf16_f32 v147, v150, v151
	v_cvt_pk_bf16_f32 v148, v144, v145
	v_lshl_add_u64 v[144:145], s[10:11], 0, v[216:217]
	v_cvt_pk_bf16_f32 v149, v230, v231
	global_store_dwordx4 v[144:145], v[146:149], off
	s_waitcnt vmcnt(15)
	v_lshlrev_b32_e32 v150, 16, v186
	v_and_b32_e32 v151, 0xffff0000, v186
	v_lshlrev_b32_e32 v146, 16, v184
	v_and_b32_e32 v147, 0xffff0000, v184
	v_lshlrev_b32_e32 v148, 16, v185
	v_and_b32_e32 v149, 0xffff0000, v185
	v_lshlrev_b32_e32 v184, 16, v187
	v_and_b32_e32 v185, 0xffff0000, v187
	v_pk_fma_f32 v[118:119], v[118:119], v[206:207], v[148:149]
	v_pk_fma_f32 v[116:117], v[116:117], v[204:205], v[146:147]
	v_pk_fma_f32 v[146:147], v[114:115], v[202:203], v[184:185]
	v_pk_fma_f32 v[114:115], v[112:113], v[200:201], v[150:151]
	v_cvt_pk_bf16_f32 v112, v116, v117
	v_cvt_pk_bf16_f32 v113, v118, v119
	s_waitcnt vmcnt(14)
	v_lshlrev_b32_e32 v116, 16, v182
	v_cvt_pk_bf16_f32 v114, v114, v115
	v_cvt_pk_bf16_f32 v115, v146, v147
	global_store_dwordx4 v[144:145], v[112:115], off offset:256
	v_and_b32_e32 v117, 0xffff0000, v182
	v_lshlrev_b32_e32 v118, 16, v183
	v_lshlrev_b32_e32 v112, 16, v180
	v_and_b32_e32 v113, 0xffff0000, v180
	v_and_b32_e32 v119, 0xffff0000, v183
	v_pk_fma_f32 v[108:109], v[108:109], v[212:213], v[112:113]
	v_lshlrev_b32_e32 v114, 16, v181
	v_and_b32_e32 v115, 0xffff0000, v181
	v_pk_fma_f32 v[112:113], v[106:107], v[210:211], v[118:119]
	v_pk_fma_f32 v[106:107], v[104:105], v[208:209], v[116:117]
	v_cvt_pk_bf16_f32 v104, v108, v109
	v_add_co_u32_e32 v108, vcc, s45, v144
	v_pk_fma_f32 v[110:111], v[110:111], v[214:215], v[114:115]
	s_nop 0
	v_addc_co_u32_e32 v109, vcc, 0, v145, vcc
	v_cvt_pk_bf16_f32 v105, v110, v111
	v_cvt_pk_bf16_f32 v106, v106, v107
	v_cvt_pk_bf16_f32 v107, v112, v113
	global_store_dwordx4 v[108:109], v[104:107], off
	s_waitcnt vmcnt(15)
	v_lshlrev_b32_e32 v110, 16, v178
	v_and_b32_e32 v111, 0xffff0000, v178
	v_lshlrev_b32_e32 v104, 16, v176
	v_and_b32_e32 v105, 0xffff0000, v176
	v_lshlrev_b32_e32 v106, 16, v177
	v_and_b32_e32 v107, 0xffff0000, v177
	v_lshlrev_b32_e32 v112, 16, v179
	v_and_b32_e32 v113, 0xffff0000, v179
	v_pk_fma_f32 v[102:103], v[102:103], v[206:207], v[106:107]
	v_pk_fma_f32 v[100:101], v[100:101], v[204:205], v[104:105]
	v_pk_fma_f32 v[104:105], v[98:99], v[202:203], v[112:113]
	v_pk_fma_f32 v[98:99], v[96:97], v[200:201], v[110:111]
	v_cvt_pk_bf16_f32 v96, v100, v101
	v_cvt_pk_bf16_f32 v97, v102, v103
	s_waitcnt vmcnt(14)
	v_lshlrev_b32_e32 v100, 16, v174
	v_cvt_pk_bf16_f32 v98, v98, v99
	v_cvt_pk_bf16_f32 v99, v104, v105
	global_store_dwordx4 v[108:109], v[96:99], off offset:256
	v_and_b32_e32 v101, 0xffff0000, v174
	v_lshlrev_b32_e32 v102, 16, v175
	v_lshlrev_b32_e32 v96, 16, v172
	v_and_b32_e32 v97, 0xffff0000, v172
	v_and_b32_e32 v103, 0xffff0000, v175
	v_pk_fma_f32 v[92:93], v[92:93], v[212:213], v[96:97]
	v_lshlrev_b32_e32 v98, 16, v173
	v_and_b32_e32 v99, 0xffff0000, v173
	v_pk_fma_f32 v[96:97], v[90:91], v[210:211], v[102:103]
	v_pk_fma_f32 v[90:91], v[88:89], v[208:209], v[100:101]
	v_cvt_pk_bf16_f32 v88, v92, v93
	v_add_co_u32_e32 v92, vcc, s36, v144
	v_pk_fma_f32 v[94:95], v[94:95], v[214:215], v[98:99]
	s_nop 0
	v_addc_co_u32_e32 v93, vcc, 0, v145, vcc
	v_cvt_pk_bf16_f32 v89, v94, v95
	v_cvt_pk_bf16_f32 v90, v90, v91
	v_cvt_pk_bf16_f32 v91, v96, v97
	global_store_dwordx4 v[92:93], v[88:91], off
	s_waitcnt vmcnt(15)
	v_lshlrev_b32_e32 v94, 16, v170
	v_and_b32_e32 v95, 0xffff0000, v170
	v_lshlrev_b32_e32 v88, 16, v168
	v_and_b32_e32 v89, 0xffff0000, v168
	v_lshlrev_b32_e32 v90, 16, v169
	v_and_b32_e32 v91, 0xffff0000, v169
	v_lshlrev_b32_e32 v96, 16, v171
	v_and_b32_e32 v97, 0xffff0000, v171
	v_pk_fma_f32 v[86:87], v[86:87], v[206:207], v[90:91]
	v_pk_fma_f32 v[84:85], v[84:85], v[204:205], v[88:89]
	v_pk_fma_f32 v[88:89], v[82:83], v[202:203], v[96:97]
	v_pk_fma_f32 v[82:83], v[80:81], v[200:201], v[94:95]
	v_cvt_pk_bf16_f32 v80, v84, v85
	v_cvt_pk_bf16_f32 v81, v86, v87
	s_waitcnt vmcnt(14)
; __device__ __forceinline__ unsigned cvt_pk_bf16(float lo, float hi) { unsigned r; asm volatile("v_cvt_pk_bf16_f32 %0, %1, %2" : "=v"(r) : "v"(lo), "v"(hi)); return r; }
;     __device__ __forceinline__ void operator()(f32x4 (&acc)[2][2][4][2], const Unit& u, int wr, int wc, int fr, int fq, LAS unsigned char*) const {
;     ...
; #pragma unroll
;             for (int ai = 0; ai < 2; ++ai)
; #pragma unroll
;                 for (int m = 0; m < 4; ++m)
; #pragma unroll
;                     for (int bj = 0; bj < 2; ++bj) { const u32x4 x = xb[ai][m][bj];
;                         f32x4 r0 = (f32x4){__uint_as_float(x.x << 16), __uint_as_float(x.x & 0xffff0000u), __uint_as_float(x.y << 16), __uint_as_float(x.y & 0xffff0000u)};
;                         f32x4 r1 = (f32x4){__uint_as_float(x.z << 16), __uint_as_float(x.z & 0xffff0000u), __uint_as_float(x.w << 16), __uint_as_float(x.w & 0xffff0000u)};
;                         r0 += sc[bj][0] * acc[ai][bj][m][0]; r1 += sc[bj][1] * acc[ai][bj][m][1];
;                         u32x4 w; w.x = cvt_pk_bf16(r0[0], r0[1]); w.y = cvt_pk_bf16(r0[2], r0[3]); w.z = cvt_pk_bf16(r1[0], r1[1]); w.w = cvt_pk_bf16(r1[2], r1[3]);
;                         *(u32x4*)(out + off0 + (size_t)(ai * HALF + m * 16) * D + bj * HALF) = w; }
	v_lshlrev_b32_e32 v84, 16, v166
	v_cvt_pk_bf16_f32 v82, v82, v83
	v_cvt_pk_bf16_f32 v83, v88, v89
	global_store_dwordx4 v[92:93], v[80:83], off offset:256
	v_and_b32_e32 v85, 0xffff0000, v166
	v_lshlrev_b32_e32 v86, 16, v167
	v_lshlrev_b32_e32 v80, 16, v164
	v_and_b32_e32 v81, 0xffff0000, v164
	v_and_b32_e32 v87, 0xffff0000, v167
	v_pk_fma_f32 v[76:77], v[76:77], v[212:213], v[80:81]
	v_lshlrev_b32_e32 v82, 16, v165
	v_and_b32_e32 v83, 0xffff0000, v165
	v_pk_fma_f32 v[80:81], v[74:75], v[210:211], v[86:87]
	v_pk_fma_f32 v[74:75], v[72:73], v[208:209], v[84:85]
	v_cvt_pk_bf16_f32 v72, v76, v77
	v_add_co_u32_e32 v76, vcc, s23, v144
	v_pk_fma_f32 v[78:79], v[78:79], v[214:215], v[82:83]
	s_nop 0
	v_addc_co_u32_e32 v77, vcc, 0, v145, vcc
	v_cvt_pk_bf16_f32 v73, v78, v79
	v_cvt_pk_bf16_f32 v74, v74, v75
	v_cvt_pk_bf16_f32 v75, v80, v81
	global_store_dwordx4 v[76:77], v[72:75], off
	s_waitcnt vmcnt(15)
	v_lshlrev_b32_e32 v78, 16, v162
	v_and_b32_e32 v79, 0xffff0000, v162
	v_lshlrev_b32_e32 v72, 16, v160
	v_and_b32_e32 v73, 0xffff0000, v160
	v_lshlrev_b32_e32 v74, 16, v161
	v_and_b32_e32 v75, 0xffff0000, v161
	v_lshlrev_b32_e32 v80, 16, v163
	v_and_b32_e32 v81, 0xffff0000, v163
	v_pk_fma_f32 v[70:71], v[70:71], v[206:207], v[74:75]
	v_pk_fma_f32 v[68:69], v[68:69], v[204:205], v[72:73]
	v_pk_fma_f32 v[72:73], v[66:67], v[202:203], v[80:81]
	v_pk_fma_f32 v[66:67], v[64:65], v[200:201], v[78:79]
	v_cvt_pk_bf16_f32 v64, v68, v69
	v_cvt_pk_bf16_f32 v65, v70, v71
	s_waitcnt vmcnt(14)
	v_lshlrev_b32_e32 v68, 16, v158
	v_cvt_pk_bf16_f32 v66, v66, v67
	v_cvt_pk_bf16_f32 v67, v72, v73
	global_store_dwordx4 v[76:77], v[64:67], off offset:256
	v_and_b32_e32 v69, 0xffff0000, v158
	v_lshlrev_b32_e32 v70, 16, v159
	v_lshlrev_b32_e32 v64, 16, v156
	v_and_b32_e32 v65, 0xffff0000, v156
	v_and_b32_e32 v71, 0xffff0000, v159
	v_pk_fma_f32 v[60:61], v[60:61], v[212:213], v[64:65]
	v_lshlrev_b32_e32 v66, 16, v157
	v_and_b32_e32 v67, 0xffff0000, v157
	v_pk_fma_f32 v[64:65], v[58:59], v[210:211], v[70:71]
	v_pk_fma_f32 v[58:59], v[56:57], v[208:209], v[68:69]
	v_cvt_pk_bf16_f32 v56, v60, v61
	v_add_co_u32_e32 v60, vcc, s93, v144
	v_pk_fma_f32 v[62:63], v[62:63], v[214:215], v[66:67]
	s_nop 0
	v_addc_co_u32_e32 v61, vcc, 0, v145, vcc
	v_cvt_pk_bf16_f32 v57, v62, v63
	v_cvt_pk_bf16_f32 v58, v58, v59
	v_cvt_pk_bf16_f32 v59, v64, v65
	global_store_dwordx4 v[60:61], v[56:59], off
	s_waitcnt vmcnt(15)
	v_lshlrev_b32_e32 v62, 16, v154
	v_and_b32_e32 v63, 0xffff0000, v154
	v_lshlrev_b32_e32 v56, 16, v152
	v_and_b32_e32 v57, 0xffff0000, v152
	v_lshlrev_b32_e32 v58, 16, v153
	v_and_b32_e32 v59, 0xffff0000, v153
	v_lshlrev_b32_e32 v64, 16, v155
	v_and_b32_e32 v65, 0xffff0000, v155
	v_pk_fma_f32 v[54:55], v[54:55], v[206:207], v[58:59]
	v_pk_fma_f32 v[52:53], v[52:53], v[204:205], v[56:57]
	v_pk_fma_f32 v[56:57], v[50:51], v[202:203], v[64:65]
	v_pk_fma_f32 v[50:51], v[48:49], v[200:201], v[62:63]
	v_cvt_pk_bf16_f32 v48, v52, v53
	v_cvt_pk_bf16_f32 v49, v54, v55
	s_waitcnt vmcnt(14)
	v_lshlrev_b32_e32 v52, 16, v142
	v_cvt_pk_bf16_f32 v50, v50, v51
	v_cvt_pk_bf16_f32 v51, v56, v57
	global_store_dwordx4 v[60:61], v[48:51], off offset:256
	v_and_b32_e32 v53, 0xffff0000, v142
	v_lshlrev_b32_e32 v54, 16, v143
	v_lshlrev_b32_e32 v48, 16, v140
	v_and_b32_e32 v49, 0xffff0000, v140
	v_and_b32_e32 v55, 0xffff0000, v143
	v_pk_fma_f32 v[44:45], v[44:45], v[212:213], v[48:49]
	v_lshlrev_b32_e32 v50, 16, v141
	v_and_b32_e32 v51, 0xffff0000, v141
	v_pk_fma_f32 v[48:49], v[42:43], v[210:211], v[54:55]
	v_pk_fma_f32 v[42:43], v[40:41], v[208:209], v[52:53]
	v_cvt_pk_bf16_f32 v40, v44, v45
	v_add_co_u32_e32 v44, vcc, s33, v144
	v_pk_fma_f32 v[46:47], v[46:47], v[214:215], v[50:51]
	s_nop 0
	v_addc_co_u32_e32 v45, vcc, 0, v145, vcc
	v_cvt_pk_bf16_f32 v41, v46, v47
	v_cvt_pk_bf16_f32 v42, v42, v43
	v_cvt_pk_bf16_f32 v43, v48, v49
	global_store_dwordx4 v[44:45], v[40:43], off
	s_waitcnt vmcnt(15)
; __device__ __forceinline__ unsigned cvt_pk_bf16(float lo, float hi) { unsigned r; asm volatile("v_cvt_pk_bf16_f32 %0, %1, %2" : "=v"(r) : "v"(lo), "v"(hi)); return r; }
;     __device__ __forceinline__ void operator()(f32x4 (&acc)[2][2][4][2], const Unit& u, int wr, int wc, int fr, int fq, LAS unsigned char*) const {
;     ...
; #pragma unroll
;             for (int ai = 0; ai < 2; ++ai)
; #pragma unroll
;                 for (int m = 0; m < 4; ++m)
; #pragma unroll
;                     for (int bj = 0; bj < 2; ++bj) { const u32x4 x = xb[ai][m][bj];
;                         f32x4 r0 = (f32x4){__uint_as_float(x.x << 16), __uint_as_float(x.x & 0xffff0000u), __uint_as_float(x.y << 16), __uint_as_float(x.y & 0xffff0000u)};
;                         f32x4 r1 = (f32x4){__uint_as_float(x.z << 16), __uint_as_float(x.z & 0xffff0000u), __uint_as_float(x.w << 16), __uint_as_float(x.w & 0xffff0000u)};
;                         r0 += sc[bj][0] * acc[ai][bj][m][0]; r1 += sc[bj][1] * acc[ai][bj][m][1];
;                         u32x4 w; w.x = cvt_pk_bf16(r0[0], r0[1]); w.y = cvt_pk_bf16(r0[2], r0[3]); w.z = cvt_pk_bf16(r1[0], r1[1]); w.w = cvt_pk_bf16(r1[2], r1[3]);
;                         *(u32x4*)(out + off0 + (size_t)(ai * HALF + m * 16) * D + bj * HALF) = w; }
	v_lshlrev_b32_e32 v46, 16, v138
	v_and_b32_e32 v47, 0xffff0000, v138
	v_lshlrev_b32_e32 v40, 16, v136
	v_and_b32_e32 v41, 0xffff0000, v136
	v_lshlrev_b32_e32 v42, 16, v137
	v_and_b32_e32 v43, 0xffff0000, v137
	v_lshlrev_b32_e32 v48, 16, v139
	v_and_b32_e32 v49, 0xffff0000, v139
	v_pk_fma_f32 v[38:39], v[38:39], v[206:207], v[42:43]
	v_pk_fma_f32 v[36:37], v[36:37], v[204:205], v[40:41]
	v_pk_fma_f32 v[40:41], v[34:35], v[202:203], v[48:49]
	v_pk_fma_f32 v[34:35], v[32:33], v[200:201], v[46:47]
	v_cvt_pk_bf16_f32 v32, v36, v37
	v_cvt_pk_bf16_f32 v33, v38, v39
	s_waitcnt vmcnt(14)
	v_lshlrev_b32_e32 v36, 16, v134
	v_cvt_pk_bf16_f32 v34, v34, v35
	v_cvt_pk_bf16_f32 v35, v40, v41
	global_store_dwordx4 v[44:45], v[32:35], off offset:256
	v_and_b32_e32 v37, 0xffff0000, v134
	v_lshlrev_b32_e32 v38, 16, v135
	v_lshlrev_b32_e32 v32, 16, v132
	v_and_b32_e32 v33, 0xffff0000, v132
	v_and_b32_e32 v39, 0xffff0000, v135
	v_pk_fma_f32 v[28:29], v[28:29], v[212:213], v[32:33]
	v_lshlrev_b32_e32 v34, 16, v133
	v_and_b32_e32 v35, 0xffff0000, v133
	v_pk_fma_f32 v[32:33], v[26:27], v[210:211], v[38:39]
	v_pk_fma_f32 v[26:27], v[24:25], v[208:209], v[36:37]
	v_cvt_pk_bf16_f32 v24, v28, v29
	v_add_co_u32_e32 v28, vcc, s18, v144
	v_pk_fma_f32 v[30:31], v[30:31], v[214:215], v[34:35]
	s_nop 0
	v_addc_co_u32_e32 v29, vcc, 0, v145, vcc
	v_cvt_pk_bf16_f32 v25, v30, v31
	v_cvt_pk_bf16_f32 v26, v26, v27
	v_cvt_pk_bf16_f32 v27, v32, v33
	global_store_dwordx4 v[28:29], v[24:27], off
	s_waitcnt vmcnt(15)
	v_lshlrev_b32_e32 v30, 16, v130
	v_and_b32_e32 v31, 0xffff0000, v130
	v_lshlrev_b32_e32 v24, 16, v128
	v_and_b32_e32 v25, 0xffff0000, v128
	v_lshlrev_b32_e32 v26, 16, v129
	v_and_b32_e32 v27, 0xffff0000, v129
	v_lshlrev_b32_e32 v32, 16, v131
	v_and_b32_e32 v33, 0xffff0000, v131
	v_pk_fma_f32 v[22:23], v[22:23], v[206:207], v[26:27]
	v_pk_fma_f32 v[20:21], v[20:21], v[204:205], v[24:25]
	v_pk_fma_f32 v[24:25], v[18:19], v[202:203], v[32:33]
	v_pk_fma_f32 v[18:19], v[16:17], v[200:201], v[30:31]
	v_cvt_pk_bf16_f32 v16, v20, v21
	v_cvt_pk_bf16_f32 v17, v22, v23
	s_waitcnt vmcnt(14)
	v_lshlrev_b32_e32 v20, 16, v126
	v_cvt_pk_bf16_f32 v18, v18, v19
	v_cvt_pk_bf16_f32 v19, v24, v25
	global_store_dwordx4 v[28:29], v[16:19], off offset:256
	v_and_b32_e32 v21, 0xffff0000, v126
	v_lshlrev_b32_e32 v22, 16, v127
	v_lshlrev_b32_e32 v16, 16, v124
	v_and_b32_e32 v17, 0xffff0000, v124
	v_and_b32_e32 v23, 0xffff0000, v127
	v_pk_fma_f32 v[12:13], v[12:13], v[212:213], v[16:17]
	v_lshlrev_b32_e32 v18, 16, v125
	v_and_b32_e32 v19, 0xffff0000, v125
	v_pk_fma_f32 v[16:17], v[10:11], v[210:211], v[22:23]
	v_pk_fma_f32 v[10:11], v[8:9], v[208:209], v[20:21]
	v_cvt_pk_bf16_f32 v8, v12, v13
	v_add_co_u32_e32 v12, vcc, s19, v144
	v_pk_fma_f32 v[14:15], v[14:15], v[214:215], v[18:19]
	s_nop 0
	v_addc_co_u32_e32 v13, vcc, 0, v145, vcc
	v_cvt_pk_bf16_f32 v9, v14, v15
	v_cvt_pk_bf16_f32 v10, v10, v11
	v_cvt_pk_bf16_f32 v11, v16, v17
	global_store_dwordx4 v[12:13], v[8:11], off
	s_waitcnt vmcnt(15)
	v_lshlrev_b32_e32 v14, 16, v122
	v_and_b32_e32 v15, 0xffff0000, v122
	v_lshlrev_b32_e32 v8, 16, v120
	v_and_b32_e32 v9, 0xffff0000, v120
	v_lshlrev_b32_e32 v16, 16, v123
	v_and_b32_e32 v17, 0xffff0000, v123
	v_lshlrev_b32_e32 v10, 16, v121
	v_and_b32_e32 v11, 0xffff0000, v121
	v_pk_fma_f32 v[4:5], v[4:5], v[204:205], v[8:9]
	v_pk_fma_f32 v[8:9], v[2:3], v[202:203], v[16:17]
	v_pk_fma_f32 v[2:3], v[0:1], v[200:201], v[14:15]
	s_and_b64 vcc, exec, s[4:5]
	v_pk_fma_f32 v[6:7], v[6:7], v[206:207], v[10:11]
	v_cvt_pk_bf16_f32 v0, v4, v5
	s_nop 0
	v_cvt_pk_bf16_f32 v1, v6, v7
	v_cvt_pk_bf16_f32 v2, v2, v3
	v_cvt_pk_bf16_f32 v3, v8, v9
	global_store_dwordx4 v[12:13], v[0:3], off offset:256
	s_cbranch_vccz .LBB0_603
	s_waitcnt vmcnt(0)
	s_cmpk_gt_u32 s16, 0xff
	v_readlane_b32 s38, v255, 44
	s_movk_i32 s30, 0x7ff
	s_cbranch_scc1 .LBB0_614
	s_barrier

; #define PG8_STAGE(bufoff, gbase, hoff, imm) do { _Pragma("unroll") for (int _i = 0; _i < 2; ++_i) { \
;         asm volatile("s_mov_b32 m0, %0\n\ts_nop 0\n\tglobal_load_lds_dwordx4 %1, %2" \
;             :: "s"(lds0 + (unsigned)((bufoff) + _i * 8192)), "v"(voff0), "s"((const char*)(gbase) + (size_t)(hoff) + (size_t)(_i * 8192)) : "memory"); } } while (0)
; #define PG8_LDA(dst, b, h) do { _Pragma("unroll") for (int m = 0; m < 4; ++m) _Pragma("unroll") for (int k = 0; k < 2; ++k) dst[m][k] = *(const LAS bf16x8*)(lds + PG8_SA(b, h) + aoff + m * 2048 + k * 1024); } while (0)
; #define PG8_LDB(dst, b, h) do { _Pragma("unroll") for (int n = 0; n < 2; ++n) _Pragma("unroll") for (int k = 0; k < 2; ++k) dst[n][k] = *(const LAS bf16x8*)(lds + PG8_SB(b, h) + boff + n * 2048 + k * 1024); } while (0)
; #define PG8_MMA(ai, bj, At, Bt) do { __builtin_amdgcn_s_setprio(1); _Pragma("unroll") for (int m = 0; m < 4; ++m) _Pragma("unroll") for (int n = 0; n < 2; ++n) _Pragma("unroll") for (int k = 0; k < 2; ++k) \
;         acc[ai][bj][m][n] = __builtin_amdgcn_mfma_f32_16x16x32_bf16(Bt[n][k], At[m][k], acc[ai][bj][m][n], 0, 0, 0); __builtin_amdgcn_s_setprio(0); } while (0)
; #define PG8_WAIT_L(n) asm volatile("s_waitcnt lgkmcnt(" #n ")" ::: "memory")
; #define PG8_BAR __builtin_amdgcn_s_barrier()
; #define PG8_SCHED __builtin_amdgcn_sched_barrier(0)
; template <class Epi>
; __device__ __forceinline__ void gemm_phase(LAS unsigned char* lds, const Gemm g, const StaticOrder& S, const Epi& E) {
;     ...
;             const char* aT = cA + (size_t)t * KS;
;             const char* a2 = last ? nA : aT + 2 * KS; const char* b2 = last ? nB : cB + (size_t)(t + 2) * KS;
;             PG8_LDB(B0, 0, 0); PG8_SCHED; PG8_LDA(At, 0, 0); PG8_STAGE(PG8_SA(1, 1), aT + KS, hA, 0);
;             PG8_WAIT_L(8); PG8_BAR; PG8_WAIT_L(0); PG8_MMA(0, 0, At, B0); PG8_BAR; PG8_SCHED;
;             PG8_LDB(B1, 0, 1); PG8_STAGE(PG8_SB(0, 0), b2, 0, 0);
;             PG8_BAR; PG8_WAIT_L(0); PG8_MMA(0, 1, At, B1); PG8_BAR;
;             PG8_LDA(At, 0, 1); PG8_STAGE(PG8_SA(0, 0), a2, 0, 0);
;             PG8_BAR; PG8_WAIT_L(0); PG8_MMA(1, 0, At, B0); PG8_BAR; PG8_SCHED;
.LBB0_738:
	s_add_u32 s78, s76, 0x8000
	s_addc_u32 s79, s77, 0
	s_and_b64 s[48:49], s[82:83], exec
	s_cselect_b32 s81, s50, s79
	s_cselect_b32 s80, s51, s78
	ds_read_b128 v[144:147], v178
	ds_read_b128 v[148:151], v178 offset:1024
	ds_read_b128 v[184:187], v178 offset:2048
	ds_read_b128 v[200:203], v178 offset:3072
	ds_read_b128 v[204:207], v178 offset:4096
	ds_read_b128 v[208:211], v178 offset:5120
	ds_read_b128 v[212:215], v178 offset:6144
	ds_read_b128 v[236:239], v178 offset:7168
	s_waitcnt lgkmcnt(8)
	s_waitcnt vmcnt(10)
	s_barrier
	s_waitcnt lgkmcnt(7)
	v_mfma_f32_16x16x32_bf16 v[116:119], v[128:131], v[144:147], v[116:119]
	v_mfma_f32_16x16x32_bf16 v[80:83], v[136:139], v[144:147], v[80:83]
	s_waitcnt lgkmcnt(5)
	v_mfma_f32_16x16x32_bf16 v[88:91], v[128:131], v[184:187], v[88:91]
	v_mfma_f32_16x16x32_bf16 v[84:87], v[136:139], v[184:187], v[84:87]
	s_waitcnt lgkmcnt(3)
	v_mfma_f32_16x16x32_bf16 v[120:123], v[128:131], v[204:207], v[120:123]
	v_mfma_f32_16x16x32_bf16 v[92:95], v[136:139], v[204:207], v[92:95]
	s_waitcnt lgkmcnt(1)
	v_mfma_f32_16x16x32_bf16 v[124:127], v[128:131], v[212:215], v[124:127]
	v_mfma_f32_16x16x32_bf16 v[96:99], v[136:139], v[212:215], v[96:99]
	v_mfma_f32_16x16x32_bf16 v[116:119], v[132:135], v[148:151], v[116:119]
	v_mfma_f32_16x16x32_bf16 v[80:83], v[140:143], v[148:151], v[80:83]
	v_mfma_f32_16x16x32_bf16 v[88:91], v[132:135], v[200:203], v[88:91]
	v_mfma_f32_16x16x32_bf16 v[84:87], v[140:143], v[200:203], v[84:87]
	v_mfma_f32_16x16x32_bf16 v[120:123], v[132:135], v[208:211], v[120:123]
	v_mfma_f32_16x16x32_bf16 v[92:95], v[140:143], v[208:211], v[92:95]
	s_waitcnt lgkmcnt(0)
	v_mfma_f32_16x16x32_bf16 v[124:127], v[132:135], v[236:239], v[124:127]
	v_mfma_f32_16x16x32_bf16 v[96:99], v[140:143], v[236:239], v[96:99]
	s_barrier
	v_add_u32_e32 v188, 0x14000, v177
	ds_read_b128 v[240:243], v188
	ds_read_b128 v[244:247], v188 offset:1024
	ds_read_b128 v[248:251], v188 offset:2048
	ds_read_b128 v[230:233], v188 offset:3072
	s_and_b64 s[48:49], s[82:83], exec
	s_cselect_b32 s76, s0, s1
	s_cselect_b32 s77, s69, s9
	s_mov_b32 m0, s28
	s_nop 0
	global_load_lds_dwordx4 v152, s[76:77]
	s_add_u32 s48, s76, 0x2000
	s_addc_u32 s49, s77, 0
	s_mov_b32 m0, s29
	s_nop 0
	global_load_lds_dwordx4 v152, s[48:49]
	s_waitcnt vmcnt(10)
	s_barrier
	s_waitcnt lgkmcnt(3)
	v_mfma_f32_16x16x32_bf16 v[48:51], v[240:243], v[144:147], v[48:51]
	s_waitcnt lgkmcnt(1)
	v_mfma_f32_16x16x32_bf16 v[16:19], v[248:251], v[144:147], v[16:19]
	v_mfma_f32_16x16x32_bf16 v[52:55], v[240:243], v[184:187], v[52:55]
	v_mfma_f32_16x16x32_bf16 v[20:23], v[248:251], v[184:187], v[20:23]
	v_mfma_f32_16x16x32_bf16 v[56:59], v[240:243], v[204:207], v[56:59]
	v_mfma_f32_16x16x32_bf16 v[24:27], v[248:251], v[204:207], v[24:27]
	v_mfma_f32_16x16x32_bf16 v[60:63], v[240:243], v[212:215], v[60:63]
	v_mfma_f32_16x16x32_bf16 v[28:31], v[248:251], v[212:215], v[28:31]
	v_mfma_f32_16x16x32_bf16 v[48:51], v[244:247], v[148:151], v[48:51]
	s_waitcnt lgkmcnt(0)
	v_mfma_f32_16x16x32_bf16 v[16:19], v[230:233], v[148:151], v[16:19]
	v_mfma_f32_16x16x32_bf16 v[52:55], v[244:247], v[200:203], v[52:55]
	v_mfma_f32_16x16x32_bf16 v[20:23], v[230:233], v[200:203], v[20:23]
	v_mfma_f32_16x16x32_bf16 v[56:59], v[244:247], v[208:211], v[56:59]
	v_mfma_f32_16x16x32_bf16 v[24:27], v[230:233], v[208:211], v[24:27]
	v_mfma_f32_16x16x32_bf16 v[60:63], v[244:247], v[236:239], v[60:63]
	v_mfma_f32_16x16x32_bf16 v[28:31], v[230:233], v[236:239], v[28:31]
	s_barrier
	ds_read_b128 v[144:147], v178 offset:16384
	ds_read_b128 v[148:151], v178 offset:17408
	ds_read_b128 v[184:187], v178 offset:18432
	ds_read_b128 v[200:203], v178 offset:19456
	ds_read_b128 v[204:207], v178 offset:20480
	ds_read_b128 v[208:211], v178 offset:21504
	ds_read_b128 v[212:215], v178 offset:22528
	ds_read_b128 v[236:239], v178 offset:23552
	s_mov_b32 m0, s89
	s_nop 0
	global_load_lds_dwordx4 v152, s[80:81]
	s_add_u32 s48, s80, 0x2000
	s_addc_u32 s49, s81, 0
	s_mov_b32 m0, s40
	s_nop 0
	global_load_lds_dwordx4 v152, s[48:49]
	s_waitcnt vmcnt(10)
	s_barrier
	s_waitcnt lgkmcnt(7)
	v_mfma_f32_16x16x32_bf16 v[100:103], v[128:131], v[144:147], v[100:103]
	v_mfma_f32_16x16x32_bf16 v[64:67], v[136:139], v[144:147], v[64:67]
	s_waitcnt lgkmcnt(5)
	v_mfma_f32_16x16x32_bf16 v[104:107], v[128:131], v[184:187], v[104:107]
	v_mfma_f32_16x16x32_bf16 v[68:71], v[136:139], v[184:187], v[68:71]
	s_waitcnt lgkmcnt(3)
	v_mfma_f32_16x16x32_bf16 v[108:111], v[128:131], v[204:207], v[108:111]
	v_mfma_f32_16x16x32_bf16 v[72:75], v[136:139], v[204:207], v[72:75]
	s_waitcnt lgkmcnt(1)
	v_mfma_f32_16x16x32_bf16 v[112:115], v[128:131], v[212:215], v[112:115]
	v_mfma_f32_16x16x32_bf16 v[76:79], v[136:139], v[212:215], v[76:79]
	v_mfma_f32_16x16x32_bf16 v[100:103], v[132:135], v[148:151], v[100:103]
	v_mfma_f32_16x16x32_bf16 v[64:67], v[140:143], v[148:151], v[64:67]
	v_mfma_f32_16x16x32_bf16 v[104:107], v[132:135], v[200:203], v[104:107]
	v_mfma_f32_16x16x32_bf16 v[68:71], v[140:143], v[200:203], v[68:71]
	v_mfma_f32_16x16x32_bf16 v[108:111], v[132:135], v[208:211], v[108:111]
	v_mfma_f32_16x16x32_bf16 v[72:75], v[140:143], v[208:211], v[72:75]
	s_waitcnt lgkmcnt(0)
	v_mfma_f32_16x16x32_bf16 v[112:115], v[132:135], v[236:239], v[112:115]
	v_mfma_f32_16x16x32_bf16 v[76:79], v[140:143], v[236:239], v[76:79]
	s_barrier
; #define PG8_STAGE(bufoff, gbase, hoff, imm) do { _Pragma("unroll") for (int _i = 0; _i < 2; ++_i) { \
;         asm volatile("s_mov_b32 m0, %0\n\ts_nop 0\n\tglobal_load_lds_dwordx4 %1, %2" \
;             :: "s"(lds0 + (unsigned)((bufoff) + _i * 8192)), "v"(voff0), "s"((const char*)(gbase) + (size_t)(hoff) + (size_t)(_i * 8192)) : "memory"); } } while (0)
; #define PG8_LDA(dst, b, h) do { _Pragma("unroll") for (int m = 0; m < 4; ++m) _Pragma("unroll") for (int k = 0; k < 2; ++k) dst[m][k] = *(const LAS bf16x8*)(lds + PG8_SA(b, h) + aoff + m * 2048 + k * 1024); } while (0)
; #define PG8_LDB(dst, b, h) do { _Pragma("unroll") for (int n = 0; n < 2; ++n) _Pragma("unroll") for (int k = 0; k < 2; ++k) dst[n][k] = *(const LAS bf16x8*)(lds + PG8_SB(b, h) + boff + n * 2048 + k * 1024); } while (0)
; #define PG8_MMA(ai, bj, At, Bt) do { __builtin_amdgcn_s_setprio(1); _Pragma("unroll") for (int m = 0; m < 4; ++m) _Pragma("unroll") for (int n = 0; n < 2; ++n) _Pragma("unroll") for (int k = 0; k < 2; ++k) \
;         acc[ai][bj][m][n] = __builtin_amdgcn_mfma_f32_16x16x32_bf16(Bt[n][k], At[m][k], acc[ai][bj][m][n], 0, 0, 0); __builtin_amdgcn_s_setprio(0); } while (0)
; #define PG8_WAIT_V(n) asm volatile("s_waitcnt vmcnt(" #n ")" ::: "memory")
; #define PG8_WAIT_L(n) asm volatile("s_waitcnt lgkmcnt(" #n ")" ::: "memory")
; #define PG8_BAR __builtin_amdgcn_s_barrier()
; #define PG8_SCHED __builtin_amdgcn_sched_barrier(0)
; template <class Epi>
; __device__ __forceinline__ void gemm_phase(LAS unsigned char* lds, const Gemm g, const StaticOrder& S, const Epi& E) {
;     ...
;             PG8_STAGE(PG8_SB(0, 1), b2, hB, 0);
;             PG8_WAIT_V(6); PG8_BAR; PG8_MMA(1, 1, At, B1); PG8_BAR;
;             PG8_LDB(B0, 1, 0); PG8_SCHED; PG8_LDA(At, 1, 0); PG8_STAGE(PG8_SA(0, 1), a2, hA, 0);
;             PG8_WAIT_L(8); PG8_BAR; PG8_WAIT_L(0); PG8_MMA(0, 0, At, B0); PG8_BAR; PG8_SCHED;
;             PG8_LDB(B1, 1, 1); PG8_STAGE(PG8_SB(1, 0), b2 + KS, 0, 0);
	v_add_u32_e32 v140, 0x18000, v177
	ds_read_b128 v[128:131], v140
	ds_read_b128 v[132:135], v140 offset:1024
	ds_read_b128 v[136:139], v140 offset:2048
	ds_read_b128 v[140:143], v140 offset:3072
	s_add_u32 s48, s76, 0x80000
	s_addc_u32 s49, s77, 0
	s_mov_b32 m0, s41
	s_nop 0
	global_load_lds_dwordx4 v152, s[48:49]
	s_add_u32 s48, s76, 0x82000
	s_addc_u32 s49, s77, 0
	s_mov_b32 m0, s42
	s_nop 0
	global_load_lds_dwordx4 v152, s[48:49]
	s_add_u32 s48, s80, 0x80000
	s_addc_u32 s49, s81, 0
	s_mov_b32 m0, s43
	s_nop 0
	global_load_lds_dwordx4 v152, s[48:49]
	s_add_u32 s48, s80, 0x82000
	s_addc_u32 s49, s81, 0
	s_mov_b32 m0, s92
	s_nop 0
	global_load_lds_dwordx4 v152, s[48:49]
	s_waitcnt vmcnt(12)
	s_barrier
	v_mfma_f32_16x16x32_bf16 v[32:35], v[240:243], v[144:147], v[32:35]
	v_mfma_f32_16x16x32_bf16 v[0:3], v[248:251], v[144:147], v[0:3]
	v_mfma_f32_16x16x32_bf16 v[36:39], v[240:243], v[184:187], v[36:39]
	v_mfma_f32_16x16x32_bf16 v[4:7], v[248:251], v[184:187], v[4:7]
	v_mfma_f32_16x16x32_bf16 v[40:43], v[240:243], v[204:207], v[40:43]
	v_mfma_f32_16x16x32_bf16 v[8:11], v[248:251], v[204:207], v[8:11]
	v_mfma_f32_16x16x32_bf16 v[44:47], v[240:243], v[212:215], v[44:47]
	v_mfma_f32_16x16x32_bf16 v[12:15], v[248:251], v[212:215], v[12:15]
	v_mfma_f32_16x16x32_bf16 v[32:35], v[244:247], v[148:151], v[32:35]
	v_mfma_f32_16x16x32_bf16 v[0:3], v[230:233], v[148:151], v[0:3]
	v_mfma_f32_16x16x32_bf16 v[36:39], v[244:247], v[200:203], v[36:39]
	v_mfma_f32_16x16x32_bf16 v[4:7], v[230:233], v[200:203], v[4:7]
	v_mfma_f32_16x16x32_bf16 v[40:43], v[244:247], v[208:211], v[40:43]
	v_mfma_f32_16x16x32_bf16 v[8:11], v[230:233], v[208:211], v[8:11]
	v_mfma_f32_16x16x32_bf16 v[44:47], v[244:247], v[236:239], v[44:47]
	v_mfma_f32_16x16x32_bf16 v[12:15], v[230:233], v[236:239], v[12:15]
	s_barrier
	ds_read_b128 v[144:147], v178 offset:32768
	ds_read_b128 v[148:151], v178 offset:33792
	ds_read_b128 v[184:187], v178 offset:34816
	ds_read_b128 v[200:203], v178 offset:35840
	ds_read_b128 v[204:207], v178 offset:36864
	ds_read_b128 v[208:211], v178 offset:37888
	ds_read_b128 v[212:215], v178 offset:38912
	ds_read_b128 v[230:233], v178 offset:39936
	s_waitcnt lgkmcnt(8)
	s_waitcnt vmcnt(10)
	s_barrier
	s_waitcnt lgkmcnt(7)
	v_mfma_f32_16x16x32_bf16 v[116:119], v[128:131], v[144:147], v[116:119]
	v_mfma_f32_16x16x32_bf16 v[80:83], v[136:139], v[144:147], v[80:83]
	s_waitcnt lgkmcnt(5)
	v_mfma_f32_16x16x32_bf16 v[88:91], v[128:131], v[184:187], v[88:91]
	v_mfma_f32_16x16x32_bf16 v[84:87], v[136:139], v[184:187], v[84:87]
	s_waitcnt lgkmcnt(3)
	v_mfma_f32_16x16x32_bf16 v[120:123], v[128:131], v[204:207], v[120:123]
	v_mfma_f32_16x16x32_bf16 v[92:95], v[136:139], v[204:207], v[92:95]
	s_waitcnt lgkmcnt(1)
	v_mfma_f32_16x16x32_bf16 v[124:127], v[128:131], v[212:215], v[124:127]
	v_mfma_f32_16x16x32_bf16 v[96:99], v[136:139], v[212:215], v[96:99]
	v_mfma_f32_16x16x32_bf16 v[116:119], v[132:135], v[148:151], v[116:119]
	v_mfma_f32_16x16x32_bf16 v[80:83], v[140:143], v[148:151], v[80:83]
	v_mfma_f32_16x16x32_bf16 v[88:91], v[132:135], v[200:203], v[88:91]
	v_mfma_f32_16x16x32_bf16 v[84:87], v[140:143], v[200:203], v[84:87]
	v_mfma_f32_16x16x32_bf16 v[120:123], v[132:135], v[208:211], v[120:123]
	v_mfma_f32_16x16x32_bf16 v[92:95], v[140:143], v[208:211], v[92:95]
	s_waitcnt lgkmcnt(0)
	v_mfma_f32_16x16x32_bf16 v[124:127], v[132:135], v[230:233], v[124:127]
	v_mfma_f32_16x16x32_bf16 v[96:99], v[140:143], v[230:233], v[96:99]
	s_barrier
	v_add_u32_e32 v188, 0x1c000, v177
	ds_read_b128 v[236:239], v188
	ds_read_b128 v[240:243], v188 offset:1024
	ds_read_b128 v[244:247], v188 offset:2048
	ds_read_b128 v[248:251], v188 offset:3072
	s_add_u32 s48, s76, 0x4000
	s_addc_u32 s49, s77, 0
	s_mov_b32 m0, s16
	s_nop 0
	global_load_lds_dwordx4 v152, s[48:49]
	s_add_u32 s48, s76, 0x6000
	s_addc_u32 s49, s77, 0
	s_mov_b32 m0, s17
	s_nop 0
	global_load_lds_dwordx4 v152, s[48:49]
	s_waitcnt vmcnt(10)
	s_barrier
; #define PG8_STAGE(bufoff, gbase, hoff, imm) do { _Pragma("unroll") for (int _i = 0; _i < 2; ++_i) { \
;         asm volatile("s_mov_b32 m0, %0\n\ts_nop 0\n\tglobal_load_lds_dwordx4 %1, %2" \
;             :: "s"(lds0 + (unsigned)((bufoff) + _i * 8192)), "v"(voff0), "s"((const char*)(gbase) + (size_t)(hoff) + (size_t)(_i * 8192)) : "memory"); } } while (0)
; #define PG8_LDA(dst, b, h) do { _Pragma("unroll") for (int m = 0; m < 4; ++m) _Pragma("unroll") for (int k = 0; k < 2; ++k) dst[m][k] = *(const LAS bf16x8*)(lds + PG8_SA(b, h) + aoff + m * 2048 + k * 1024); } while (0)
; #define PG8_MMA(ai, bj, At, Bt) do { __builtin_amdgcn_s_setprio(1); _Pragma("unroll") for (int m = 0; m < 4; ++m) _Pragma("unroll") for (int n = 0; n < 2; ++n) _Pragma("unroll") for (int k = 0; k < 2; ++k) \
;         acc[ai][bj][m][n] = __builtin_amdgcn_mfma_f32_16x16x32_bf16(Bt[n][k], At[m][k], acc[ai][bj][m][n], 0, 0, 0); __builtin_amdgcn_s_setprio(0); } while (0)
; #define PG8_WAIT_V(n) asm volatile("s_waitcnt vmcnt(" #n ")" ::: "memory")
; #define PG8_WAIT_L(n) asm volatile("s_waitcnt lgkmcnt(" #n ")" ::: "memory")
; #define PG8_BAR __builtin_amdgcn_s_barrier()
; #define PG8_SCHED __builtin_amdgcn_sched_barrier(0)
; template <class Epi>
; __device__ __forceinline__ void gemm_phase(LAS unsigned char* lds, const Gemm g, const StaticOrder& S, const Epi& E) {
;     ...
;             PG8_BAR; PG8_WAIT_L(0); PG8_MMA(0, 1, At, B1); PG8_BAR;
;             PG8_LDA(At, 1, 1); PG8_STAGE(PG8_SA(1, 0), a2 + KS, 0, 0);
;             PG8_BAR; PG8_WAIT_L(0); PG8_MMA(1, 0, At, B0); PG8_BAR; PG8_SCHED;
;             PG8_STAGE(PG8_SB(1, 1), b2 + KS, hB, 0);
;             PG8_WAIT_V(6); PG8_BAR; PG8_MMA(1, 1, At, B1); PG8_BAR;
	s_waitcnt lgkmcnt(3)
	v_mfma_f32_16x16x32_bf16 v[48:51], v[236:239], v[144:147], v[48:51]
	s_waitcnt lgkmcnt(1)
	v_mfma_f32_16x16x32_bf16 v[16:19], v[244:247], v[144:147], v[16:19]
	v_mfma_f32_16x16x32_bf16 v[52:55], v[236:239], v[184:187], v[52:55]
	v_mfma_f32_16x16x32_bf16 v[20:23], v[244:247], v[184:187], v[20:23]
	v_mfma_f32_16x16x32_bf16 v[56:59], v[236:239], v[204:207], v[56:59]
	v_mfma_f32_16x16x32_bf16 v[24:27], v[244:247], v[204:207], v[24:27]
	v_mfma_f32_16x16x32_bf16 v[60:63], v[236:239], v[212:215], v[60:63]
	v_mfma_f32_16x16x32_bf16 v[28:31], v[244:247], v[212:215], v[28:31]
	v_mfma_f32_16x16x32_bf16 v[48:51], v[240:243], v[148:151], v[48:51]
	s_waitcnt lgkmcnt(0)
	v_mfma_f32_16x16x32_bf16 v[16:19], v[248:251], v[148:151], v[16:19]
	v_mfma_f32_16x16x32_bf16 v[52:55], v[240:243], v[200:203], v[52:55]
	v_mfma_f32_16x16x32_bf16 v[20:23], v[248:251], v[200:203], v[20:23]
	v_mfma_f32_16x16x32_bf16 v[56:59], v[240:243], v[208:211], v[56:59]
	v_mfma_f32_16x16x32_bf16 v[24:27], v[248:251], v[208:211], v[24:27]
	v_mfma_f32_16x16x32_bf16 v[60:63], v[240:243], v[230:233], v[60:63]
	v_mfma_f32_16x16x32_bf16 v[28:31], v[248:251], v[230:233], v[28:31]
	s_barrier
	ds_read_b128 v[144:147], v178 offset:49152
	ds_read_b128 v[148:151], v178 offset:50176
	ds_read_b128 v[184:187], v178 offset:51200
	ds_read_b128 v[200:203], v178 offset:52224
	ds_read_b128 v[204:207], v178 offset:53248
	ds_read_b128 v[208:211], v178 offset:54272
	ds_read_b128 v[212:215], v178 offset:55296
	ds_read_b128 v[230:233], v178 offset:56320
	s_add_u32 s48, s80, 0x4000
	s_addc_u32 s49, s81, 0
	s_mov_b32 m0, s24
	s_nop 0
	global_load_lds_dwordx4 v152, s[48:49]
	s_add_u32 s48, s80, 0x6000
	s_addc_u32 s49, s81, 0
	s_mov_b32 m0, s37
	s_nop 0
	global_load_lds_dwordx4 v152, s[48:49]
	s_waitcnt vmcnt(10)
	s_barrier
	s_waitcnt lgkmcnt(7)
	v_mfma_f32_16x16x32_bf16 v[100:103], v[128:131], v[144:147], v[100:103]
	v_mfma_f32_16x16x32_bf16 v[64:67], v[136:139], v[144:147], v[64:67]
	s_waitcnt lgkmcnt(5)
	v_mfma_f32_16x16x32_bf16 v[104:107], v[128:131], v[184:187], v[104:107]
	v_mfma_f32_16x16x32_bf16 v[68:71], v[136:139], v[184:187], v[68:71]
	s_waitcnt lgkmcnt(3)
	v_mfma_f32_16x16x32_bf16 v[108:111], v[128:131], v[204:207], v[108:111]
	v_mfma_f32_16x16x32_bf16 v[72:75], v[136:139], v[204:207], v[72:75]
	s_waitcnt lgkmcnt(1)
	v_mfma_f32_16x16x32_bf16 v[112:115], v[128:131], v[212:215], v[112:115]
	v_mfma_f32_16x16x32_bf16 v[76:79], v[136:139], v[212:215], v[76:79]
	v_mfma_f32_16x16x32_bf16 v[100:103], v[132:135], v[148:151], v[100:103]
	v_mfma_f32_16x16x32_bf16 v[64:67], v[140:143], v[148:151], v[64:67]
	v_mfma_f32_16x16x32_bf16 v[104:107], v[132:135], v[200:203], v[104:107]
	v_mfma_f32_16x16x32_bf16 v[68:71], v[140:143], v[200:203], v[68:71]
	v_mfma_f32_16x16x32_bf16 v[108:111], v[132:135], v[208:211], v[108:111]
	v_mfma_f32_16x16x32_bf16 v[72:75], v[140:143], v[208:211], v[72:75]
	s_waitcnt lgkmcnt(0)
	v_mfma_f32_16x16x32_bf16 v[112:115], v[132:135], v[230:233], v[112:115]
	v_mfma_f32_16x16x32_bf16 v[76:79], v[140:143], v[230:233], v[76:79]
	s_barrier
	v_add_u32_e32 v140, 0x10000, v177
	ds_read_b128 v[128:131], v140
	ds_read_b128 v[132:135], v140 offset:1024
	ds_read_b128 v[136:139], v140 offset:2048
	ds_read_b128 v[140:143], v140 offset:3072
	s_add_u32 s48, s76, 0x84000
	s_addc_u32 s49, s77, 0
	s_mov_b32 m0, s97
	s_nop 0
	global_load_lds_dwordx4 v152, s[48:49]
	s_add_u32 s48, s76, 0x86000
	s_addc_u32 s49, s77, 0
	s_mov_b32 m0, s38
	s_nop 0
	global_load_lds_dwordx4 v152, s[48:49]
	s_add_u32 s48, s80, 0x84000
	s_addc_u32 s49, s81, 0
	s_mov_b32 m0, s34
	s_nop 0
	global_load_lds_dwordx4 v152, s[48:49]
	s_add_u32 s48, s80, 0x86000
	s_addc_u32 s49, s81, 0
	s_mov_b32 m0, s25
	s_nop 0
	global_load_lds_dwordx4 v152, s[48:49]
	s_waitcnt vmcnt(12)
	s_barrier
	v_mfma_f32_16x16x32_bf16 v[32:35], v[236:239], v[144:147], v[32:35]
	v_mfma_f32_16x16x32_bf16 v[0:3], v[244:247], v[144:147], v[0:3]
	v_mfma_f32_16x16x32_bf16 v[36:39], v[236:239], v[184:187], v[36:39]
	v_mfma_f32_16x16x32_bf16 v[4:7], v[244:247], v[184:187], v[4:7]
	v_mfma_f32_16x16x32_bf16 v[40:43], v[236:239], v[204:207], v[40:43]
	v_mfma_f32_16x16x32_bf16 v[8:11], v[244:247], v[204:207], v[8:11]
	v_mfma_f32_16x16x32_bf16 v[44:47], v[236:239], v[212:215], v[44:47]
	v_mfma_f32_16x16x32_bf16 v[12:15], v[244:247], v[212:215], v[12:15]
	v_mfma_f32_16x16x32_bf16 v[32:35], v[240:243], v[148:151], v[32:35]
	v_mfma_f32_16x16x32_bf16 v[0:3], v[248:251], v[148:151], v[0:3]
	v_mfma_f32_16x16x32_bf16 v[36:39], v[240:243], v[200:203], v[36:39]
	v_mfma_f32_16x16x32_bf16 v[4:7], v[248:251], v[200:203], v[4:7]
	v_mfma_f32_16x16x32_bf16 v[40:43], v[240:243], v[208:211], v[40:43]
	v_mfma_f32_16x16x32_bf16 v[8:11], v[248:251], v[208:211], v[8:11]
	v_mfma_f32_16x16x32_bf16 v[44:47], v[240:243], v[230:233], v[44:47]
	v_mfma_f32_16x16x32_bf16 v[12:15], v[248:251], v[230:233], v[12:15]
	s_add_i32 s71, s71, 2
	s_add_u32 s1, s1, 0x8000
	s_addc_u32 s9, s9, 0
	s_cmp_gt_u32 s71, 29
	s_mov_b64 s[76:77], s[78:79]
	s_barrier
	s_cbranch_scc1 .LBB0_741

; #define PG8_STAGE(bufoff, gbase, hoff, imm) do { _Pragma("unroll") for (int _i = 0; _i < 2; ++_i) { \
;         asm volatile("s_mov_b32 m0, %0\n\ts_nop 0\n\tglobal_load_lds_dwordx4 %1, %2" \
;             :: "s"(lds0 + (unsigned)((bufoff) + _i * 8192)), "v"(voff0), "s"((const char*)(gbase) + (size_t)(hoff) + (size_t)(_i * 8192)) : "memory"); } } while (0)
; #define PG8_LDA(dst, b, h) do { _Pragma("unroll") for (int m = 0; m < 4; ++m) _Pragma("unroll") for (int k = 0; k < 2; ++k) dst[m][k] = *(const LAS bf16x8*)(lds + PG8_SA(b, h) + aoff + m * 2048 + k * 1024); } while (0)
; #define PG8_LDB(dst, b, h) do { _Pragma("unroll") for (int n = 0; n < 2; ++n) _Pragma("unroll") for (int k = 0; k < 2; ++k) dst[n][k] = *(const LAS bf16x8*)(lds + PG8_SB(b, h) + boff + n * 2048 + k * 1024); } while (0)
; #define PG8_MMA(ai, bj, At, Bt) do { __builtin_amdgcn_s_setprio(1); _Pragma("unroll") for (int m = 0; m < 4; ++m) _Pragma("unroll") for (int n = 0; n < 2; ++n) _Pragma("unroll") for (int k = 0; k < 2; ++k) \
;         acc[ai][bj][m][n] = __builtin_amdgcn_mfma_f32_16x16x32_bf16(Bt[n][k], At[m][k], acc[ai][bj][m][n], 0, 0, 0); __builtin_amdgcn_s_setprio(0); } while (0)
; #define PG8_WAIT_L(n) asm volatile("s_waitcnt lgkmcnt(" #n ")" ::: "memory")
; #define PG8_BAR __builtin_amdgcn_s_barrier()
; #define PG8_SCHED __builtin_amdgcn_sched_barrier(0)
; template <class Epi>
; __device__ __forceinline__ void gemm_phase(LAS unsigned char* lds, const Gemm g, const StaticOrder& S, const Epi& E) {
;     ...
;             const char* aT = cA + (size_t)t * KS;
;             const char* a2 = last ? nA : aT + 2 * KS; const char* b2 = last ? nB : cB + (size_t)(t + 2) * KS;
;             PG8_LDB(B0, 0, 0); PG8_SCHED; PG8_LDA(At, 0, 0); PG8_STAGE(PG8_SA(1, 1), aT + KS, hA, 0);
;             PG8_WAIT_L(8); PG8_BAR; PG8_WAIT_L(0); PG8_MMA(0, 0, At, B0); PG8_BAR; PG8_SCHED;
;             PG8_LDB(B1, 0, 1); PG8_STAGE(PG8_SB(0, 0), b2, 0, 0);
;             PG8_BAR; PG8_WAIT_L(0); PG8_MMA(0, 1, At, B1); PG8_BAR;
;             PG8_LDA(At, 0, 1); PG8_STAGE(PG8_SA(0, 0), a2, 0, 0);
;             PG8_BAR; PG8_WAIT_L(0); PG8_MMA(1, 0, At, B0); PG8_BAR; PG8_SCHED;
.LBB0_860:
	s_add_u32 s58, s56, 0x8000
	v_add_u32_e32 v132, 0x10000, v236
	s_addc_u32 s59, s57, 0
	ds_read_b128 v[120:123], v132
	ds_read_b128 v[124:127], v132 offset:1024
	ds_read_b128 v[128:131], v132 offset:2048
	ds_read_b128 v[132:135], v132 offset:3072
	s_add_u32 s48, s56, 0x164000
	s_addc_u32 s49, s57, 0
	s_add_u32 s60, s56, 0x166000
	s_addc_u32 s61, s57, 0
	s_cmpk_eq_i32 s69, 0x54
	s_cselect_b32 s57, s7, s59
	s_cselect_b32 s56, s6, s58
	ds_read_b128 v[136:139], v237
	ds_read_b128 v[140:143], v237 offset:1024
	ds_read_b128 v[152:155], v237 offset:2048
	ds_read_b128 v[156:159], v237 offset:3072
	ds_read_b128 v[160:163], v237 offset:4096
	ds_read_b128 v[164:167], v237 offset:5120
	ds_read_b128 v[168:171], v237 offset:6144
	ds_read_b128 v[172:175], v237 offset:7168
	s_mov_b32 m0, s65
	s_nop 0
	global_load_lds_dwordx4 v188, s[48:49]
	s_mov_b32 m0, s66
	s_nop 0
	global_load_lds_dwordx4 v188, s[60:61]
	s_waitcnt lgkmcnt(8)
	s_waitcnt vmcnt(10)
	s_barrier
	s_waitcnt lgkmcnt(7)
	v_mfma_f32_16x16x32_bf16 v[148:151], v[120:123], v[136:139], v[148:151]
	v_mfma_f32_16x16x32_bf16 v[144:147], v[128:131], v[136:139], v[144:147]
	s_waitcnt lgkmcnt(5)
	v_mfma_f32_16x16x32_bf16 v[108:111], v[120:123], v[152:155], v[108:111]
	v_mfma_f32_16x16x32_bf16 v[104:107], v[128:131], v[152:155], v[104:107]
	s_waitcnt lgkmcnt(3)
	v_mfma_f32_16x16x32_bf16 v[92:95], v[120:123], v[160:163], v[92:95]
	v_mfma_f32_16x16x32_bf16 v[88:91], v[128:131], v[160:163], v[88:91]
	s_waitcnt lgkmcnt(1)
	v_mfma_f32_16x16x32_bf16 v[76:79], v[120:123], v[168:171], v[76:79]
	v_mfma_f32_16x16x32_bf16 v[72:75], v[128:131], v[168:171], v[72:75]
	v_mfma_f32_16x16x32_bf16 v[148:151], v[124:127], v[140:143], v[148:151]
	v_mfma_f32_16x16x32_bf16 v[144:147], v[132:135], v[140:143], v[144:147]
	v_mfma_f32_16x16x32_bf16 v[108:111], v[124:127], v[156:159], v[108:111]
	v_mfma_f32_16x16x32_bf16 v[104:107], v[132:135], v[156:159], v[104:107]
	v_mfma_f32_16x16x32_bf16 v[92:95], v[124:127], v[164:167], v[92:95]
	v_mfma_f32_16x16x32_bf16 v[88:91], v[132:135], v[164:167], v[88:91]
	s_waitcnt lgkmcnt(0)
	v_mfma_f32_16x16x32_bf16 v[76:79], v[124:127], v[172:175], v[76:79]
	v_mfma_f32_16x16x32_bf16 v[72:75], v[132:135], v[172:175], v[72:75]
	s_barrier
	v_add_u32_e32 v200, 0x14000, v236
	ds_read_b128 v[176:179], v200
	ds_read_b128 v[180:183], v200 offset:1024
	ds_read_b128 v[184:187], v200 offset:2048
	ds_read_b128 v[200:203], v200 offset:3072
	s_cselect_b32 s60, s8, s0
	s_cselect_b32 s61, s9, s1
	s_mov_b32 m0, s26
	s_nop 0
	global_load_lds_dwordx4 v188, s[60:61]
	s_add_u32 s48, s60, 0x2000
	s_addc_u32 s49, s61, 0
	s_mov_b32 m0, s27
	s_nop 0
	global_load_lds_dwordx4 v188, s[48:49]
	s_waitcnt vmcnt(10)
	s_barrier
	s_waitcnt lgkmcnt(3)
	v_mfma_f32_16x16x32_bf16 v[116:119], v[176:179], v[136:139], v[116:119]
	s_waitcnt lgkmcnt(1)
	v_mfma_f32_16x16x32_bf16 v[112:115], v[184:187], v[136:139], v[112:115]
	v_mfma_f32_16x16x32_bf16 v[100:103], v[176:179], v[152:155], v[100:103]
	v_mfma_f32_16x16x32_bf16 v[96:99], v[184:187], v[152:155], v[96:99]
	v_mfma_f32_16x16x32_bf16 v[84:87], v[176:179], v[160:163], v[84:87]
	v_mfma_f32_16x16x32_bf16 v[80:83], v[184:187], v[160:163], v[80:83]
	v_mfma_f32_16x16x32_bf16 v[68:71], v[176:179], v[168:171], v[68:71]
	v_mfma_f32_16x16x32_bf16 v[64:67], v[184:187], v[168:171], v[64:67]
	v_mfma_f32_16x16x32_bf16 v[116:119], v[180:183], v[140:143], v[116:119]
	s_waitcnt lgkmcnt(0)
	v_mfma_f32_16x16x32_bf16 v[112:115], v[200:203], v[140:143], v[112:115]
	v_mfma_f32_16x16x32_bf16 v[100:103], v[180:183], v[156:159], v[100:103]
	v_mfma_f32_16x16x32_bf16 v[96:99], v[200:203], v[156:159], v[96:99]
	v_mfma_f32_16x16x32_bf16 v[84:87], v[180:183], v[164:167], v[84:87]
	v_mfma_f32_16x16x32_bf16 v[80:83], v[200:203], v[164:167], v[80:83]
	v_mfma_f32_16x16x32_bf16 v[68:71], v[180:183], v[172:175], v[68:71]
	v_mfma_f32_16x16x32_bf16 v[64:67], v[200:203], v[172:175], v[64:67]
	s_barrier
	ds_read_b128 v[136:139], v237 offset:16384
	ds_read_b128 v[140:143], v237 offset:17408
	ds_read_b128 v[152:155], v237 offset:18432
	ds_read_b128 v[156:159], v237 offset:19456
	ds_read_b128 v[160:163], v237 offset:20480
	ds_read_b128 v[164:167], v237 offset:21504
	ds_read_b128 v[168:171], v237 offset:22528
	ds_read_b128 v[172:175], v237 offset:23552
	s_mov_b32 m0, s25
	s_nop 0
	global_load_lds_dwordx4 v188, s[56:57]
	s_add_u32 s48, s56, 0x2000
	s_addc_u32 s49, s57, 0
	s_mov_b32 m0, s28
	s_nop 0
	global_load_lds_dwordx4 v188, s[48:49]
	s_barrier
	s_waitcnt lgkmcnt(7)
	v_mfma_f32_16x16x32_bf16 v[60:63], v[120:123], v[136:139], v[60:63]
	v_mfma_f32_16x16x32_bf16 v[56:59], v[128:131], v[136:139], v[56:59]
	s_waitcnt lgkmcnt(5)
	v_mfma_f32_16x16x32_bf16 v[44:47], v[120:123], v[152:155], v[44:47]
	v_mfma_f32_16x16x32_bf16 v[40:43], v[128:131], v[152:155], v[40:43]
	s_waitcnt lgkmcnt(3)
	v_mfma_f32_16x16x32_bf16 v[28:31], v[120:123], v[160:163], v[28:31]
	v_mfma_f32_16x16x32_bf16 v[24:27], v[128:131], v[160:163], v[24:27]
	s_waitcnt lgkmcnt(1)
	v_mfma_f32_16x16x32_bf16 v[12:15], v[120:123], v[168:171], v[12:15]
	v_mfma_f32_16x16x32_bf16 v[8:11], v[128:131], v[168:171], v[8:11]
	v_mfma_f32_16x16x32_bf16 v[60:63], v[124:127], v[140:143], v[60:63]
	v_mfma_f32_16x16x32_bf16 v[56:59], v[132:135], v[140:143], v[56:59]
	v_mfma_f32_16x16x32_bf16 v[44:47], v[124:127], v[156:159], v[44:47]
	v_mfma_f32_16x16x32_bf16 v[40:43], v[132:135], v[156:159], v[40:43]
	v_mfma_f32_16x16x32_bf16 v[28:31], v[124:127], v[164:167], v[28:31]
	v_mfma_f32_16x16x32_bf16 v[24:27], v[132:135], v[164:167], v[24:27]
	s_waitcnt lgkmcnt(0)
	v_mfma_f32_16x16x32_bf16 v[12:15], v[124:127], v[172:175], v[12:15]
	v_mfma_f32_16x16x32_bf16 v[8:11], v[132:135], v[172:175], v[8:11]
	s_barrier
; #define PG8_STAGE(bufoff, gbase, hoff, imm) do { _Pragma("unroll") for (int _i = 0; _i < 2; ++_i) { \
;         asm volatile("s_mov_b32 m0, %0\n\ts_nop 0\n\tglobal_load_lds_dwordx4 %1, %2" \
;             :: "s"(lds0 + (unsigned)((bufoff) + _i * 8192)), "v"(voff0), "s"((const char*)(gbase) + (size_t)(hoff) + (size_t)(_i * 8192)) : "memory"); } } while (0)
; #define PG8_LDA(dst, b, h) do { _Pragma("unroll") for (int m = 0; m < 4; ++m) _Pragma("unroll") for (int k = 0; k < 2; ++k) dst[m][k] = *(const LAS bf16x8*)(lds + PG8_SA(b, h) + aoff + m * 2048 + k * 1024); } while (0)
; #define PG8_LDB(dst, b, h) do { _Pragma("unroll") for (int n = 0; n < 2; ++n) _Pragma("unroll") for (int k = 0; k < 2; ++k) dst[n][k] = *(const LAS bf16x8*)(lds + PG8_SB(b, h) + boff + n * 2048 + k * 1024); } while (0)
; #define PG8_MMA(ai, bj, At, Bt) do { __builtin_amdgcn_s_setprio(1); _Pragma("unroll") for (int m = 0; m < 4; ++m) _Pragma("unroll") for (int n = 0; n < 2; ++n) _Pragma("unroll") for (int k = 0; k < 2; ++k) \
;         acc[ai][bj][m][n] = __builtin_amdgcn_mfma_f32_16x16x32_bf16(Bt[n][k], At[m][k], acc[ai][bj][m][n], 0, 0, 0); __builtin_amdgcn_s_setprio(0); } while (0)
; #define PG8_WAIT_V(n) asm volatile("s_waitcnt vmcnt(" #n ")" ::: "memory")
; #define PG8_WAIT_L(n) asm volatile("s_waitcnt lgkmcnt(" #n ")" ::: "memory")
; #define PG8_BAR __builtin_amdgcn_s_barrier()
; #define PG8_SCHED __builtin_amdgcn_sched_barrier(0)
; template <class Epi>
; __device__ __forceinline__ void gemm_phase(LAS unsigned char* lds, const Gemm g, const StaticOrder& S, const Epi& E) {
;     ...
;             PG8_STAGE(PG8_SB(0, 1), b2, hB, 0);
;             PG8_WAIT_V(6); PG8_BAR; PG8_MMA(1, 1, At, B1); PG8_BAR;
;             PG8_LDB(B0, 1, 0); PG8_SCHED; PG8_LDA(At, 1, 0); PG8_STAGE(PG8_SA(0, 1), a2, hA, 0);
;             PG8_WAIT_L(8); PG8_BAR; PG8_WAIT_L(0); PG8_MMA(0, 0, At, B0); PG8_BAR; PG8_SCHED;
;             PG8_LDB(B1, 1, 1); PG8_STAGE(PG8_SB(1, 0), b2 + KS, 0, 0);
;             PG8_BAR; PG8_WAIT_L(0); PG8_MMA(0, 1, At, B1); PG8_BAR;
;             PG8_LDA(At, 1, 1); PG8_STAGE(PG8_SA(1, 0), a2 + KS, 0, 0);
	s_add_u32 s48, s60, 0x160000
	s_addc_u32 s49, s61, 0
	s_mov_b32 m0, s29
	s_nop 0
	global_load_lds_dwordx4 v188, s[48:49]
	s_add_u32 s48, s60, 0x162000
	s_addc_u32 s49, s61, 0
	s_mov_b32 m0, s30
	s_nop 0
	global_load_lds_dwordx4 v188, s[48:49]
	s_waitcnt vmcnt(10)
	s_barrier
	v_mfma_f32_16x16x32_bf16 v[52:55], v[176:179], v[136:139], v[52:55]
	v_mfma_f32_16x16x32_bf16 v[48:51], v[184:187], v[136:139], v[48:51]
	v_mfma_f32_16x16x32_bf16 v[36:39], v[176:179], v[152:155], v[36:39]
	v_mfma_f32_16x16x32_bf16 v[32:35], v[184:187], v[152:155], v[32:35]
	v_mfma_f32_16x16x32_bf16 v[20:23], v[176:179], v[160:163], v[20:23]
	v_mfma_f32_16x16x32_bf16 v[16:19], v[184:187], v[160:163], v[16:19]
	v_mfma_f32_16x16x32_bf16 v[4:7], v[176:179], v[168:171], v[4:7]
	v_mfma_f32_16x16x32_bf16 v[0:3], v[184:187], v[168:171], v[0:3]
	v_mfma_f32_16x16x32_bf16 v[52:55], v[180:183], v[140:143], v[52:55]
	v_mfma_f32_16x16x32_bf16 v[48:51], v[200:203], v[140:143], v[48:51]
	v_mfma_f32_16x16x32_bf16 v[36:39], v[180:183], v[156:159], v[36:39]
	v_mfma_f32_16x16x32_bf16 v[32:35], v[200:203], v[156:159], v[32:35]
	v_mfma_f32_16x16x32_bf16 v[20:23], v[180:183], v[164:167], v[20:23]
	v_mfma_f32_16x16x32_bf16 v[16:19], v[200:203], v[164:167], v[16:19]
	v_mfma_f32_16x16x32_bf16 v[4:7], v[180:183], v[172:175], v[4:7]
	v_mfma_f32_16x16x32_bf16 v[0:3], v[200:203], v[172:175], v[0:3]
	v_add_u32_e32 v132, 0x18000, v236
	s_barrier
	ds_read_b128 v[120:123], v132
	ds_read_b128 v[124:127], v132 offset:1024
	ds_read_b128 v[128:131], v132 offset:2048
	ds_read_b128 v[132:135], v132 offset:3072
	ds_read_b128 v[136:139], v237 offset:32768
	ds_read_b128 v[140:143], v237 offset:33792
	ds_read_b128 v[152:155], v237 offset:34816
	ds_read_b128 v[156:159], v237 offset:35840
	ds_read_b128 v[160:163], v237 offset:36864
	ds_read_b128 v[164:167], v237 offset:37888
	ds_read_b128 v[168:171], v237 offset:38912
	ds_read_b128 v[172:175], v237 offset:39936
	s_add_u32 s48, s56, 0x160000
	s_addc_u32 s49, s57, 0
	s_mov_b32 m0, s34
	s_nop 0
	global_load_lds_dwordx4 v188, s[48:49]
	s_add_u32 s48, s56, 0x162000
	s_addc_u32 s49, s57, 0
	s_mov_b32 m0, s37
	s_nop 0
	global_load_lds_dwordx4 v188, s[48:49]
	s_waitcnt lgkmcnt(8)
	s_waitcnt vmcnt(10)
	s_barrier
	s_waitcnt lgkmcnt(7)
	v_mfma_f32_16x16x32_bf16 v[148:151], v[120:123], v[136:139], v[148:151]
	v_mfma_f32_16x16x32_bf16 v[144:147], v[128:131], v[136:139], v[144:147]
	s_waitcnt lgkmcnt(5)
	v_mfma_f32_16x16x32_bf16 v[108:111], v[120:123], v[152:155], v[108:111]
	v_mfma_f32_16x16x32_bf16 v[104:107], v[128:131], v[152:155], v[104:107]
	s_waitcnt lgkmcnt(3)
	v_mfma_f32_16x16x32_bf16 v[92:95], v[120:123], v[160:163], v[92:95]
	v_mfma_f32_16x16x32_bf16 v[88:91], v[128:131], v[160:163], v[88:91]
	s_waitcnt lgkmcnt(1)
	v_mfma_f32_16x16x32_bf16 v[76:79], v[120:123], v[168:171], v[76:79]
	v_mfma_f32_16x16x32_bf16 v[72:75], v[128:131], v[168:171], v[72:75]
	v_mfma_f32_16x16x32_bf16 v[148:151], v[124:127], v[140:143], v[148:151]
	v_mfma_f32_16x16x32_bf16 v[144:147], v[132:135], v[140:143], v[144:147]
	v_mfma_f32_16x16x32_bf16 v[108:111], v[124:127], v[156:159], v[108:111]
	v_mfma_f32_16x16x32_bf16 v[104:107], v[132:135], v[156:159], v[104:107]
	v_mfma_f32_16x16x32_bf16 v[92:95], v[124:127], v[164:167], v[92:95]
	v_mfma_f32_16x16x32_bf16 v[88:91], v[132:135], v[164:167], v[88:91]
	s_waitcnt lgkmcnt(0)
	v_mfma_f32_16x16x32_bf16 v[76:79], v[124:127], v[172:175], v[76:79]
	v_mfma_f32_16x16x32_bf16 v[72:75], v[132:135], v[172:175], v[72:75]
	s_barrier
	v_add_u32_e32 v200, 0x1c000, v236
	ds_read_b128 v[176:179], v200
	ds_read_b128 v[180:183], v200 offset:1024
	ds_read_b128 v[184:187], v200 offset:2048
	ds_read_b128 v[200:203], v200 offset:3072
	s_add_u32 s48, s60, 0x4000
	s_addc_u32 s49, s61, 0
	s_mov_b32 m0, s41
	s_nop 0
	global_load_lds_dwordx4 v188, s[48:49]
	s_add_u32 s48, s60, 0x6000
	s_addc_u32 s49, s61, 0
	s_mov_b32 m0, s42
	s_nop 0
	global_load_lds_dwordx4 v188, s[48:49]
	s_waitcnt vmcnt(10)
	s_barrier
	s_waitcnt lgkmcnt(3)
	v_mfma_f32_16x16x32_bf16 v[116:119], v[176:179], v[136:139], v[116:119]
	s_waitcnt lgkmcnt(1)
	v_mfma_f32_16x16x32_bf16 v[112:115], v[184:187], v[136:139], v[112:115]
	v_mfma_f32_16x16x32_bf16 v[100:103], v[176:179], v[152:155], v[100:103]
	v_mfma_f32_16x16x32_bf16 v[96:99], v[184:187], v[152:155], v[96:99]
	v_mfma_f32_16x16x32_bf16 v[84:87], v[176:179], v[160:163], v[84:87]
	v_mfma_f32_16x16x32_bf16 v[80:83], v[184:187], v[160:163], v[80:83]
	v_mfma_f32_16x16x32_bf16 v[68:71], v[176:179], v[168:171], v[68:71]
	v_mfma_f32_16x16x32_bf16 v[64:67], v[184:187], v[168:171], v[64:67]
	v_mfma_f32_16x16x32_bf16 v[116:119], v[180:183], v[140:143], v[116:119]
	s_waitcnt lgkmcnt(0)
	v_mfma_f32_16x16x32_bf16 v[112:115], v[200:203], v[140:143], v[112:115]
	v_mfma_f32_16x16x32_bf16 v[100:103], v[180:183], v[156:159], v[100:103]
	v_mfma_f32_16x16x32_bf16 v[96:99], v[200:203], v[156:159], v[96:99]
	v_mfma_f32_16x16x32_bf16 v[84:87], v[180:183], v[164:167], v[84:87]
	v_mfma_f32_16x16x32_bf16 v[80:83], v[200:203], v[164:167], v[80:83]
	v_mfma_f32_16x16x32_bf16 v[68:71], v[180:183], v[172:175], v[68:71]
	v_mfma_f32_16x16x32_bf16 v[64:67], v[200:203], v[172:175], v[64:67]
	s_barrier
	ds_read_b128 v[136:139], v237 offset:49152
	ds_read_b128 v[140:143], v237 offset:50176
	ds_read_b128 v[152:155], v237 offset:51200
	ds_read_b128 v[156:159], v237 offset:52224
	ds_read_b128 v[160:163], v237 offset:53248
	ds_read_b128 v[164:167], v237 offset:54272
	ds_read_b128 v[168:171], v237 offset:55296
	ds_read_b128 v[172:175], v237 offset:56320
	s_add_u32 s48, s56, 0x4000
	s_addc_u32 s49, s57, 0
	s_mov_b32 m0, s43
	s_nop 0
	global_load_lds_dwordx4 v188, s[48:49]
	s_add_u32 s48, s56, 0x6000
	s_addc_u32 s49, s57, 0
	s_mov_b32 m0, s62
	s_nop 0
	global_load_lds_dwordx4 v188, s[48:49]
	s_barrier
; template <class Epi>
; __device__ __forceinline__ void gemm_phase(LAS unsigned char* lds, const Gemm g, const StaticOrder& S, const Epi& E) {
;     ...
;             PG8_BAR; PG8_WAIT_L(0); PG8_MMA(1, 0, At, B0); PG8_BAR; PG8_SCHED;
;             PG8_STAGE(PG8_SB(1, 1), b2 + KS, hB, 0);
;             PG8_WAIT_V(6); PG8_BAR; PG8_MMA(1, 1, At, B1); PG8_BAR;
;     __device__ __forceinline__ void operator()(f32x4 (&acc)[2][2][4][2], const Unit& u, int wr, int wc, int fr, int fq, LAS unsigned char*) const {
;         const int b = u.pm >> 6;
;         const int col0 = u.pn * BM + wc * 32 + 8 * fq;
;         const size_t off0 = (size_t)(u.pm * BM + wr * 64 + fr) * D + col0;
;         f32x4 sc[2][2];
; #pragma unroll
;         for (int bj = 0; bj < 2; ++bj)
; #pragma unroll
;             for (int n = 0; n < 2; ++n) { f32x4 gt = *(const f32x4*)(gate + (size_t)b * MODW + col0 + bj * HALF + n * 4); sc[bj][n] = gt + 1.0f;
;                 if (cs) sc[bj][n] *= *(const f32x4*)(cs + col0 + bj * HALF + n * 4); }
;         if (IN_F32) {
; #pragma unroll
;             for (int ai = 0; ai < 2; ++ai) {
;                 f32x4 r[4][2][2];
; #pragma unroll
;                 for (int m = 0; m < 4; ++m)
; #pragma unroll
;                     for (int bj = 0; bj < 2; ++bj)
; #pragma unroll
;                         for (int n = 0; n < 2; ++n) r[m][bj][n] = *(const f32x4*)((const float*)in + off0 + (size_t)(ai * HALF + m * 16) * D + bj * HALF + n * 4);
; #pragma unroll
;                 for (int m = 0; m < 4; ++m)
; #pragma unroll
;                     for (int bj = 0; bj < 2; ++bj) { const f32x4 r0 = r[m][bj][0] + sc[bj][0] * acc[ai][bj][m][0], r1 = r[m][bj][1] + sc[bj][1] * acc[ai][bj][m][1];
;                         u32x4 w; w.x = cvt_pk_bf16(r0[0], r0[1]); w.y = cvt_pk_bf16(r0[2], r0[3]); w.z = cvt_pk_bf16(r1[0], r1[1]); w.w = cvt_pk_bf16(r1[2], r1[3]);
;                         *(u32x4*)(out + off0 + (size_t)(ai * HALF + m * 16) * D + bj * HALF) = w; }
;                 asm volatile("" ::: "memory");
;             }
;         } else {
;             u32x4 xb[2][4][2];
; #pragma unroll
;             for (int ai = 0; ai < 2; ++ai)
; #pragma unroll
;                 for (int m = 0; m < 4; ++m)
; #pragma unroll
;                     for (int bj = 0; bj < 2; ++bj) xb[ai][m][bj] = *(const u32x4*)((const bf16_t*)in + off0 + (size_t)(ai * HALF + m * 16) * D + bj * HALF);
	s_waitcnt lgkmcnt(7)
	v_mfma_f32_16x16x32_bf16 v[60:63], v[120:123], v[136:139], v[60:63]
	v_mfma_f32_16x16x32_bf16 v[56:59], v[128:131], v[136:139], v[56:59]
	s_waitcnt lgkmcnt(5)
	v_mfma_f32_16x16x32_bf16 v[44:47], v[120:123], v[152:155], v[44:47]
	v_mfma_f32_16x16x32_bf16 v[40:43], v[128:131], v[152:155], v[40:43]
	s_waitcnt lgkmcnt(3)
	v_mfma_f32_16x16x32_bf16 v[28:31], v[120:123], v[160:163], v[28:31]
	v_mfma_f32_16x16x32_bf16 v[24:27], v[128:131], v[160:163], v[24:27]
	s_waitcnt lgkmcnt(1)
	v_mfma_f32_16x16x32_bf16 v[12:15], v[120:123], v[168:171], v[12:15]
	v_mfma_f32_16x16x32_bf16 v[8:11], v[128:131], v[168:171], v[8:11]
	v_mfma_f32_16x16x32_bf16 v[60:63], v[124:127], v[140:143], v[60:63]
	v_mfma_f32_16x16x32_bf16 v[56:59], v[132:135], v[140:143], v[56:59]
	v_mfma_f32_16x16x32_bf16 v[44:47], v[124:127], v[156:159], v[44:47]
	v_mfma_f32_16x16x32_bf16 v[40:43], v[132:135], v[156:159], v[40:43]
	v_mfma_f32_16x16x32_bf16 v[28:31], v[124:127], v[164:167], v[28:31]
	v_mfma_f32_16x16x32_bf16 v[24:27], v[132:135], v[164:167], v[24:27]
	s_waitcnt lgkmcnt(0)
	v_mfma_f32_16x16x32_bf16 v[12:15], v[124:127], v[172:175], v[12:15]
	v_mfma_f32_16x16x32_bf16 v[8:11], v[132:135], v[172:175], v[8:11]
	s_barrier
	s_add_u32 s48, s60, 0x164000
	s_addc_u32 s49, s61, 0
	s_mov_b32 m0, s63
	s_nop 0
	global_load_lds_dwordx4 v188, s[48:49]
	s_add_u32 s48, s60, 0x166000
	s_addc_u32 s49, s61, 0
	s_mov_b32 m0, s64
	s_nop 0
	global_load_lds_dwordx4 v188, s[48:49]
	s_waitcnt vmcnt(10)
	s_barrier
	v_mfma_f32_16x16x32_bf16 v[52:55], v[176:179], v[136:139], v[52:55]
	v_mfma_f32_16x16x32_bf16 v[48:51], v[184:187], v[136:139], v[48:51]
	v_mfma_f32_16x16x32_bf16 v[36:39], v[176:179], v[152:155], v[36:39]
	v_mfma_f32_16x16x32_bf16 v[32:35], v[184:187], v[152:155], v[32:35]
	v_mfma_f32_16x16x32_bf16 v[20:23], v[176:179], v[160:163], v[20:23]
	v_mfma_f32_16x16x32_bf16 v[16:19], v[184:187], v[160:163], v[16:19]
	v_mfma_f32_16x16x32_bf16 v[4:7], v[176:179], v[168:171], v[4:7]
	v_mfma_f32_16x16x32_bf16 v[0:3], v[184:187], v[168:171], v[0:3]
	v_mfma_f32_16x16x32_bf16 v[52:55], v[180:183], v[140:143], v[52:55]
	v_mfma_f32_16x16x32_bf16 v[48:51], v[200:203], v[140:143], v[48:51]
	v_mfma_f32_16x16x32_bf16 v[36:39], v[180:183], v[156:159], v[36:39]
	v_mfma_f32_16x16x32_bf16 v[32:35], v[200:203], v[156:159], v[32:35]
	v_mfma_f32_16x16x32_bf16 v[20:23], v[180:183], v[164:167], v[20:23]
	v_mfma_f32_16x16x32_bf16 v[16:19], v[200:203], v[164:167], v[16:19]
	v_mfma_f32_16x16x32_bf16 v[4:7], v[180:183], v[172:175], v[4:7]
	v_mfma_f32_16x16x32_bf16 v[0:3], v[200:203], v[172:175], v[0:3]
	s_add_i32 s69, s69, 2
	s_add_u32 s0, s0, 0x8000
	s_addc_u32 s1, s1, 0
	s_cmpk_gt_u32 s69, 0x55
	s_mov_b64 s[56:57], s[58:59]
	s_barrier
	s_cbranch_scc0 .LBB0_860
	s_ashr_i32 s0, s50, 6
	s_mul_hi_i32 s1, s0, 0xc000
	s_mul_i32 s0, s0, 0xc000
	v_lshl_or_b32 v128, s51, 8, v234
	s_add_u32 s0, s39, s0
	v_ashrrev_i32_e32 v129, 31, v128
	s_addc_u32 s1, s40, s1
	v_lshl_add_u64 v[130:131], v[128:129], 2, s[0:1]
	global_load_dwordx4 v[120:123], v[130:131], off offset:16
	global_load_dwordx4 v[124:127], v[130:131], off
	s_mov_b32 s51, s67
	s_mov_b64 s[58:59], s[8:9]
	s_mov_b64 s[56:57], s[6:7]
	s_waitcnt vmcnt(1)
	v_pk_add_f32 v[210:211], v[122:123], 1.0 op_sel_hi:[1,0]
	s_waitcnt vmcnt(0)
	v_pk_add_f32 v[214:215], v[126:127], 1.0 op_sel_hi:[1,0]
	v_pk_add_f32 v[212:213], v[124:125], 1.0 op_sel_hi:[1,0]
	v_pk_add_f32 v[208:209], v[120:121], 1.0 op_sel_hi:[1,0]
	global_load_dwordx4 v[120:123], v[130:131], off offset:528
	global_load_dwordx4 v[124:127], v[130:131], off offset:512
	s_waitcnt vmcnt(1)
	v_pk_add_f32 v[200:201], v[120:121], 1.0 op_sel_hi:[1,0]
	v_lshl_add_u32 v120, s50, 8, v233
	v_ashrrev_i32_e32 v121, 31, v120
	v_lshlrev_b64 v[120:121], 11, v[120:121]
	v_lshl_add_u64 v[120:121], v[120:121], 0, v[128:129]
	v_lshlrev_b64 v[216:217], 1, v[120:121]
	v_lshl_add_u64 v[120:121], s[52:53], 0, v[216:217]
	global_load_dwordx4 v[238:241], v[120:121], off
	global_load_dwordx4 v[184:187], v[120:121], off offset:256
	v_pk_add_f32 v[202:203], v[122:123], 1.0 op_sel_hi:[1,0]
	v_add_co_u32_e32 v122, vcc, s45, v120
	s_waitcnt vmcnt(2)
	v_pk_add_f32 v[206:207], v[126:127], 1.0 op_sel_hi:[1,0]
	v_addc_co_u32_e32 v123, vcc, 0, v121, vcc
	global_load_dwordx4 v[180:183], v[122:123], off
	global_load_dwordx4 v[176:179], v[122:123], off offset:256
	v_add_co_u32_e32 v122, vcc, s36, v120
	v_pk_add_f32 v[204:205], v[124:125], 1.0 op_sel_hi:[1,0]
	s_nop 0
	v_addc_co_u32_e32 v123, vcc, 0, v121, vcc
	global_load_dwordx4 v[172:175], v[122:123], off
	global_load_dwordx4 v[168:171], v[122:123], off offset:256
	v_add_co_u32_e32 v122, vcc, s23, v120
	s_mov_b32 s50, s68
	s_nop 0
	v_addc_co_u32_e32 v123, vcc, 0, v121, vcc
	global_load_dwordx4 v[164:167], v[122:123], off
	global_load_dwordx4 v[160:163], v[122:123], off offset:256
	v_add_co_u32_e32 v122, vcc, s93, v120
	s_waitcnt vmcnt(7)
; __device__ __forceinline__ unsigned cvt_pk_bf16(float lo, float hi) { unsigned r; asm volatile("v_cvt_pk_bf16_f32 %0, %1, %2" : "=v"(r) : "v"(lo), "v"(hi)); return r; }
;     __device__ __forceinline__ void operator()(f32x4 (&acc)[2][2][4][2], const Unit& u, int wr, int wc, int fr, int fq, LAS unsigned char*) const {
;     ...
; #pragma unroll
;             for (int ai = 0; ai < 2; ++ai)
; #pragma unroll
;                 for (int m = 0; m < 4; ++m)
; #pragma unroll
;                     for (int bj = 0; bj < 2; ++bj) { const u32x4 x = xb[ai][m][bj];
;                         f32x4 r0 = (f32x4){__uint_as_float(x.x << 16), __uint_as_float(x.x & 0xffff0000u), __uint_as_float(x.y << 16), __uint_as_float(x.y & 0xffff0000u)};
;                         f32x4 r1 = (f32x4){__uint_as_float(x.z << 16), __uint_as_float(x.z & 0xffff0000u), __uint_as_float(x.w << 16), __uint_as_float(x.w & 0xffff0000u)};
;                         r0 += sc[bj][0] * acc[ai][bj][m][0]; r1 += sc[bj][1] * acc[ai][bj][m][1];
;                         u32x4 w; w.x = cvt_pk_bf16(r0[0], r0[1]); w.y = cvt_pk_bf16(r0[2], r0[3]); w.z = cvt_pk_bf16(r1[0], r1[1]); w.w = cvt_pk_bf16(r1[2], r1[3]);
;                         *(u32x4*)(out + off0 + (size_t)(ai * HALF + m * 16) * D + bj * HALF) = w; }
	v_lshlrev_b32_e32 v230, 16, v238
	v_addc_co_u32_e32 v123, vcc, 0, v121, vcc
	global_load_dwordx4 v[156:159], v[122:123], off
	global_load_dwordx4 v[152:155], v[122:123], off offset:256
	v_add_co_u32_e32 v122, vcc, s33, v120
	v_and_b32_e32 v231, 0xffff0000, v238
	s_nop 0
	v_addc_co_u32_e32 v123, vcc, 0, v121, vcc
	global_load_dwordx4 v[140:143], v[122:123], off
	global_load_dwordx4 v[136:139], v[122:123], off offset:256
	v_add_co_u32_e32 v122, vcc, s18, v120
	v_lshlrev_b32_e32 v242, 16, v240
	s_nop 0
	v_addc_co_u32_e32 v123, vcc, 0, v121, vcc
	global_load_dwordx4 v[132:135], v[122:123], off
	global_load_dwordx4 v[128:131], v[122:123], off offset:256
	v_add_co_u32_e32 v120, vcc, s19, v120
	v_and_b32_e32 v243, 0xffff0000, v240
	s_nop 0
	v_addc_co_u32_e32 v121, vcc, 0, v121, vcc
	global_load_dwordx4 v[124:127], v[120:121], off
	s_nop 0
	global_load_dwordx4 v[120:123], v[120:121], off offset:256
	v_lshlrev_b32_e32 v238, 16, v239
	v_and_b32_e32 v239, 0xffff0000, v239
	v_lshlrev_b32_e32 v240, 16, v241
	v_and_b32_e32 v241, 0xffff0000, v241
	v_pk_fma_f32 v[148:149], v[148:149], v[212:213], v[230:231]
	v_pk_fma_f32 v[144:145], v[144:145], v[208:209], v[242:243]
	v_pk_fma_f32 v[150:151], v[150:151], v[214:215], v[238:239]
	v_pk_fma_f32 v[230:231], v[146:147], v[210:211], v[240:241]
	v_cvt_pk_bf16_f32 v146, v148, v149
	v_cvt_pk_bf16_f32 v147, v150, v151
	v_cvt_pk_bf16_f32 v148, v144, v145
	v_lshl_add_u64 v[144:145], s[54:55], 0, v[216:217]
	v_cvt_pk_bf16_f32 v149, v230, v231
	global_store_dwordx4 v[144:145], v[146:149], off
	s_waitcnt vmcnt(15)
	v_lshlrev_b32_e32 v150, 16, v186
	v_and_b32_e32 v151, 0xffff0000, v186
	v_lshlrev_b32_e32 v146, 16, v184
	v_and_b32_e32 v147, 0xffff0000, v184
	v_lshlrev_b32_e32 v148, 16, v185
	v_and_b32_e32 v149, 0xffff0000, v185
	v_lshlrev_b32_e32 v184, 16, v187
	v_and_b32_e32 v185, 0xffff0000, v187
	v_pk_fma_f32 v[118:119], v[118:119], v[206:207], v[148:149]
	v_pk_fma_f32 v[116:117], v[116:117], v[204:205], v[146:147]
	v_pk_fma_f32 v[146:147], v[114:115], v[202:203], v[184:185]
	v_pk_fma_f32 v[114:115], v[112:113], v[200:201], v[150:151]
	v_cvt_pk_bf16_f32 v112, v116, v117
	v_cvt_pk_bf16_f32 v113, v118, v119
	s_waitcnt vmcnt(14)
	v_lshlrev_b32_e32 v116, 16, v182
	v_cvt_pk_bf16_f32 v114, v114, v115
	v_cvt_pk_bf16_f32 v115, v146, v147
	global_store_dwordx4 v[144:145], v[112:115], off offset:256
	v_and_b32_e32 v117, 0xffff0000, v182
	v_lshlrev_b32_e32 v118, 16, v183
	v_lshlrev_b32_e32 v112, 16, v180
	v_and_b32_e32 v113, 0xffff0000, v180
	v_and_b32_e32 v119, 0xffff0000, v183
	v_pk_fma_f32 v[108:109], v[108:109], v[212:213], v[112:113]
	v_lshlrev_b32_e32 v114, 16, v181
	v_and_b32_e32 v115, 0xffff0000, v181
	v_pk_fma_f32 v[112:113], v[106:107], v[210:211], v[118:119]
	v_pk_fma_f32 v[106:107], v[104:105], v[208:209], v[116:117]
	v_cvt_pk_bf16_f32 v104, v108, v109
	v_add_co_u32_e32 v108, vcc, s45, v144
	v_pk_fma_f32 v[110:111], v[110:111], v[214:215], v[114:115]
	s_nop 0
	v_addc_co_u32_e32 v109, vcc, 0, v145, vcc
	v_cvt_pk_bf16_f32 v105, v110, v111
	v_cvt_pk_bf16_f32 v106, v106, v107
	v_cvt_pk_bf16_f32 v107, v112, v113
	global_store_dwordx4 v[108:109], v[104:107], off
	s_waitcnt vmcnt(15)
	v_lshlrev_b32_e32 v110, 16, v178
	v_and_b32_e32 v111, 0xffff0000, v178
	v_lshlrev_b32_e32 v104, 16, v176
	v_and_b32_e32 v105, 0xffff0000, v176
	v_lshlrev_b32_e32 v106, 16, v177
	v_and_b32_e32 v107, 0xffff0000, v177
	v_lshlrev_b32_e32 v112, 16, v179
	v_and_b32_e32 v113, 0xffff0000, v179
	v_pk_fma_f32 v[102:103], v[102:103], v[206:207], v[106:107]
	v_pk_fma_f32 v[100:101], v[100:101], v[204:205], v[104:105]
	v_pk_fma_f32 v[104:105], v[98:99], v[202:203], v[112:113]
	v_pk_fma_f32 v[98:99], v[96:97], v[200:201], v[110:111]
	v_cvt_pk_bf16_f32 v96, v100, v101
	v_cvt_pk_bf16_f32 v97, v102, v103
	s_waitcnt vmcnt(14)
	v_lshlrev_b32_e32 v100, 16, v174
	v_cvt_pk_bf16_f32 v98, v98, v99
	v_cvt_pk_bf16_f32 v99, v104, v105
	global_store_dwordx4 v[108:109], v[96:99], off offset:256
	v_and_b32_e32 v101, 0xffff0000, v174
	v_lshlrev_b32_e32 v102, 16, v175
	v_lshlrev_b32_e32 v96, 16, v172
	v_and_b32_e32 v97, 0xffff0000, v172
	v_and_b32_e32 v103, 0xffff0000, v175
	v_pk_fma_f32 v[92:93], v[92:93], v[212:213], v[96:97]
	v_lshlrev_b32_e32 v98, 16, v173
	v_and_b32_e32 v99, 0xffff0000, v173
	v_pk_fma_f32 v[96:97], v[90:91], v[210:211], v[102:103]
	v_pk_fma_f32 v[90:91], v[88:89], v[208:209], v[100:101]
	v_cvt_pk_bf16_f32 v88, v92, v93
	v_add_co_u32_e32 v92, vcc, s36, v144
	v_pk_fma_f32 v[94:95], v[94:95], v[214:215], v[98:99]
	s_nop 0
	v_addc_co_u32_e32 v93, vcc, 0, v145, vcc
	v_cvt_pk_bf16_f32 v89, v94, v95
	v_cvt_pk_bf16_f32 v90, v90, v91
	v_cvt_pk_bf16_f32 v91, v96, v97
	global_store_dwordx4 v[92:93], v[88:91], off
	s_waitcnt vmcnt(15)
	v_lshlrev_b32_e32 v94, 16, v170
	v_and_b32_e32 v95, 0xffff0000, v170
	v_lshlrev_b32_e32 v88, 16, v168
	v_and_b32_e32 v89, 0xffff0000, v168
	v_lshlrev_b32_e32 v90, 16, v169
	v_and_b32_e32 v91, 0xffff0000, v169
	v_lshlrev_b32_e32 v96, 16, v171
	v_and_b32_e32 v97, 0xffff0000, v171
	v_pk_fma_f32 v[86:87], v[86:87], v[206:207], v[90:91]
	v_pk_fma_f32 v[84:85], v[84:85], v[204:205], v[88:89]
	v_pk_fma_f32 v[88:89], v[82:83], v[202:203], v[96:97]
	v_pk_fma_f32 v[82:83], v[80:81], v[200:201], v[94:95]
	v_cvt_pk_bf16_f32 v80, v84, v85
	v_cvt_pk_bf16_f32 v81, v86, v87
	s_waitcnt vmcnt(14)
; __device__ __forceinline__ unsigned cvt_pk_bf16(float lo, float hi) { unsigned r; asm volatile("v_cvt_pk_bf16_f32 %0, %1, %2" : "=v"(r) : "v"(lo), "v"(hi)); return r; }
;     __device__ __forceinline__ void operator()(f32x4 (&acc)[2][2][4][2], const Unit& u, int wr, int wc, int fr, int fq, LAS unsigned char*) const {
;     ...
; #pragma unroll
;             for (int ai = 0; ai < 2; ++ai)
; #pragma unroll
;                 for (int m = 0; m < 4; ++m)
; #pragma unroll
;                     for (int bj = 0; bj < 2; ++bj) { const u32x4 x = xb[ai][m][bj];
;                         f32x4 r0 = (f32x4){__uint_as_float(x.x << 16), __uint_as_float(x.x & 0xffff0000u), __uint_as_float(x.y << 16), __uint_as_float(x.y & 0xffff0000u)};
;                         f32x4 r1 = (f32x4){__uint_as_float(x.z << 16), __uint_as_float(x.z & 0xffff0000u), __uint_as_float(x.w << 16), __uint_as_float(x.w & 0xffff0000u)};
;                         r0 += sc[bj][0] * acc[ai][bj][m][0]; r1 += sc[bj][1] * acc[ai][bj][m][1];
;                         u32x4 w; w.x = cvt_pk_bf16(r0[0], r0[1]); w.y = cvt_pk_bf16(r0[2], r0[3]); w.z = cvt_pk_bf16(r1[0], r1[1]); w.w = cvt_pk_bf16(r1[2], r1[3]);
;                         *(u32x4*)(out + off0 + (size_t)(ai * HALF + m * 16) * D + bj * HALF) = w; }
	v_lshlrev_b32_e32 v84, 16, v166
	v_cvt_pk_bf16_f32 v82, v82, v83
	v_cvt_pk_bf16_f32 v83, v88, v89
	global_store_dwordx4 v[92:93], v[80:83], off offset:256
	v_and_b32_e32 v85, 0xffff0000, v166
	v_lshlrev_b32_e32 v86, 16, v167
	v_lshlrev_b32_e32 v80, 16, v164
	v_and_b32_e32 v81, 0xffff0000, v164
	v_and_b32_e32 v87, 0xffff0000, v167
	v_pk_fma_f32 v[76:77], v[76:77], v[212:213], v[80:81]
	v_lshlrev_b32_e32 v82, 16, v165
	v_and_b32_e32 v83, 0xffff0000, v165
	v_pk_fma_f32 v[80:81], v[74:75], v[210:211], v[86:87]
	v_pk_fma_f32 v[74:75], v[72:73], v[208:209], v[84:85]
	v_cvt_pk_bf16_f32 v72, v76, v77
	v_add_co_u32_e32 v76, vcc, s23, v144
	v_pk_fma_f32 v[78:79], v[78:79], v[214:215], v[82:83]
	s_nop 0
	v_addc_co_u32_e32 v77, vcc, 0, v145, vcc
	v_cvt_pk_bf16_f32 v73, v78, v79
	v_cvt_pk_bf16_f32 v74, v74, v75
	v_cvt_pk_bf16_f32 v75, v80, v81
	global_store_dwordx4 v[76:77], v[72:75], off
	s_waitcnt vmcnt(15)
	v_lshlrev_b32_e32 v78, 16, v162
	v_and_b32_e32 v79, 0xffff0000, v162
	v_lshlrev_b32_e32 v72, 16, v160
	v_and_b32_e32 v73, 0xffff0000, v160
	v_lshlrev_b32_e32 v74, 16, v161
	v_and_b32_e32 v75, 0xffff0000, v161
	v_lshlrev_b32_e32 v80, 16, v163
	v_and_b32_e32 v81, 0xffff0000, v163
	v_pk_fma_f32 v[70:71], v[70:71], v[206:207], v[74:75]
	v_pk_fma_f32 v[68:69], v[68:69], v[204:205], v[72:73]
	v_pk_fma_f32 v[72:73], v[66:67], v[202:203], v[80:81]
	v_pk_fma_f32 v[66:67], v[64:65], v[200:201], v[78:79]
	v_cvt_pk_bf16_f32 v64, v68, v69
	v_cvt_pk_bf16_f32 v65, v70, v71
	s_waitcnt vmcnt(14)
	v_lshlrev_b32_e32 v68, 16, v158
	v_cvt_pk_bf16_f32 v66, v66, v67
	v_cvt_pk_bf16_f32 v67, v72, v73
	global_store_dwordx4 v[76:77], v[64:67], off offset:256
	v_and_b32_e32 v69, 0xffff0000, v158
	v_lshlrev_b32_e32 v70, 16, v159
	v_lshlrev_b32_e32 v64, 16, v156
	v_and_b32_e32 v65, 0xffff0000, v156
	v_and_b32_e32 v71, 0xffff0000, v159
	v_pk_fma_f32 v[60:61], v[60:61], v[212:213], v[64:65]
	v_lshlrev_b32_e32 v66, 16, v157
	v_and_b32_e32 v67, 0xffff0000, v157
	v_pk_fma_f32 v[64:65], v[58:59], v[210:211], v[70:71]
	v_pk_fma_f32 v[58:59], v[56:57], v[208:209], v[68:69]
	v_cvt_pk_bf16_f32 v56, v60, v61
	v_add_co_u32_e32 v60, vcc, s93, v144
	v_pk_fma_f32 v[62:63], v[62:63], v[214:215], v[66:67]
	s_nop 0
	v_addc_co_u32_e32 v61, vcc, 0, v145, vcc
	v_cvt_pk_bf16_f32 v57, v62, v63
	v_cvt_pk_bf16_f32 v58, v58, v59
	v_cvt_pk_bf16_f32 v59, v64, v65
	global_store_dwordx4 v[60:61], v[56:59], off
	s_waitcnt vmcnt(15)
	v_lshlrev_b32_e32 v62, 16, v154
	v_and_b32_e32 v63, 0xffff0000, v154
	v_lshlrev_b32_e32 v56, 16, v152
	v_and_b32_e32 v57, 0xffff0000, v152
	v_lshlrev_b32_e32 v58, 16, v153
	v_and_b32_e32 v59, 0xffff0000, v153
	v_lshlrev_b32_e32 v64, 16, v155
	v_and_b32_e32 v65, 0xffff0000, v155
	v_pk_fma_f32 v[54:55], v[54:55], v[206:207], v[58:59]
	v_pk_fma_f32 v[52:53], v[52:53], v[204:205], v[56:57]
	v_pk_fma_f32 v[56:57], v[50:51], v[202:203], v[64:65]
	v_pk_fma_f32 v[50:51], v[48:49], v[200:201], v[62:63]
	v_cvt_pk_bf16_f32 v48, v52, v53
	v_cvt_pk_bf16_f32 v49, v54, v55
	s_waitcnt vmcnt(14)
	v_lshlrev_b32_e32 v52, 16, v142
	v_cvt_pk_bf16_f32 v50, v50, v51
	v_cvt_pk_bf16_f32 v51, v56, v57
	global_store_dwordx4 v[60:61], v[48:51], off offset:256
	v_and_b32_e32 v53, 0xffff0000, v142
	v_lshlrev_b32_e32 v54, 16, v143
	v_lshlrev_b32_e32 v48, 16, v140
	v_and_b32_e32 v49, 0xffff0000, v140
	v_and_b32_e32 v55, 0xffff0000, v143
	v_pk_fma_f32 v[44:45], v[44:45], v[212:213], v[48:49]
	v_lshlrev_b32_e32 v50, 16, v141
	v_and_b32_e32 v51, 0xffff0000, v141
	v_pk_fma_f32 v[48:49], v[42:43], v[210:211], v[54:55]
	v_pk_fma_f32 v[42:43], v[40:41], v[208:209], v[52:53]
	v_cvt_pk_bf16_f32 v40, v44, v45
	v_add_co_u32_e32 v44, vcc, s33, v144
	v_pk_fma_f32 v[46:47], v[46:47], v[214:215], v[50:51]
	s_nop 0
	v_addc_co_u32_e32 v45, vcc, 0, v145, vcc
	v_cvt_pk_bf16_f32 v41, v46, v47
	v_cvt_pk_bf16_f32 v42, v42, v43
	v_cvt_pk_bf16_f32 v43, v48, v49
	global_store_dwordx4 v[44:45], v[40:43], off
	s_waitcnt vmcnt(15)
; __device__ __forceinline__ unsigned cvt_pk_bf16(float lo, float hi) { unsigned r; asm volatile("v_cvt_pk_bf16_f32 %0, %1, %2" : "=v"(r) : "v"(lo), "v"(hi)); return r; }
; #define PG8_WAIT_V(n) asm volatile("s_waitcnt vmcnt(" #n ")" ::: "memory")
; #define PG8_BAR __builtin_amdgcn_s_barrier()
; template <class Epi>
; __device__ __forceinline__ void gemm_phase(LAS unsigned char* lds, const Gemm g, const StaticOrder& S, const Epi& E) {
;     ...
;         if (!has_next) break;
; #pragma unroll
;         for (int a = 0; a < 2; ++a)
; #pragma unroll
;             for (int b = 0; b < 2; ++b)
; #pragma unroll
;                 for (int m = 0; m < 4; ++m)
; #pragma unroll
;                     for (int n = 0; n < 2; ++n) acc[a][b][m][n] = (f32x4){0.f, 0.f, 0.f, 0.f};
;         cur = nxt; cA = nA; cB = nB; ++ui;
;     }
;     PG8_WAIT_V(0);
;     if (wr == 0) PG8_BAR;
;     PG8_BAR;
;     __device__ __forceinline__ void operator()(f32x4 (&acc)[2][2][4][2], const Unit& u, int wr, int wc, int fr, int fq, LAS unsigned char*) const {
;     ...
;                     for (int bj = 0; bj < 2; ++bj) { const u32x4 x = xb[ai][m][bj];
;                         f32x4 r0 = (f32x4){__uint_as_float(x.x << 16), __uint_as_float(x.x & 0xffff0000u), __uint_as_float(x.y << 16), __uint_as_float(x.y & 0xffff0000u)};
;                         f32x4 r1 = (f32x4){__uint_as_float(x.z << 16), __uint_as_float(x.z & 0xffff0000u), __uint_as_float(x.w << 16), __uint_as_float(x.w & 0xffff0000u)};
;                         r0 += sc[bj][0] * acc[ai][bj][m][0]; r1 += sc[bj][1] * acc[ai][bj][m][1];
;                         u32x4 w; w.x = cvt_pk_bf16(r0[0], r0[1]); w.y = cvt_pk_bf16(r0[2], r0[3]); w.z = cvt_pk_bf16(r1[0], r1[1]); w.w = cvt_pk_bf16(r1[2], r1[3]);
;                         *(u32x4*)(out + off0 + (size_t)(ai * HALF + m * 16) * D + bj * HALF) = w; }
	v_lshlrev_b32_e32 v46, 16, v138
	v_and_b32_e32 v47, 0xffff0000, v138
	v_lshlrev_b32_e32 v40, 16, v136
	v_and_b32_e32 v41, 0xffff0000, v136
	v_lshlrev_b32_e32 v42, 16, v137
	v_and_b32_e32 v43, 0xffff0000, v137
	v_lshlrev_b32_e32 v48, 16, v139
	v_and_b32_e32 v49, 0xffff0000, v139
	v_pk_fma_f32 v[38:39], v[38:39], v[206:207], v[42:43]
	v_pk_fma_f32 v[36:37], v[36:37], v[204:205], v[40:41]
	v_pk_fma_f32 v[40:41], v[34:35], v[202:203], v[48:49]
	v_pk_fma_f32 v[34:35], v[32:33], v[200:201], v[46:47]
	v_cvt_pk_bf16_f32 v32, v36, v37
	v_cvt_pk_bf16_f32 v33, v38, v39
	s_waitcnt vmcnt(14)
	v_lshlrev_b32_e32 v36, 16, v134
	v_cvt_pk_bf16_f32 v34, v34, v35
	v_cvt_pk_bf16_f32 v35, v40, v41
	global_store_dwordx4 v[44:45], v[32:35], off offset:256
	v_and_b32_e32 v37, 0xffff0000, v134
	v_lshlrev_b32_e32 v38, 16, v135
	v_lshlrev_b32_e32 v32, 16, v132
	v_and_b32_e32 v33, 0xffff0000, v132
	v_and_b32_e32 v39, 0xffff0000, v135
	v_pk_fma_f32 v[28:29], v[28:29], v[212:213], v[32:33]
	v_lshlrev_b32_e32 v34, 16, v133
	v_and_b32_e32 v35, 0xffff0000, v133
	v_pk_fma_f32 v[32:33], v[26:27], v[210:211], v[38:39]
	v_pk_fma_f32 v[26:27], v[24:25], v[208:209], v[36:37]
	v_cvt_pk_bf16_f32 v24, v28, v29
	v_add_co_u32_e32 v28, vcc, s18, v144
	v_pk_fma_f32 v[30:31], v[30:31], v[214:215], v[34:35]
	s_nop 0
	v_addc_co_u32_e32 v29, vcc, 0, v145, vcc
	v_cvt_pk_bf16_f32 v25, v30, v31
	v_cvt_pk_bf16_f32 v26, v26, v27
	v_cvt_pk_bf16_f32 v27, v32, v33
	global_store_dwordx4 v[28:29], v[24:27], off
	s_waitcnt vmcnt(15)
	v_lshlrev_b32_e32 v30, 16, v130
	v_and_b32_e32 v31, 0xffff0000, v130
	v_lshlrev_b32_e32 v24, 16, v128
	v_and_b32_e32 v25, 0xffff0000, v128
	v_lshlrev_b32_e32 v26, 16, v129
	v_and_b32_e32 v27, 0xffff0000, v129
	v_lshlrev_b32_e32 v32, 16, v131
	v_and_b32_e32 v33, 0xffff0000, v131
	v_pk_fma_f32 v[22:23], v[22:23], v[206:207], v[26:27]
	v_pk_fma_f32 v[20:21], v[20:21], v[204:205], v[24:25]
	v_pk_fma_f32 v[24:25], v[18:19], v[202:203], v[32:33]
	v_pk_fma_f32 v[18:19], v[16:17], v[200:201], v[30:31]
	v_cvt_pk_bf16_f32 v16, v20, v21
	v_cvt_pk_bf16_f32 v17, v22, v23
	s_waitcnt vmcnt(14)
	v_lshlrev_b32_e32 v20, 16, v126
	v_cvt_pk_bf16_f32 v18, v18, v19
	v_cvt_pk_bf16_f32 v19, v24, v25
	global_store_dwordx4 v[28:29], v[16:19], off offset:256
	v_and_b32_e32 v21, 0xffff0000, v126
	v_lshlrev_b32_e32 v22, 16, v127
	v_lshlrev_b32_e32 v16, 16, v124
	v_and_b32_e32 v17, 0xffff0000, v124
	v_and_b32_e32 v23, 0xffff0000, v127
	v_pk_fma_f32 v[12:13], v[12:13], v[212:213], v[16:17]
	v_lshlrev_b32_e32 v18, 16, v125
	v_and_b32_e32 v19, 0xffff0000, v125
	v_pk_fma_f32 v[16:17], v[10:11], v[210:211], v[22:23]
	v_pk_fma_f32 v[10:11], v[8:9], v[208:209], v[20:21]
	v_cvt_pk_bf16_f32 v8, v12, v13
	v_add_co_u32_e32 v12, vcc, s19, v144
	v_pk_fma_f32 v[14:15], v[14:15], v[214:215], v[18:19]
	s_nop 0
	v_addc_co_u32_e32 v13, vcc, 0, v145, vcc
	v_cvt_pk_bf16_f32 v9, v14, v15
	v_cvt_pk_bf16_f32 v10, v10, v11
	v_cvt_pk_bf16_f32 v11, v16, v17
	global_store_dwordx4 v[12:13], v[8:11], off
	s_waitcnt vmcnt(15)
	v_lshlrev_b32_e32 v14, 16, v122
	v_and_b32_e32 v15, 0xffff0000, v122
	v_lshlrev_b32_e32 v8, 16, v120
	v_and_b32_e32 v9, 0xffff0000, v120
	v_lshlrev_b32_e32 v16, 16, v123
	v_and_b32_e32 v17, 0xffff0000, v123
	v_lshlrev_b32_e32 v10, 16, v121
	v_and_b32_e32 v11, 0xffff0000, v121
	v_pk_fma_f32 v[4:5], v[4:5], v[204:205], v[8:9]
	v_pk_fma_f32 v[8:9], v[2:3], v[202:203], v[16:17]
	v_pk_fma_f32 v[2:3], v[0:1], v[200:201], v[14:15]
	s_and_b64 vcc, exec, s[4:5]
	v_pk_fma_f32 v[6:7], v[6:7], v[206:207], v[10:11]
	v_cvt_pk_bf16_f32 v0, v4, v5
	s_nop 0
	v_cvt_pk_bf16_f32 v1, v6, v7
	v_cvt_pk_bf16_f32 v2, v2, v3
	v_cvt_pk_bf16_f32 v3, v8, v9
	global_store_dwordx4 v[12:13], v[0:3], off offset:256
	s_cbranch_vccz .LBB0_849
	s_waitcnt vmcnt(0)
	s_cmpk_gt_u32 s21, 0xff
	v_readlane_b32 s38, v255, 44
	s_cbranch_scc1 .LBB0_864
	s_barrier
